# speedup vs baseline: 1.0057x; 1.0022x over previous
; #define STA(b, h, half, kt) STAGE(((b) * 2 + (h)) * G_HT * 2, pA, ((size_t)(half) * G_HALF * lda + (size_t)(kt) * G_BK) * 2, lda)
; #define STB(b, h, half, kt) STAGE((4 + (b) * 2 + (h)) * G_HT * 2, pB, ((size_t)(half) * G_HALF * K + (size_t)(kt) * G_BK) * 2, K)
; #define LDA(dst, b, h) for (int m = 0; m < 4; ++m) for (int k = 0; k < 2; ++k) \
;     dst[m][k] = *reinterpret_cast<const bf16x8*>(aRd + (((b) * 2 + (h)) * G_HT * 2 + m * 2048 + k * 1024))
; #define LDB(dst, b, h) for (int n = 0; n < 2; ++n) for (int k = 0; k < 2; ++k) \
;     dst[n][k] = *reinterpret_cast<const bf16x8*>(bRd + (((b) * 2 + (h)) * G_HT * 2 + n * 2048 + k * 1024))
; #define MMA(ai, bj, At, Bx) do { __builtin_amdgcn_s_setprio(1); \
;     for (int m = 0; m < 4; ++m) for (int n = 0; n < 2; ++n) for (int k = 0; k < 2; ++k) \
;       acc[ai][bj][m][n] = __builtin_amdgcn_mfma_f32_16x16x32_bf16(Bx[n][k], At[m][k], acc[ai][bj][m][n], 0, 0, 0);     \
;     __builtin_amdgcn_s_setprio(0); } while (0)
; #define WAIT_V(n) asm volatile("s_waitcnt vmcnt(" #n ")" ::: "memory")
; #define WAIT_L(n) asm volatile("s_waitcnt lgkmcnt(" #n ")" ::: "memory")
; #define BAR __builtin_amdgcn_s_barrier()
; #define SCHED __builtin_amdgcn_sched_barrier(0)
; template <int EPI>
; __device__ __forceinline__ void gemm_tile(const bf16* __restrict__ A, int lda, const bf16* __restrict__ Bt, int K,
;                                           int brow, int bcol, const EpiArgs& ea, char* shmc, bool has_next, int nbrow, int nbcol, bool first_tile) {
;     ...
;     LDB(B0, 0, 0); SCHED; LDA(At, 0, 0); STA(1, 1, 1, t + 1);
;     WAIT_L(8); BAR; WAIT_L(0); MMA(0, 0, At, B0); BAR; SCHED;
;     LDB(B1, 0, 1); STB(0, 0, 0, t + 2);
;     BAR; WAIT_L(0); MMA(0, 1, At, B1); BAR;
;     LDA(At, 0, 1); STA(0, 0, 0, t + 2);
;     BAR; WAIT_L(0); MMA(1, 0, At, B0); BAR; SCHED;
;     STB(0, 1, 1, t + 2);
;     WAIT_V(6); BAR; MMA(1, 1, At, B1); BAR;
.LBB0_96:
	ds_read_b128 v[162:165], v141
	ds_read_b128 v[166:169], v142
	ds_read_b128 v[170:173], v143
	ds_read_b128 v[174:177], v144
	s_add_u32 s82, s34, 0xffffff00
	s_addc_u32 s83, s35, -1
	s_mov_b32 m0, s77
	ds_read_b128 v[178:181], v160
	ds_read_b128 v[182:185], v160 offset:1024
	ds_read_b128 v[186:189], v160 offset:2048
	ds_read_b128 v[190:193], v160 offset:3072
	ds_read_b128 v[194:197], v160 offset:4096
	ds_read_b128 v[198:201], v160 offset:5120
	ds_read_b128 v[202:205], v160 offset:6144
	ds_read_b128 v[206:209], v160 offset:7168
	v_lshl_add_u64 v[210:211], v[134:135], 0, s[82:83]
	global_load_lds_dwordx4 v[210:211], off
	v_lshl_add_u64 v[210:211], v[210:211], 0, s[0:1]
	s_mov_b32 m0, s68
	s_nop 0
	global_load_lds_dwordx4 v[210:211], off
	s_waitcnt lgkmcnt(8)
	s_barrier
	s_waitcnt lgkmcnt(0)
	s_setprio 1
	v_mfma_f32_16x16x32_bf16 v[124:127], v[162:165], v[178:181], v[124:127]
	v_mfma_f32_16x16x32_bf16 v[120:123], v[170:173], v[178:181], v[120:123]
	v_mfma_f32_16x16x32_bf16 v[116:119], v[162:165], v[186:189], v[116:119]
	v_mfma_f32_16x16x32_bf16 v[112:115], v[170:173], v[186:189], v[112:115]
	v_mfma_f32_16x16x32_bf16 v[108:111], v[162:165], v[194:197], v[108:111]
	v_mfma_f32_16x16x32_bf16 v[104:107], v[170:173], v[194:197], v[104:107]
	v_mfma_f32_16x16x32_bf16 v[100:103], v[162:165], v[202:205], v[100:103]
	v_mfma_f32_16x16x32_bf16 v[96:99], v[170:173], v[202:205], v[96:99]
	v_mfma_f32_16x16x32_bf16 v[124:127], v[166:169], v[182:185], v[124:127]
	v_mfma_f32_16x16x32_bf16 v[120:123], v[174:177], v[182:185], v[120:123]
	v_mfma_f32_16x16x32_bf16 v[116:119], v[166:169], v[190:193], v[116:119]
	v_mfma_f32_16x16x32_bf16 v[112:115], v[174:177], v[190:193], v[112:115]
	v_mfma_f32_16x16x32_bf16 v[108:111], v[166:169], v[198:201], v[108:111]
	v_mfma_f32_16x16x32_bf16 v[104:107], v[174:177], v[198:201], v[104:107]
	v_mfma_f32_16x16x32_bf16 v[100:103], v[166:169], v[206:209], v[100:103]
	v_mfma_f32_16x16x32_bf16 v[96:99], v[174:177], v[206:209], v[96:99]
	s_setprio 0
	s_barrier
	s_add_u32 s82, s34, 0xffefff80
	s_addc_u32 s83, s35, -1
	s_mov_b64 s[84:85], s[82:83]
	s_mov_b32 m0, s71
	ds_read_b128 v[210:213], v145
	ds_read_b128 v[214:217], v146
	ds_read_b128 v[218:221], v147
	ds_read_b128 v[222:225], v148
	v_lshl_add_u64 v[226:227], v[136:137], 0, s[84:85]
	global_load_lds_dwordx4 v[226:227], off
	v_lshl_add_u64 v[226:227], v[226:227], 0, s[0:1]
	s_mov_b32 m0, s72
	s_nop 0
	global_load_lds_dwordx4 v[226:227], off
	s_barrier
	s_waitcnt lgkmcnt(0)
	s_setprio 1
	v_mfma_f32_16x16x32_bf16 v[92:95], v[210:213], v[178:181], v[92:95]
	v_mfma_f32_16x16x32_bf16 v[88:91], v[218:221], v[178:181], v[88:91]
	v_mfma_f32_16x16x32_bf16 v[84:87], v[210:213], v[186:189], v[84:87]
	v_mfma_f32_16x16x32_bf16 v[80:83], v[218:221], v[186:189], v[80:83]
	v_mfma_f32_16x16x32_bf16 v[76:79], v[210:213], v[194:197], v[76:79]
	v_mfma_f32_16x16x32_bf16 v[72:75], v[218:221], v[194:197], v[72:75]
	v_mfma_f32_16x16x32_bf16 v[68:71], v[210:213], v[202:205], v[68:71]
	v_mfma_f32_16x16x32_bf16 v[64:67], v[218:221], v[202:205], v[64:67]
	v_mfma_f32_16x16x32_bf16 v[92:95], v[214:217], v[182:185], v[92:95]
	v_mfma_f32_16x16x32_bf16 v[88:91], v[222:225], v[182:185], v[88:91]
	v_mfma_f32_16x16x32_bf16 v[84:87], v[214:217], v[190:193], v[84:87]
	v_mfma_f32_16x16x32_bf16 v[80:83], v[222:225], v[190:193], v[80:83]
	v_mfma_f32_16x16x32_bf16 v[76:79], v[214:217], v[198:201], v[76:79]
	v_mfma_f32_16x16x32_bf16 v[72:75], v[222:225], v[198:201], v[72:75]
	v_mfma_f32_16x16x32_bf16 v[68:71], v[214:217], v[206:209], v[68:71]
	v_mfma_f32_16x16x32_bf16 v[64:67], v[222:225], v[206:209], v[64:67]
	s_setprio 0
	s_mov_b32 m0, s7
	s_barrier
	ds_read_b128 v[178:181], v160 offset:16384
	ds_read_b128 v[182:185], v160 offset:17408
	ds_read_b128 v[186:189], v160 offset:18432
	ds_read_b128 v[190:193], v160 offset:19456
	ds_read_b128 v[194:197], v160 offset:20480
	ds_read_b128 v[198:201], v160 offset:21504
	ds_read_b128 v[202:205], v160 offset:22528
	ds_read_b128 v[206:209], v160 offset:23552
	v_lshl_add_u64 v[226:227], v[134:135], 0, s[82:83]
	global_load_lds_dwordx4 v[226:227], off
	v_lshl_add_u64 v[226:227], v[226:227], 0, s[0:1]
	s_mov_b32 m0, s79
	s_nop 0
	global_load_lds_dwordx4 v[226:227], off
	s_barrier
	s_waitcnt lgkmcnt(0)
	s_setprio 1
	v_mfma_f32_16x16x32_bf16 v[60:63], v[162:165], v[178:181], v[60:63]
	v_mfma_f32_16x16x32_bf16 v[56:59], v[170:173], v[178:181], v[56:59]
	v_mfma_f32_16x16x32_bf16 v[52:55], v[162:165], v[186:189], v[52:55]
	v_mfma_f32_16x16x32_bf16 v[48:51], v[170:173], v[186:189], v[48:51]
	v_mfma_f32_16x16x32_bf16 v[44:47], v[162:165], v[194:197], v[44:47]
	v_mfma_f32_16x16x32_bf16 v[40:43], v[170:173], v[194:197], v[40:43]
	v_mfma_f32_16x16x32_bf16 v[36:39], v[162:165], v[202:205], v[36:39]
	v_mfma_f32_16x16x32_bf16 v[32:35], v[170:173], v[202:205], v[32:35]
	v_mfma_f32_16x16x32_bf16 v[60:63], v[166:169], v[182:185], v[60:63]
	v_mfma_f32_16x16x32_bf16 v[56:59], v[174:177], v[182:185], v[56:59]
	v_mfma_f32_16x16x32_bf16 v[52:55], v[166:169], v[190:193], v[52:55]
	v_mfma_f32_16x16x32_bf16 v[48:51], v[174:177], v[190:193], v[48:51]
	v_mfma_f32_16x16x32_bf16 v[44:47], v[166:169], v[198:201], v[44:47]
	v_mfma_f32_16x16x32_bf16 v[40:43], v[174:177], v[198:201], v[40:43]
	v_mfma_f32_16x16x32_bf16 v[36:39], v[166:169], v[206:209], v[36:39]
	v_mfma_f32_16x16x32_bf16 v[32:35], v[174:177], v[206:209], v[32:35]
	s_setprio 0
	s_barrier
	s_add_u32 s82, s34, 0xffffff80
	s_addc_u32 s83, s35, -1
	s_mov_b64 s[84:85], s[82:83]
	s_mov_b32 m0, s73
	v_lshl_add_u64 v[162:163], v[136:137], 0, s[84:85]
	global_load_lds_dwordx4 v[162:163], off
	v_lshl_add_u64 v[162:163], v[162:163], 0, s[0:1]
	s_mov_b32 m0, s74
	s_nop 0
	global_load_lds_dwordx4 v[162:163], off
	s_waitcnt vmcnt(6)
	s_barrier
; #define STA(b, h, half, kt) STAGE(((b) * 2 + (h)) * G_HT * 2, pA, ((size_t)(half) * G_HALF * lda + (size_t)(kt) * G_BK) * 2, lda)
; #define STB(b, h, half, kt) STAGE((4 + (b) * 2 + (h)) * G_HT * 2, pB, ((size_t)(half) * G_HALF * K + (size_t)(kt) * G_BK) * 2, K)
; #define LDA(dst, b, h) for (int m = 0; m < 4; ++m) for (int k = 0; k < 2; ++k) \
;     dst[m][k] = *reinterpret_cast<const bf16x8*>(aRd + (((b) * 2 + (h)) * G_HT * 2 + m * 2048 + k * 1024))
; #define LDB(dst, b, h) for (int n = 0; n < 2; ++n) for (int k = 0; k < 2; ++k) \
;     dst[n][k] = *reinterpret_cast<const bf16x8*>(bRd + (((b) * 2 + (h)) * G_HT * 2 + n * 2048 + k * 1024))
; #define MMA(ai, bj, At, Bx) do { __builtin_amdgcn_s_setprio(1); \
;     for (int m = 0; m < 4; ++m) for (int n = 0; n < 2; ++n) for (int k = 0; k < 2; ++k) \
;       acc[ai][bj][m][n] = __builtin_amdgcn_mfma_f32_16x16x32_bf16(Bx[n][k], At[m][k], acc[ai][bj][m][n], 0, 0, 0);     \
;     __builtin_amdgcn_s_setprio(0); } while (0)
; #define WAIT_V(n) asm volatile("s_waitcnt vmcnt(" #n ")" ::: "memory")
; #define WAIT_L(n) asm volatile("s_waitcnt lgkmcnt(" #n ")" ::: "memory")
; #define BAR __builtin_amdgcn_s_barrier()
; #define SCHED __builtin_amdgcn_sched_barrier(0)
; template <int EPI>
; __device__ __forceinline__ void gemm_tile(const bf16* __restrict__ A, int lda, const bf16* __restrict__ Bt, int K,
;                                           int brow, int bcol, const EpiArgs& ea, char* shmc, bool has_next, int nbrow, int nbcol, bool first_tile) {
;     ...
;     WAIT_V(6); BAR; MMA(1, 1, At, B1); BAR;
;     LDB(B0, 1, 0); SCHED; LDA(At, 1, 0); STA(0, 1, 1, t + 2);
;     WAIT_L(8); BAR; WAIT_L(0); MMA(0, 0, At, B0); BAR; SCHED;
;     LDB(B1, 1, 1); STB(1, 0, 0, t + 3);
;     BAR; WAIT_L(0); MMA(0, 1, At, B1); BAR;
;     LDA(At, 1, 1); STA(1, 0, 0, t + 3);
;     BAR; WAIT_L(0); MMA(1, 0, At, B0); BAR; SCHED;
	s_setprio 1
	v_mfma_f32_16x16x32_bf16 v[28:31], v[210:213], v[178:181], v[28:31]
	v_mfma_f32_16x16x32_bf16 v[24:27], v[218:221], v[178:181], v[24:27]
	v_mfma_f32_16x16x32_bf16 v[20:23], v[210:213], v[186:189], v[20:23]
	v_mfma_f32_16x16x32_bf16 v[16:19], v[218:221], v[186:189], v[16:19]
	v_mfma_f32_16x16x32_bf16 v[12:15], v[210:213], v[194:197], v[12:15]
	v_mfma_f32_16x16x32_bf16 v[8:11], v[218:221], v[194:197], v[8:11]
	v_mfma_f32_16x16x32_bf16 v[4:7], v[210:213], v[202:205], v[4:7]
	v_mfma_f32_16x16x32_bf16 v[0:3], v[218:221], v[202:205], v[0:3]
	v_mfma_f32_16x16x32_bf16 v[28:31], v[214:217], v[182:185], v[28:31]
	v_mfma_f32_16x16x32_bf16 v[24:27], v[222:225], v[182:185], v[24:27]
	v_mfma_f32_16x16x32_bf16 v[20:23], v[214:217], v[190:193], v[20:23]
	v_mfma_f32_16x16x32_bf16 v[16:19], v[222:225], v[190:193], v[16:19]
	v_mfma_f32_16x16x32_bf16 v[12:15], v[214:217], v[198:201], v[12:15]
	v_mfma_f32_16x16x32_bf16 v[8:11], v[222:225], v[198:201], v[8:11]
	v_mfma_f32_16x16x32_bf16 v[4:7], v[214:217], v[206:209], v[4:7]
	v_mfma_f32_16x16x32_bf16 v[0:3], v[222:225], v[206:209], v[0:3]
	s_setprio 0
	s_barrier
	ds_read_b128 v[162:165], v149
	ds_read_b128 v[166:169], v150
	ds_read_b128 v[170:173], v151
	ds_read_b128 v[174:177], v152
	s_mov_b32 m0, s80
	ds_read_b128 v[178:181], v160 offset:32768
	ds_read_b128 v[182:185], v160 offset:33792
	ds_read_b128 v[186:189], v160 offset:34816
	ds_read_b128 v[190:193], v160 offset:35840
	ds_read_b128 v[194:197], v160 offset:36864
	ds_read_b128 v[198:201], v160 offset:37888
	ds_read_b128 v[202:205], v160 offset:38912
	ds_read_b128 v[206:209], v160 offset:39936
	v_lshl_add_u64 v[210:211], v[134:135], 0, s[82:83]
	global_load_lds_dwordx4 v[210:211], off
	v_lshl_add_u64 v[210:211], v[210:211], 0, s[0:1]
	s_mov_b32 m0, s81
	s_nop 0
	global_load_lds_dwordx4 v[210:211], off
	s_waitcnt lgkmcnt(8)
	s_barrier
	s_waitcnt lgkmcnt(0)
	s_setprio 1
	v_mfma_f32_16x16x32_bf16 v[124:127], v[162:165], v[178:181], v[124:127]
	v_mfma_f32_16x16x32_bf16 v[120:123], v[170:173], v[178:181], v[120:123]
	v_mfma_f32_16x16x32_bf16 v[116:119], v[162:165], v[186:189], v[116:119]
	v_mfma_f32_16x16x32_bf16 v[112:115], v[170:173], v[186:189], v[112:115]
	v_mfma_f32_16x16x32_bf16 v[108:111], v[162:165], v[194:197], v[108:111]
	v_mfma_f32_16x16x32_bf16 v[104:107], v[170:173], v[194:197], v[104:107]
	v_mfma_f32_16x16x32_bf16 v[100:103], v[162:165], v[202:205], v[100:103]
	v_mfma_f32_16x16x32_bf16 v[96:99], v[170:173], v[202:205], v[96:99]
	v_mfma_f32_16x16x32_bf16 v[124:127], v[166:169], v[182:185], v[124:127]
	v_mfma_f32_16x16x32_bf16 v[120:123], v[174:177], v[182:185], v[120:123]
	v_mfma_f32_16x16x32_bf16 v[116:119], v[166:169], v[190:193], v[116:119]
	v_mfma_f32_16x16x32_bf16 v[112:115], v[174:177], v[190:193], v[112:115]
	v_mfma_f32_16x16x32_bf16 v[108:111], v[166:169], v[198:201], v[108:111]
	v_mfma_f32_16x16x32_bf16 v[104:107], v[174:177], v[198:201], v[104:107]
	v_mfma_f32_16x16x32_bf16 v[100:103], v[166:169], v[206:209], v[100:103]
	v_mfma_f32_16x16x32_bf16 v[96:99], v[174:177], v[206:209], v[96:99]
	s_setprio 0
	s_barrier
	s_add_u32 s82, s34, 0xfff00000
	s_addc_u32 s83, s35, -1
	s_mov_b64 s[84:85], s[82:83]
	s_mov_b32 m0, s11
	ds_read_b128 v[210:213], v153
	ds_read_b128 v[214:217], v154
	ds_read_b128 v[218:221], v155
	ds_read_b128 v[222:225], v156
	v_lshl_add_u64 v[226:227], v[136:137], 0, s[84:85]
	global_load_lds_dwordx4 v[226:227], off
	v_lshl_add_u64 v[226:227], v[226:227], 0, s[0:1]
	s_mov_b32 m0, s63
	s_nop 0
	global_load_lds_dwordx4 v[226:227], off
	s_barrier
	s_waitcnt lgkmcnt(0)
	s_setprio 1
	v_mfma_f32_16x16x32_bf16 v[92:95], v[210:213], v[178:181], v[92:95]
	v_mfma_f32_16x16x32_bf16 v[88:91], v[218:221], v[178:181], v[88:91]
	v_mfma_f32_16x16x32_bf16 v[84:87], v[210:213], v[186:189], v[84:87]
	v_mfma_f32_16x16x32_bf16 v[80:83], v[218:221], v[186:189], v[80:83]
	v_mfma_f32_16x16x32_bf16 v[76:79], v[210:213], v[194:197], v[76:79]
	v_mfma_f32_16x16x32_bf16 v[72:75], v[218:221], v[194:197], v[72:75]
	v_mfma_f32_16x16x32_bf16 v[68:71], v[210:213], v[202:205], v[68:71]
	v_mfma_f32_16x16x32_bf16 v[64:67], v[218:221], v[202:205], v[64:67]
	v_mfma_f32_16x16x32_bf16 v[92:95], v[214:217], v[182:185], v[92:95]
	v_mfma_f32_16x16x32_bf16 v[88:91], v[222:225], v[182:185], v[88:91]
	v_mfma_f32_16x16x32_bf16 v[84:87], v[214:217], v[190:193], v[84:87]
	v_mfma_f32_16x16x32_bf16 v[80:83], v[222:225], v[190:193], v[80:83]
	v_mfma_f32_16x16x32_bf16 v[76:79], v[214:217], v[198:201], v[76:79]
	v_mfma_f32_16x16x32_bf16 v[72:75], v[222:225], v[198:201], v[72:75]
	v_mfma_f32_16x16x32_bf16 v[68:71], v[214:217], v[206:209], v[68:71]
	v_mfma_f32_16x16x32_bf16 v[64:67], v[222:225], v[206:209], v[64:67]
	s_setprio 0
	s_mov_b32 m0, s66
	s_barrier
	ds_read_b128 v[178:181], v160 offset:49152
	ds_read_b128 v[182:185], v160 offset:50176
	ds_read_b128 v[186:189], v160 offset:51200
	ds_read_b128 v[190:193], v160 offset:52224
	ds_read_b128 v[194:197], v160 offset:53248
	ds_read_b128 v[198:201], v160 offset:54272
	ds_read_b128 v[202:205], v160 offset:55296
	ds_read_b128 v[206:209], v160 offset:56320
	v_lshl_add_u64 v[226:227], v[134:135], 0, s[82:83]
	global_load_lds_dwordx4 v[226:227], off
	v_lshl_add_u64 v[226:227], v[226:227], 0, s[0:1]
	s_mov_b32 m0, s67
	s_nop 0
	global_load_lds_dwordx4 v[226:227], off
	s_barrier
; #define STA(b, h, half, kt) STAGE(((b) * 2 + (h)) * G_HT * 2, pA, ((size_t)(half) * G_HALF * lda + (size_t)(kt) * G_BK) * 2, lda)
; #define STB(b, h, half, kt) STAGE((4 + (b) * 2 + (h)) * G_HT * 2, pB, ((size_t)(half) * G_HALF * K + (size_t)(kt) * G_BK) * 2, K)
; #define LDA(dst, b, h) for (int m = 0; m < 4; ++m) for (int k = 0; k < 2; ++k) \
;     dst[m][k] = *reinterpret_cast<const bf16x8*>(aRd + (((b) * 2 + (h)) * G_HT * 2 + m * 2048 + k * 1024))
; #define LDB(dst, b, h) for (int n = 0; n < 2; ++n) for (int k = 0; k < 2; ++k) \
;     dst[n][k] = *reinterpret_cast<const bf16x8*>(bRd + (((b) * 2 + (h)) * G_HT * 2 + n * 2048 + k * 1024))
; #define MMA(ai, bj, At, Bx) do { __builtin_amdgcn_s_setprio(1); \
;     for (int m = 0; m < 4; ++m) for (int n = 0; n < 2; ++n) for (int k = 0; k < 2; ++k) \
;       acc[ai][bj][m][n] = __builtin_amdgcn_mfma_f32_16x16x32_bf16(Bx[n][k], At[m][k], acc[ai][bj][m][n], 0, 0, 0);     \
;     __builtin_amdgcn_s_setprio(0); } while (0)
; #define WAIT_V(n) asm volatile("s_waitcnt vmcnt(" #n ")" ::: "memory")
; #define WAIT_L(n) asm volatile("s_waitcnt lgkmcnt(" #n ")" ::: "memory")
; #define BAR __builtin_amdgcn_s_barrier()
; #define SCHED __builtin_amdgcn_sched_barrier(0)
; template <int EPI>
; __device__ __forceinline__ void gemm_tile(const bf16* __restrict__ A, int lda, const bf16* __restrict__ Bt, int K,
;                                           int brow, int bcol, const EpiArgs& ea, char* shmc, bool has_next, int nbrow, int nbcol, bool first_tile) {
;     ...
;     BAR; WAIT_L(0); MMA(1, 0, At, B0); BAR; SCHED;
;     STB(1, 1, 1, t + 3);
;     WAIT_V(6); BAR; MMA(1, 1, At, B1); BAR;
;   }
;   { LDB(B0, 0, 0); LDA(At, 0, 0); STA(1, 1, 1, nt - 1);
;     BAR; WAIT_L(0); MMA(0, 0, At, B0); BAR;
;     LDB(B1, 0, 1); BAR; WAIT_L(0); MMA(0, 1, At, B1); BAR;
;     LDA(At, 0, 1); WAIT_V(4); BAR; WAIT_L(0); MMA(1, 0, At, B0); MMA(1, 1, At, B1); BAR; }
	s_waitcnt lgkmcnt(0)
	s_setprio 1
	v_mfma_f32_16x16x32_bf16 v[60:63], v[162:165], v[178:181], v[60:63]
	v_mfma_f32_16x16x32_bf16 v[56:59], v[170:173], v[178:181], v[56:59]
	v_mfma_f32_16x16x32_bf16 v[52:55], v[162:165], v[186:189], v[52:55]
	v_mfma_f32_16x16x32_bf16 v[48:51], v[170:173], v[186:189], v[48:51]
	v_mfma_f32_16x16x32_bf16 v[44:47], v[162:165], v[194:197], v[44:47]
	v_mfma_f32_16x16x32_bf16 v[40:43], v[170:173], v[194:197], v[40:43]
	v_mfma_f32_16x16x32_bf16 v[36:39], v[162:165], v[202:205], v[36:39]
	v_mfma_f32_16x16x32_bf16 v[32:35], v[170:173], v[202:205], v[32:35]
	v_mfma_f32_16x16x32_bf16 v[60:63], v[166:169], v[182:185], v[60:63]
	v_mfma_f32_16x16x32_bf16 v[56:59], v[174:177], v[182:185], v[56:59]
	v_mfma_f32_16x16x32_bf16 v[52:55], v[166:169], v[190:193], v[52:55]
	v_mfma_f32_16x16x32_bf16 v[48:51], v[174:177], v[190:193], v[48:51]
	v_mfma_f32_16x16x32_bf16 v[44:47], v[166:169], v[198:201], v[44:47]
	v_mfma_f32_16x16x32_bf16 v[40:43], v[174:177], v[198:201], v[40:43]
	v_mfma_f32_16x16x32_bf16 v[36:39], v[166:169], v[206:209], v[36:39]
	v_mfma_f32_16x16x32_bf16 v[32:35], v[174:177], v[206:209], v[32:35]
	s_setprio 0
	s_barrier
	s_mov_b64 s[82:83], s[34:35]
	s_mov_b32 m0, s69
	v_lshl_add_u64 v[162:163], v[136:137], 0, s[82:83]
	global_load_lds_dwordx4 v[162:163], off
	v_lshl_add_u64 v[162:163], v[162:163], 0, s[0:1]
	s_mov_b32 m0, s70
	s_nop 0
	global_load_lds_dwordx4 v[162:163], off
	s_waitcnt vmcnt(6)
	s_barrier
	s_setprio 1
	v_mfma_f32_16x16x32_bf16 v[28:31], v[210:213], v[178:181], v[28:31]
	v_mfma_f32_16x16x32_bf16 v[24:27], v[218:221], v[178:181], v[24:27]
	v_mfma_f32_16x16x32_bf16 v[20:23], v[210:213], v[186:189], v[20:23]
	v_mfma_f32_16x16x32_bf16 v[16:19], v[218:221], v[186:189], v[16:19]
	v_mfma_f32_16x16x32_bf16 v[12:15], v[210:213], v[194:197], v[12:15]
	v_mfma_f32_16x16x32_bf16 v[8:11], v[218:221], v[194:197], v[8:11]
	v_mfma_f32_16x16x32_bf16 v[4:7], v[210:213], v[202:205], v[4:7]
	v_mfma_f32_16x16x32_bf16 v[0:3], v[218:221], v[202:205], v[0:3]
	v_mfma_f32_16x16x32_bf16 v[28:31], v[214:217], v[182:185], v[28:31]
	v_mfma_f32_16x16x32_bf16 v[24:27], v[222:225], v[182:185], v[24:27]
	v_mfma_f32_16x16x32_bf16 v[20:23], v[214:217], v[190:193], v[20:23]
	v_mfma_f32_16x16x32_bf16 v[16:19], v[222:225], v[190:193], v[16:19]
	v_mfma_f32_16x16x32_bf16 v[12:15], v[214:217], v[198:201], v[12:15]
	v_mfma_f32_16x16x32_bf16 v[8:11], v[222:225], v[198:201], v[8:11]
	v_mfma_f32_16x16x32_bf16 v[4:7], v[214:217], v[206:209], v[4:7]
	v_mfma_f32_16x16x32_bf16 v[0:3], v[222:225], v[206:209], v[0:3]
	s_setprio 0
	s_add_i32 s75, s75, 2
	s_add_u32 s34, s34, 0x100
	s_addc_u32 s35, s35, 0
	s_cmp_lt_u32 s75, 60
	s_barrier
	s_cbranch_scc1 .LBB0_96
	s_mov_b64 s[34:35], 0x101f80
	s_mov_b32 m0, s77
	ds_read_b128 v[162:165], v141
	ds_read_b128 v[166:169], v142
	ds_read_b128 v[170:173], v143
	ds_read_b128 v[174:177], v144
	ds_read_b128 v[178:181], v160
	ds_read_b128 v[182:185], v160 offset:1024
	ds_read_b128 v[186:189], v160 offset:2048
	ds_read_b128 v[190:193], v160 offset:3072
	ds_read_b128 v[194:197], v160 offset:4096
	ds_read_b128 v[198:201], v160 offset:5120
	ds_read_b128 v[202:205], v160 offset:6144
	ds_read_b128 v[206:209], v160 offset:7168
	s_nop 0
	v_lshl_add_u64 v[134:135], v[134:135], 0, s[34:35]
	global_load_lds_dwordx4 v[134:135], off
	v_lshl_add_u64 v[134:135], v[134:135], 0, s[0:1]
	s_mov_b32 m0, s68
	s_nop 0
	global_load_lds_dwordx4 v[134:135], off
	s_barrier
	s_waitcnt lgkmcnt(0)
	s_setprio 1
	s_waitcnt lgkmcnt(0)
	v_mfma_f32_16x16x32_bf16 v[124:127], v[162:165], v[178:181], v[124:127]
	v_mfma_f32_16x16x32_bf16 v[116:119], v[162:165], v[186:189], v[116:119]
	v_mfma_f32_16x16x32_bf16 v[112:115], v[170:173], v[186:189], v[112:115]
	v_mfma_f32_16x16x32_bf16 v[100:103], v[162:165], v[202:205], v[100:103]
	v_mfma_f32_16x16x32_bf16 v[96:99], v[170:173], v[202:205], v[96:99]
	v_mfma_f32_16x16x32_bf16 v[124:127], v[166:169], v[182:185], v[124:127]
	v_mfma_f32_16x16x32_bf16 v[120:123], v[170:173], v[178:181], v[120:123]
	v_mfma_f32_16x16x32_bf16 v[116:119], v[166:169], v[190:193], v[116:119]
	v_mfma_f32_16x16x32_bf16 v[112:115], v[174:177], v[190:193], v[112:115]
	v_mfma_f32_16x16x32_bf16 v[108:111], v[162:165], v[194:197], v[108:111]
	v_mfma_f32_16x16x32_bf16 v[104:107], v[170:173], v[194:197], v[104:107]
	v_mfma_f32_16x16x32_bf16 v[100:103], v[166:169], v[206:209], v[100:103]
	v_mfma_f32_16x16x32_bf16 v[96:99], v[174:177], v[206:209], v[96:99]
	v_mfma_f32_16x16x32_bf16 v[134:137], v[174:177], v[182:185], v[120:123]
	v_mfma_f32_16x16x32_bf16 v[210:213], v[166:169], v[198:201], v[108:111]
	v_mfma_f32_16x16x32_bf16 v[214:217], v[174:177], v[198:201], v[104:107]
	s_setprio 0
	s_barrier
	s_nop 0
	ds_read_b128 v[104:107], v145
	ds_read_b128 v[108:111], v146
	ds_read_b128 v[120:123], v147
	ds_read_b128 v[218:221], v148
	s_barrier
	s_waitcnt lgkmcnt(0)
	s_setprio 1
	s_waitcnt lgkmcnt(0)
	v_mfma_f32_16x16x32_bf16 v[84:87], v[104:107], v[186:189], v[84:87]
	v_mfma_f32_16x16x32_bf16 v[80:83], v[120:123], v[186:189], v[80:83]
	v_mfma_f32_16x16x32_bf16 v[68:71], v[104:107], v[202:205], v[68:71]
	v_mfma_f32_16x16x32_bf16 v[92:95], v[104:107], v[178:181], v[92:95]
	v_mfma_f32_16x16x32_bf16 v[88:91], v[120:123], v[178:181], v[88:91]
	v_mfma_f32_16x16x32_bf16 v[84:87], v[108:111], v[190:193], v[84:87]
	v_mfma_f32_16x16x32_bf16 v[80:83], v[218:221], v[190:193], v[80:83]
	v_mfma_f32_16x16x32_bf16 v[76:79], v[104:107], v[194:197], v[76:79]
	v_mfma_f32_16x16x32_bf16 v[72:75], v[120:123], v[194:197], v[72:75]
	v_mfma_f32_16x16x32_bf16 v[68:71], v[108:111], v[206:209], v[68:71]
	v_mfma_f32_16x16x32_bf16 v[64:67], v[120:123], v[202:205], v[64:67]
	v_mfma_f32_16x16x32_bf16 v[222:225], v[108:111], v[182:185], v[92:95]
	v_mfma_f32_16x16x32_bf16 v[178:181], v[218:221], v[182:185], v[88:91]
	v_mfma_f32_16x16x32_bf16 v[182:185], v[108:111], v[198:201], v[76:79]
	v_mfma_f32_16x16x32_bf16 v[186:189], v[218:221], v[198:201], v[72:75]
	v_mfma_f32_16x16x32_bf16 v[190:193], v[218:221], v[206:209], v[64:67]
	s_setprio 0
	s_barrier
; #define LDA(dst, b, h) for (int m = 0; m < 4; ++m) for (int k = 0; k < 2; ++k) \
;     dst[m][k] = *reinterpret_cast<const bf16x8*>(aRd + (((b) * 2 + (h)) * G_HT * 2 + m * 2048 + k * 1024))
; #define LDB(dst, b, h) for (int n = 0; n < 2; ++n) for (int k = 0; k < 2; ++k) \
;     dst[n][k] = *reinterpret_cast<const bf16x8*>(bRd + (((b) * 2 + (h)) * G_HT * 2 + n * 2048 + k * 1024))
; #define MMA(ai, bj, At, Bx) do { __builtin_amdgcn_s_setprio(1); \
;     for (int m = 0; m < 4; ++m) for (int n = 0; n < 2; ++n) for (int k = 0; k < 2; ++k) \
;       acc[ai][bj][m][n] = __builtin_amdgcn_mfma_f32_16x16x32_bf16(Bx[n][k], At[m][k], acc[ai][bj][m][n], 0, 0, 0);     \
;     __builtin_amdgcn_s_setprio(0); } while (0)
; #define WAIT_V(n) asm volatile("s_waitcnt vmcnt(" #n ")" ::: "memory")
; #define WAIT_L(n) asm volatile("s_waitcnt lgkmcnt(" #n ")" ::: "memory")
; #define BAR __builtin_amdgcn_s_barrier()
; template <int EPI>
; __device__ __forceinline__ void gemm_tile(const bf16* __restrict__ A, int lda, const bf16* __restrict__ Bt, int K,
;                                           int brow, int bcol, const EpiArgs& ea, char* shmc, bool has_next, int nbrow, int nbcol, bool first_tile) {
;     ...
;     LDA(At, 0, 1); WAIT_V(4); BAR; WAIT_L(0); MMA(1, 0, At, B0); MMA(1, 1, At, B1); BAR; }
;   { LDB(B0, 1, 0); LDA(At, 1, 0); WAIT_V(2); BAR; WAIT_L(0); MMA(0, 0, At, B0); BAR;
	s_nop 0
	ds_read_b128 v[64:67], v160 offset:16384
	ds_read_b128 v[72:75], v160 offset:17408
	ds_read_b128 v[76:79], v160 offset:18432
	ds_read_b128 v[88:91], v160 offset:19456
	ds_read_b128 v[92:95], v160 offset:20480
	ds_read_b128 v[194:197], v160 offset:21504
	ds_read_b128 v[198:201], v160 offset:22528
	ds_read_b128 v[202:205], v160 offset:23552
	s_waitcnt vmcnt(4)
	s_barrier
	s_waitcnt lgkmcnt(0)
	s_setprio 1
	s_waitcnt lgkmcnt(0)
	v_mfma_f32_16x16x32_bf16 v[60:63], v[162:165], v[64:67], v[60:63]
	v_mfma_f32_16x16x32_bf16 v[52:55], v[162:165], v[76:79], v[52:55]
	v_mfma_f32_16x16x32_bf16 v[48:51], v[170:173], v[76:79], v[48:51]
	v_mfma_f32_16x16x32_bf16 v[36:39], v[162:165], v[198:201], v[36:39]
	v_mfma_f32_16x16x32_bf16 v[32:35], v[170:173], v[198:201], v[32:35]
	v_mfma_f32_16x16x32_bf16 v[60:63], v[166:169], v[72:75], v[60:63]
	v_mfma_f32_16x16x32_bf16 v[56:59], v[170:173], v[64:67], v[56:59]
	v_mfma_f32_16x16x32_bf16 v[52:55], v[166:169], v[88:91], v[52:55]
	v_mfma_f32_16x16x32_bf16 v[48:51], v[174:177], v[88:91], v[48:51]
	v_mfma_f32_16x16x32_bf16 v[44:47], v[162:165], v[92:95], v[44:47]
	v_mfma_f32_16x16x32_bf16 v[40:43], v[170:173], v[92:95], v[40:43]
	v_mfma_f32_16x16x32_bf16 v[36:39], v[166:169], v[202:205], v[36:39]
	v_mfma_f32_16x16x32_bf16 v[32:35], v[174:177], v[202:205], v[32:35]
	v_mfma_f32_16x16x32_bf16 v[206:209], v[174:177], v[72:75], v[56:59]
	v_mfma_f32_16x16x32_bf16 v[226:229], v[166:169], v[194:197], v[44:47]
	v_mfma_f32_16x16x32_bf16 v[230:233], v[174:177], v[194:197], v[40:43]
	s_setprio 0
	s_setprio 1
	v_mfma_f32_16x16x32_bf16 v[20:23], v[104:107], v[76:79], v[20:23]
	v_mfma_f32_16x16x32_bf16 v[16:19], v[120:123], v[76:79], v[16:19]
	v_mfma_f32_16x16x32_bf16 v[4:7], v[104:107], v[198:201], v[4:7]
	v_mfma_f32_16x16x32_bf16 v[28:31], v[104:107], v[64:67], v[28:31]
	v_mfma_f32_16x16x32_bf16 v[24:27], v[120:123], v[64:67], v[24:27]
	v_mfma_f32_16x16x32_bf16 v[20:23], v[108:111], v[88:91], v[20:23]
	v_mfma_f32_16x16x32_bf16 v[16:19], v[218:221], v[88:91], v[16:19]
	v_mfma_f32_16x16x32_bf16 v[12:15], v[104:107], v[92:95], v[12:15]
	v_mfma_f32_16x16x32_bf16 v[8:11], v[120:123], v[92:95], v[8:11]
	v_mfma_f32_16x16x32_bf16 v[4:7], v[108:111], v[202:205], v[4:7]
	v_mfma_f32_16x16x32_bf16 v[0:3], v[120:123], v[198:201], v[0:3]
	v_mfma_f32_16x16x32_bf16 v[162:165], v[108:111], v[72:75], v[28:31]
	v_mfma_f32_16x16x32_bf16 v[166:169], v[218:221], v[72:75], v[24:27]
	v_mfma_f32_16x16x32_bf16 v[170:173], v[108:111], v[194:197], v[12:15]
	v_mfma_f32_16x16x32_bf16 v[174:177], v[218:221], v[194:197], v[8:11]
	v_mfma_f32_16x16x32_bf16 v[194:197], v[218:221], v[202:205], v[0:3]
	s_setprio 0
	s_barrier
	s_nop 0
	ds_read_b128 v[0:3], v149
	ds_read_b128 v[8:11], v150
	ds_read_b128 v[12:15], v151
	ds_read_b128 v[198:201], v152
	ds_read_b128 v[24:27], v160 offset:32768
	ds_read_b128 v[28:31], v160 offset:33792
	ds_read_b128 v[40:43], v160 offset:34816
	ds_read_b128 v[44:47], v160 offset:35840
	ds_read_b128 v[56:59], v160 offset:36864
	ds_read_b128 v[64:67], v160 offset:37888
	ds_read_b128 v[202:205], v160 offset:38912
	ds_read_b128 v[218:221], v160 offset:39936
	s_waitcnt vmcnt(2)
	s_barrier
	s_waitcnt lgkmcnt(0)
	s_setprio 1
	s_waitcnt lgkmcnt(0)
	v_mfma_f32_16x16x32_bf16 v[72:75], v[0:3], v[24:27], v[124:127]
	v_mfma_f32_16x16x32_bf16 v[120:123], v[8:11], v[28:31], v[72:75]
	v_mfma_f32_16x16x32_bf16 v[72:75], v[12:15], v[24:27], v[134:137]
	v_mfma_f32_16x16x32_bf16 v[124:127], v[198:201], v[28:31], v[72:75]
	v_mfma_f32_16x16x32_bf16 v[72:75], v[0:3], v[40:43], v[116:119]
	v_mfma_f32_16x16x32_bf16 v[104:107], v[8:11], v[44:47], v[72:75]
	v_mfma_f32_16x16x32_bf16 v[72:75], v[12:15], v[40:43], v[112:115]
	v_mfma_f32_16x16x32_bf16 v[108:111], v[198:201], v[44:47], v[72:75]
	v_mfma_f32_16x16x32_bf16 v[72:75], v[0:3], v[56:59], v[210:213]
	v_mfma_f32_16x16x32_bf16 v[88:91], v[8:11], v[64:67], v[72:75]
	v_mfma_f32_16x16x32_bf16 v[72:75], v[12:15], v[56:59], v[214:217]
	v_mfma_f32_16x16x32_bf16 v[92:95], v[198:201], v[64:67], v[72:75]
	v_mfma_f32_16x16x32_bf16 v[72:75], v[0:3], v[202:205], v[100:103]
	v_mfma_f32_16x16x32_bf16 v[76:79], v[12:15], v[202:205], v[96:99]
	v_mfma_f32_16x16x32_bf16 v[72:75], v[8:11], v[218:221], v[72:75]
	v_mfma_f32_16x16x32_bf16 v[76:79], v[198:201], v[218:221], v[76:79]
	s_setprio 0
	s_barrier
; #define LDA(dst, b, h) for (int m = 0; m < 4; ++m) for (int k = 0; k < 2; ++k) \
;     dst[m][k] = *reinterpret_cast<const bf16x8*>(aRd + (((b) * 2 + (h)) * G_HT * 2 + m * 2048 + k * 1024))
; #define LDB(dst, b, h) for (int n = 0; n < 2; ++n) for (int k = 0; k < 2; ++k) \
;     dst[n][k] = *reinterpret_cast<const bf16x8*>(bRd + (((b) * 2 + (h)) * G_HT * 2 + n * 2048 + k * 1024))
; #define MMA(ai, bj, At, Bx) do { __builtin_amdgcn_s_setprio(1); \
;     for (int m = 0; m < 4; ++m) for (int n = 0; n < 2; ++n) for (int k = 0; k < 2; ++k) \
;       acc[ai][bj][m][n] = __builtin_amdgcn_mfma_f32_16x16x32_bf16(Bx[n][k], At[m][k], acc[ai][bj][m][n], 0, 0, 0);     \
;     __builtin_amdgcn_s_setprio(0); } while (0)
; #define WAIT_V(n) asm volatile("s_waitcnt vmcnt(" #n ")" ::: "memory")
; #define WAIT_L(n) asm volatile("s_waitcnt lgkmcnt(" #n ")" ::: "memory")
; #define BAR __builtin_amdgcn_s_barrier()
; template <int EPI>
; __device__ __forceinline__ void gemm_tile(const bf16* __restrict__ A, int lda, const bf16* __restrict__ Bt, int K,
;                                           int brow, int bcol, const EpiArgs& ea, char* shmc, bool has_next, int nbrow, int nbcol, bool first_tile) {
;     ...
;     LDB(B1, 1, 1); WAIT_V(0); BAR; WAIT_L(0); MMA(0, 1, At, B1); BAR;
;     LDA(At, 1, 1); BAR; WAIT_L(0); MMA(1, 0, At, B0); MMA(1, 1, At, B1); BAR; }
;   if (wr == 0) BAR;
	ds_read_b128 v[134:137], v153
	ds_read_b128 v[210:213], v154
	ds_read_b128 v[214:217], v155
	ds_read_b128 v[234:237], v156
	s_waitcnt vmcnt(0)
	s_barrier
	s_waitcnt lgkmcnt(0)
	s_setprio 1
	s_waitcnt lgkmcnt(0)
	v_mfma_f32_16x16x32_bf16 v[96:99], v[134:137], v[24:27], v[222:225]
	v_mfma_f32_16x16x32_bf16 v[24:27], v[214:217], v[24:27], v[178:181]
	v_mfma_f32_16x16x32_bf16 v[116:119], v[234:237], v[28:31], v[24:27]
	v_mfma_f32_16x16x32_bf16 v[24:27], v[134:137], v[40:43], v[84:87]
	v_mfma_f32_16x16x32_bf16 v[112:115], v[210:213], v[28:31], v[96:99]
	v_mfma_f32_16x16x32_bf16 v[96:99], v[210:213], v[44:47], v[24:27]
	v_mfma_f32_16x16x32_bf16 v[24:27], v[214:217], v[40:43], v[80:83]
	v_mfma_f32_16x16x32_bf16 v[100:103], v[234:237], v[44:47], v[24:27]
	v_mfma_f32_16x16x32_bf16 v[24:27], v[134:137], v[56:59], v[182:185]
	v_mfma_f32_16x16x32_bf16 v[80:83], v[210:213], v[64:67], v[24:27]
	v_mfma_f32_16x16x32_bf16 v[24:27], v[214:217], v[56:59], v[186:189]
	v_mfma_f32_16x16x32_bf16 v[84:87], v[234:237], v[64:67], v[24:27]
	v_mfma_f32_16x16x32_bf16 v[24:27], v[134:137], v[202:205], v[68:71]
	v_mfma_f32_16x16x32_bf16 v[64:67], v[210:213], v[218:221], v[24:27]
	v_mfma_f32_16x16x32_bf16 v[24:27], v[214:217], v[202:205], v[190:193]
	v_mfma_f32_16x16x32_bf16 v[68:71], v[234:237], v[218:221], v[24:27]
	s_setprio 0
	s_barrier
	ds_read_b128 v[178:181], v160 offset:49152
	ds_read_b128 v[182:185], v160 offset:50176
	ds_read_b128 v[186:189], v160 offset:51200
	ds_read_b128 v[190:193], v160 offset:52224
	ds_read_b128 v[202:205], v160 offset:53248
	ds_read_b128 v[218:221], v160 offset:54272
	ds_read_b128 v[222:225], v160 offset:55296
	ds_read_b128 v[238:241], v160 offset:56320
	s_barrier
	s_waitcnt lgkmcnt(0)
	s_setprio 1
	s_waitcnt lgkmcnt(0)
	v_mfma_f32_16x16x32_bf16 v[24:27], v[0:3], v[178:181], v[60:63]
	v_mfma_f32_16x16x32_bf16 v[56:59], v[8:11], v[182:185], v[24:27]
	v_mfma_f32_16x16x32_bf16 v[24:27], v[12:15], v[178:181], v[206:209]
	v_mfma_f32_16x16x32_bf16 v[60:63], v[198:201], v[182:185], v[24:27]
	v_mfma_f32_16x16x32_bf16 v[24:27], v[0:3], v[186:189], v[52:55]
	v_mfma_f32_16x16x32_bf16 v[40:43], v[8:11], v[190:193], v[24:27]
	v_mfma_f32_16x16x32_bf16 v[24:27], v[12:15], v[186:189], v[48:51]
	v_mfma_f32_16x16x32_bf16 v[44:47], v[198:201], v[190:193], v[24:27]
	v_mfma_f32_16x16x32_bf16 v[24:27], v[0:3], v[202:205], v[226:229]
	v_mfma_f32_16x16x32_bf16 v[0:3], v[0:3], v[222:225], v[36:39]
	v_mfma_f32_16x16x32_bf16 v[24:27], v[8:11], v[218:221], v[24:27]
	v_mfma_f32_16x16x32_bf16 v[28:31], v[12:15], v[202:205], v[230:233]
	v_mfma_f32_16x16x32_bf16 v[8:11], v[8:11], v[238:241], v[0:3]
	v_mfma_f32_16x16x32_bf16 v[0:3], v[12:15], v[222:225], v[32:35]
	v_mfma_f32_16x16x32_bf16 v[28:31], v[198:201], v[218:221], v[28:31]
	v_mfma_f32_16x16x32_bf16 v[12:15], v[198:201], v[238:241], v[0:3]
	s_setprio 0
	s_setprio 1
	v_mfma_f32_16x16x32_bf16 v[0:3], v[134:137], v[178:181], v[162:165]
	v_mfma_f32_16x16x32_bf16 v[48:51], v[210:213], v[182:185], v[0:3]
	v_mfma_f32_16x16x32_bf16 v[0:3], v[214:217], v[178:181], v[166:169]
	v_mfma_f32_16x16x32_bf16 v[52:55], v[234:237], v[182:185], v[0:3]
	v_mfma_f32_16x16x32_bf16 v[0:3], v[134:137], v[186:189], v[20:23]
	v_mfma_f32_16x16x32_bf16 v[32:35], v[210:213], v[190:193], v[0:3]
	v_mfma_f32_16x16x32_bf16 v[0:3], v[214:217], v[186:189], v[16:19]
	v_mfma_f32_16x16x32_bf16 v[36:39], v[234:237], v[190:193], v[0:3]
	v_mfma_f32_16x16x32_bf16 v[0:3], v[134:137], v[202:205], v[170:173]
	v_mfma_f32_16x16x32_bf16 v[16:19], v[210:213], v[218:221], v[0:3]
	v_mfma_f32_16x16x32_bf16 v[0:3], v[214:217], v[202:205], v[174:177]
	v_mfma_f32_16x16x32_bf16 v[20:23], v[234:237], v[218:221], v[0:3]
	v_mfma_f32_16x16x32_bf16 v[0:3], v[134:137], v[222:225], v[4:7]
	v_mfma_f32_16x16x32_bf16 v[4:7], v[214:217], v[222:225], v[194:197]
	v_mfma_f32_16x16x32_bf16 v[0:3], v[210:213], v[238:241], v[0:3]
	v_mfma_f32_16x16x32_bf16 v[4:7], v[234:237], v[238:241], v[4:7]
	s_setprio 0
	s_barrier
	s_and_saveexec_b64 s[34:35], s[4:5]
	s_cbranch_execz .LBB0_99
	s_barrier

; #define STA(b, h, half, kt) STAGE(((b) * 2 + (h)) * G_HT * 2, pA, ((size_t)(half) * G_HALF * lda + (size_t)(kt) * G_BK) * 2, lda)
; #define STB(b, h, half, kt) STAGE((4 + (b) * 2 + (h)) * G_HT * 2, pB, ((size_t)(half) * G_HALF * K + (size_t)(kt) * G_BK) * 2, K)
; #define LDA(dst, b, h) for (int m = 0; m < 4; ++m) for (int k = 0; k < 2; ++k) \
;     dst[m][k] = *reinterpret_cast<const bf16x8*>(aRd + (((b) * 2 + (h)) * G_HT * 2 + m * 2048 + k * 1024))
; #define LDB(dst, b, h) for (int n = 0; n < 2; ++n) for (int k = 0; k < 2; ++k) \
;     dst[n][k] = *reinterpret_cast<const bf16x8*>(bRd + (((b) * 2 + (h)) * G_HT * 2 + n * 2048 + k * 1024))
; #define MMA(ai, bj, At, Bx) do { __builtin_amdgcn_s_setprio(1); \
;     for (int m = 0; m < 4; ++m) for (int n = 0; n < 2; ++n) for (int k = 0; k < 2; ++k) \
;       acc[ai][bj][m][n] = __builtin_amdgcn_mfma_f32_16x16x32_bf16(Bx[n][k], At[m][k], acc[ai][bj][m][n], 0, 0, 0);     \
;     __builtin_amdgcn_s_setprio(0); } while (0)
; #define WAIT_V(n) asm volatile("s_waitcnt vmcnt(" #n ")" ::: "memory")
; #define WAIT_L(n) asm volatile("s_waitcnt lgkmcnt(" #n ")" ::: "memory")
; #define BAR __builtin_amdgcn_s_barrier()
; #define SCHED __builtin_amdgcn_sched_barrier(0)
; template <int EPI>
; __device__ __forceinline__ void gemm_tile(const bf16* __restrict__ A, int lda, const bf16* __restrict__ Bt, int K,
;                                           int brow, int bcol, const EpiArgs& ea, char* shmc, bool has_next, int nbrow, int nbcol, bool first_tile) {
;     ...
;     LDB(B0, 0, 0); SCHED; LDA(At, 0, 0); STA(1, 1, 1, t + 1);
;     WAIT_L(8); BAR; WAIT_L(0); MMA(0, 0, At, B0); BAR; SCHED;
;     LDB(B1, 0, 1); STB(0, 0, 0, t + 2);
;     BAR; WAIT_L(0); MMA(0, 1, At, B1); BAR;
;     LDA(At, 0, 1); STA(0, 0, 0, t + 2);
;     BAR; WAIT_L(0); MMA(1, 0, At, B0); BAR; SCHED;
;     STB(0, 1, 1, t + 2);
;     WAIT_V(6); BAR; MMA(1, 1, At, B1); BAR;
.LBB0_654:
	ds_read_b128 v[140:143], v145
	ds_read_b128 v[166:169], v146
	ds_read_b128 v[170:173], v147
	ds_read_b128 v[174:177], v148
	s_add_u32 s42, s14, 0xffffff00
	s_addc_u32 s43, s15, -1
	s_mov_b32 m0, s29
	ds_read_b128 v[178:181], v164
	ds_read_b128 v[182:185], v164 offset:1024
	ds_read_b128 v[186:189], v164 offset:2048
	ds_read_b128 v[190:193], v164 offset:3072
	ds_read_b128 v[194:197], v164 offset:4096
	ds_read_b128 v[198:201], v164 offset:5120
	ds_read_b128 v[202:205], v164 offset:6144
	ds_read_b128 v[206:209], v164 offset:7168
	v_lshl_add_u64 v[210:211], v[136:137], 0, s[42:43]
	global_load_lds_dwordx4 v[210:211], off
	v_lshl_add_u64 v[210:211], v[210:211], 0, s[10:11]
	s_mov_b32 m0, s21
	s_nop 0
	global_load_lds_dwordx4 v[210:211], off
	s_waitcnt lgkmcnt(8)
	s_barrier
	s_waitcnt lgkmcnt(0)
	s_setprio 1
	v_mfma_f32_16x16x32_bf16 v[124:127], v[140:143], v[178:181], v[124:127]
	v_mfma_f32_16x16x32_bf16 v[120:123], v[170:173], v[178:181], v[120:123]
	v_mfma_f32_16x16x32_bf16 v[116:119], v[140:143], v[186:189], v[116:119]
	v_mfma_f32_16x16x32_bf16 v[112:115], v[170:173], v[186:189], v[112:115]
	v_mfma_f32_16x16x32_bf16 v[108:111], v[140:143], v[194:197], v[108:111]
	v_mfma_f32_16x16x32_bf16 v[104:107], v[170:173], v[194:197], v[104:107]
	v_mfma_f32_16x16x32_bf16 v[100:103], v[140:143], v[202:205], v[100:103]
	v_mfma_f32_16x16x32_bf16 v[96:99], v[170:173], v[202:205], v[96:99]
	v_mfma_f32_16x16x32_bf16 v[124:127], v[166:169], v[182:185], v[124:127]
	v_mfma_f32_16x16x32_bf16 v[120:123], v[174:177], v[182:185], v[120:123]
	v_mfma_f32_16x16x32_bf16 v[116:119], v[166:169], v[190:193], v[116:119]
	v_mfma_f32_16x16x32_bf16 v[112:115], v[174:177], v[190:193], v[112:115]
	v_mfma_f32_16x16x32_bf16 v[108:111], v[166:169], v[198:201], v[108:111]
	v_mfma_f32_16x16x32_bf16 v[104:107], v[174:177], v[198:201], v[104:107]
	v_mfma_f32_16x16x32_bf16 v[100:103], v[166:169], v[206:209], v[100:103]
	v_mfma_f32_16x16x32_bf16 v[96:99], v[174:177], v[206:209], v[96:99]
	s_setprio 0
	s_barrier
	s_add_u32 s42, s14, 0xffefff80
	s_addc_u32 s43, s15, -1
	s_mov_b64 s[48:49], s[42:43]
	s_mov_b32 m0, s24
	ds_read_b128 v[210:213], v149
	ds_read_b128 v[214:217], v150
	ds_read_b128 v[218:221], v151
	ds_read_b128 v[222:225], v152
	v_lshl_add_u64 v[226:227], v[138:139], 0, s[48:49]
	global_load_lds_dwordx4 v[226:227], off
	v_lshl_add_u64 v[226:227], v[226:227], 0, s[10:11]
	s_mov_b32 m0, s25
	s_nop 0
	global_load_lds_dwordx4 v[226:227], off
	s_barrier
	s_waitcnt lgkmcnt(0)
	s_setprio 1
	v_mfma_f32_16x16x32_bf16 v[92:95], v[210:213], v[178:181], v[92:95]
	v_mfma_f32_16x16x32_bf16 v[88:91], v[218:221], v[178:181], v[88:91]
	v_mfma_f32_16x16x32_bf16 v[84:87], v[210:213], v[186:189], v[84:87]
	v_mfma_f32_16x16x32_bf16 v[80:83], v[218:221], v[186:189], v[80:83]
	v_mfma_f32_16x16x32_bf16 v[76:79], v[210:213], v[194:197], v[76:79]
	v_mfma_f32_16x16x32_bf16 v[72:75], v[218:221], v[194:197], v[72:75]
	v_mfma_f32_16x16x32_bf16 v[68:71], v[210:213], v[202:205], v[68:71]
	v_mfma_f32_16x16x32_bf16 v[64:67], v[218:221], v[202:205], v[64:67]
	v_mfma_f32_16x16x32_bf16 v[92:95], v[214:217], v[182:185], v[92:95]
	v_mfma_f32_16x16x32_bf16 v[88:91], v[222:225], v[182:185], v[88:91]
	v_mfma_f32_16x16x32_bf16 v[84:87], v[214:217], v[190:193], v[84:87]
	v_mfma_f32_16x16x32_bf16 v[80:83], v[222:225], v[190:193], v[80:83]
	v_mfma_f32_16x16x32_bf16 v[76:79], v[214:217], v[198:201], v[76:79]
	v_mfma_f32_16x16x32_bf16 v[72:75], v[222:225], v[198:201], v[72:75]
	v_mfma_f32_16x16x32_bf16 v[68:71], v[214:217], v[206:209], v[68:71]
	v_mfma_f32_16x16x32_bf16 v[64:67], v[222:225], v[206:209], v[64:67]
	s_setprio 0
	s_mov_b32 m0, s1
	s_barrier
	ds_read_b128 v[178:181], v164 offset:16384
	ds_read_b128 v[182:185], v164 offset:17408
	ds_read_b128 v[186:189], v164 offset:18432
	ds_read_b128 v[190:193], v164 offset:19456
	ds_read_b128 v[194:197], v164 offset:20480
	ds_read_b128 v[198:201], v164 offset:21504
	ds_read_b128 v[202:205], v164 offset:22528
	ds_read_b128 v[206:209], v164 offset:23552
	v_lshl_add_u64 v[226:227], v[136:137], 0, s[42:43]
	global_load_lds_dwordx4 v[226:227], off
	v_lshl_add_u64 v[226:227], v[226:227], 0, s[10:11]
	s_mov_b32 m0, s30
	s_nop 0
	global_load_lds_dwordx4 v[226:227], off
	s_barrier
	s_waitcnt lgkmcnt(0)
	s_setprio 1
	v_mfma_f32_16x16x32_bf16 v[60:63], v[140:143], v[178:181], v[60:63]
	v_mfma_f32_16x16x32_bf16 v[56:59], v[170:173], v[178:181], v[56:59]
	v_mfma_f32_16x16x32_bf16 v[52:55], v[140:143], v[186:189], v[52:55]
	v_mfma_f32_16x16x32_bf16 v[48:51], v[170:173], v[186:189], v[48:51]
	v_mfma_f32_16x16x32_bf16 v[44:47], v[140:143], v[194:197], v[44:47]
	v_mfma_f32_16x16x32_bf16 v[40:43], v[170:173], v[194:197], v[40:43]
	v_mfma_f32_16x16x32_bf16 v[36:39], v[140:143], v[202:205], v[36:39]
	v_mfma_f32_16x16x32_bf16 v[32:35], v[170:173], v[202:205], v[32:35]
	v_mfma_f32_16x16x32_bf16 v[60:63], v[166:169], v[182:185], v[60:63]
	v_mfma_f32_16x16x32_bf16 v[56:59], v[174:177], v[182:185], v[56:59]
	v_mfma_f32_16x16x32_bf16 v[52:55], v[166:169], v[190:193], v[52:55]
	v_mfma_f32_16x16x32_bf16 v[48:51], v[174:177], v[190:193], v[48:51]
	v_mfma_f32_16x16x32_bf16 v[44:47], v[166:169], v[198:201], v[44:47]
	v_mfma_f32_16x16x32_bf16 v[40:43], v[174:177], v[198:201], v[40:43]
	v_mfma_f32_16x16x32_bf16 v[36:39], v[166:169], v[206:209], v[36:39]
	v_mfma_f32_16x16x32_bf16 v[32:35], v[174:177], v[206:209], v[32:35]
	s_setprio 0
	s_barrier
	s_add_u32 s42, s14, 0xffffff80
	s_addc_u32 s43, s15, -1
	s_mov_b64 s[48:49], s[42:43]
	s_mov_b32 m0, s26
	v_lshl_add_u64 v[140:141], v[138:139], 0, s[48:49]
	global_load_lds_dwordx4 v[140:141], off
	v_lshl_add_u64 v[140:141], v[140:141], 0, s[10:11]
	s_mov_b32 m0, s27
	s_nop 0
	global_load_lds_dwordx4 v[140:141], off
	s_waitcnt vmcnt(6)
	s_barrier
; #define STA(b, h, half, kt) STAGE(((b) * 2 + (h)) * G_HT * 2, pA, ((size_t)(half) * G_HALF * lda + (size_t)(kt) * G_BK) * 2, lda)
; #define STB(b, h, half, kt) STAGE((4 + (b) * 2 + (h)) * G_HT * 2, pB, ((size_t)(half) * G_HALF * K + (size_t)(kt) * G_BK) * 2, K)
; #define LDA(dst, b, h) for (int m = 0; m < 4; ++m) for (int k = 0; k < 2; ++k) \
;     dst[m][k] = *reinterpret_cast<const bf16x8*>(aRd + (((b) * 2 + (h)) * G_HT * 2 + m * 2048 + k * 1024))
; #define LDB(dst, b, h) for (int n = 0; n < 2; ++n) for (int k = 0; k < 2; ++k) \
;     dst[n][k] = *reinterpret_cast<const bf16x8*>(bRd + (((b) * 2 + (h)) * G_HT * 2 + n * 2048 + k * 1024))
; #define MMA(ai, bj, At, Bx) do { __builtin_amdgcn_s_setprio(1); \
;     for (int m = 0; m < 4; ++m) for (int n = 0; n < 2; ++n) for (int k = 0; k < 2; ++k) \
;       acc[ai][bj][m][n] = __builtin_amdgcn_mfma_f32_16x16x32_bf16(Bx[n][k], At[m][k], acc[ai][bj][m][n], 0, 0, 0);     \
;     __builtin_amdgcn_s_setprio(0); } while (0)
; #define WAIT_V(n) asm volatile("s_waitcnt vmcnt(" #n ")" ::: "memory")
; #define WAIT_L(n) asm volatile("s_waitcnt lgkmcnt(" #n ")" ::: "memory")
; #define BAR __builtin_amdgcn_s_barrier()
; #define SCHED __builtin_amdgcn_sched_barrier(0)
; template <int EPI>
; __device__ __forceinline__ void gemm_tile(const bf16* __restrict__ A, int lda, const bf16* __restrict__ Bt, int K,
;                                           int brow, int bcol, const EpiArgs& ea, char* shmc, bool has_next, int nbrow, int nbcol, bool first_tile) {
;     ...
;     WAIT_V(6); BAR; MMA(1, 1, At, B1); BAR;
;     LDB(B0, 1, 0); SCHED; LDA(At, 1, 0); STA(0, 1, 1, t + 2);
;     WAIT_L(8); BAR; WAIT_L(0); MMA(0, 0, At, B0); BAR; SCHED;
;     LDB(B1, 1, 1); STB(1, 0, 0, t + 3);
;     BAR; WAIT_L(0); MMA(0, 1, At, B1); BAR;
;     LDA(At, 1, 1); STA(1, 0, 0, t + 3);
;     BAR; WAIT_L(0); MMA(1, 0, At, B0); BAR; SCHED;
	s_setprio 1
	v_mfma_f32_16x16x32_bf16 v[28:31], v[210:213], v[178:181], v[28:31]
	v_mfma_f32_16x16x32_bf16 v[24:27], v[218:221], v[178:181], v[24:27]
	v_mfma_f32_16x16x32_bf16 v[20:23], v[210:213], v[186:189], v[20:23]
	v_mfma_f32_16x16x32_bf16 v[16:19], v[218:221], v[186:189], v[16:19]
	v_mfma_f32_16x16x32_bf16 v[12:15], v[210:213], v[194:197], v[12:15]
	v_mfma_f32_16x16x32_bf16 v[8:11], v[218:221], v[194:197], v[8:11]
	v_mfma_f32_16x16x32_bf16 v[4:7], v[210:213], v[202:205], v[4:7]
	v_mfma_f32_16x16x32_bf16 v[0:3], v[218:221], v[202:205], v[0:3]
	v_mfma_f32_16x16x32_bf16 v[28:31], v[214:217], v[182:185], v[28:31]
	v_mfma_f32_16x16x32_bf16 v[24:27], v[222:225], v[182:185], v[24:27]
	v_mfma_f32_16x16x32_bf16 v[20:23], v[214:217], v[190:193], v[20:23]
	v_mfma_f32_16x16x32_bf16 v[16:19], v[222:225], v[190:193], v[16:19]
	v_mfma_f32_16x16x32_bf16 v[12:15], v[214:217], v[198:201], v[12:15]
	v_mfma_f32_16x16x32_bf16 v[8:11], v[222:225], v[198:201], v[8:11]
	v_mfma_f32_16x16x32_bf16 v[4:7], v[214:217], v[206:209], v[4:7]
	v_mfma_f32_16x16x32_bf16 v[0:3], v[222:225], v[206:209], v[0:3]
	s_setprio 0
	s_barrier
	ds_read_b128 v[140:143], v153
	ds_read_b128 v[166:169], v154
	ds_read_b128 v[170:173], v155
	ds_read_b128 v[174:177], v156
	s_mov_b32 m0, s31
	ds_read_b128 v[178:181], v164 offset:32768
	ds_read_b128 v[182:185], v164 offset:33792
	ds_read_b128 v[186:189], v164 offset:34816
	ds_read_b128 v[190:193], v164 offset:35840
	ds_read_b128 v[194:197], v164 offset:36864
	ds_read_b128 v[198:201], v164 offset:37888
	ds_read_b128 v[202:205], v164 offset:38912
	ds_read_b128 v[206:209], v164 offset:39936
	v_lshl_add_u64 v[210:211], v[136:137], 0, s[42:43]
	global_load_lds_dwordx4 v[210:211], off
	v_lshl_add_u64 v[210:211], v[210:211], 0, s[10:11]
	s_mov_b32 m0, s34
	s_nop 0
	global_load_lds_dwordx4 v[210:211], off
	s_waitcnt lgkmcnt(8)
	s_barrier
	s_waitcnt lgkmcnt(0)
	s_setprio 1
	v_mfma_f32_16x16x32_bf16 v[124:127], v[140:143], v[178:181], v[124:127]
	v_mfma_f32_16x16x32_bf16 v[120:123], v[170:173], v[178:181], v[120:123]
	v_mfma_f32_16x16x32_bf16 v[116:119], v[140:143], v[186:189], v[116:119]
	v_mfma_f32_16x16x32_bf16 v[112:115], v[170:173], v[186:189], v[112:115]
	v_mfma_f32_16x16x32_bf16 v[108:111], v[140:143], v[194:197], v[108:111]
	v_mfma_f32_16x16x32_bf16 v[104:107], v[170:173], v[194:197], v[104:107]
	v_mfma_f32_16x16x32_bf16 v[100:103], v[140:143], v[202:205], v[100:103]
	v_mfma_f32_16x16x32_bf16 v[96:99], v[170:173], v[202:205], v[96:99]
	v_mfma_f32_16x16x32_bf16 v[124:127], v[166:169], v[182:185], v[124:127]
	v_mfma_f32_16x16x32_bf16 v[120:123], v[174:177], v[182:185], v[120:123]
	v_mfma_f32_16x16x32_bf16 v[116:119], v[166:169], v[190:193], v[116:119]
	v_mfma_f32_16x16x32_bf16 v[112:115], v[174:177], v[190:193], v[112:115]
	v_mfma_f32_16x16x32_bf16 v[108:111], v[166:169], v[198:201], v[108:111]
	v_mfma_f32_16x16x32_bf16 v[104:107], v[174:177], v[198:201], v[104:107]
	v_mfma_f32_16x16x32_bf16 v[100:103], v[166:169], v[206:209], v[100:103]
	v_mfma_f32_16x16x32_bf16 v[96:99], v[174:177], v[206:209], v[96:99]
	s_setprio 0
	s_barrier
	s_add_u32 s42, s14, 0xfff00000
	s_addc_u32 s43, s15, -1
	s_mov_b64 s[48:49], s[42:43]
	s_mov_b32 m0, s13
	ds_read_b128 v[210:213], v158
	ds_read_b128 v[214:217], v159
	ds_read_b128 v[218:221], v160
	ds_read_b128 v[222:225], v161
	v_lshl_add_u64 v[226:227], v[138:139], 0, s[48:49]
	global_load_lds_dwordx4 v[226:227], off
	v_lshl_add_u64 v[226:227], v[226:227], 0, s[10:11]
	s_mov_b32 m0, s18
	s_nop 0
	global_load_lds_dwordx4 v[226:227], off
	s_barrier
	s_waitcnt lgkmcnt(0)
	s_setprio 1
	v_mfma_f32_16x16x32_bf16 v[92:95], v[210:213], v[178:181], v[92:95]
	v_mfma_f32_16x16x32_bf16 v[88:91], v[218:221], v[178:181], v[88:91]
	v_mfma_f32_16x16x32_bf16 v[84:87], v[210:213], v[186:189], v[84:87]
	v_mfma_f32_16x16x32_bf16 v[80:83], v[218:221], v[186:189], v[80:83]
	v_mfma_f32_16x16x32_bf16 v[76:79], v[210:213], v[194:197], v[76:79]
	v_mfma_f32_16x16x32_bf16 v[72:75], v[218:221], v[194:197], v[72:75]
	v_mfma_f32_16x16x32_bf16 v[68:71], v[210:213], v[202:205], v[68:71]
	v_mfma_f32_16x16x32_bf16 v[64:67], v[218:221], v[202:205], v[64:67]
	v_mfma_f32_16x16x32_bf16 v[92:95], v[214:217], v[182:185], v[92:95]
	v_mfma_f32_16x16x32_bf16 v[88:91], v[222:225], v[182:185], v[88:91]
	v_mfma_f32_16x16x32_bf16 v[84:87], v[214:217], v[190:193], v[84:87]
	v_mfma_f32_16x16x32_bf16 v[80:83], v[222:225], v[190:193], v[80:83]
	v_mfma_f32_16x16x32_bf16 v[76:79], v[214:217], v[198:201], v[76:79]
	v_mfma_f32_16x16x32_bf16 v[72:75], v[222:225], v[198:201], v[72:75]
	v_mfma_f32_16x16x32_bf16 v[68:71], v[214:217], v[206:209], v[68:71]
	v_mfma_f32_16x16x32_bf16 v[64:67], v[222:225], v[206:209], v[64:67]
	s_setprio 0
	s_mov_b32 m0, s19
	s_barrier
	ds_read_b128 v[178:181], v164 offset:49152
	ds_read_b128 v[182:185], v164 offset:50176
	ds_read_b128 v[186:189], v164 offset:51200
	ds_read_b128 v[190:193], v164 offset:52224
	ds_read_b128 v[194:197], v164 offset:53248
	ds_read_b128 v[198:201], v164 offset:54272
	ds_read_b128 v[202:205], v164 offset:55296
	ds_read_b128 v[206:209], v164 offset:56320
	v_lshl_add_u64 v[226:227], v[136:137], 0, s[42:43]
	global_load_lds_dwordx4 v[226:227], off
	v_lshl_add_u64 v[226:227], v[226:227], 0, s[10:11]
	s_mov_b32 m0, s20
	s_nop 0
	global_load_lds_dwordx4 v[226:227], off
	s_barrier
; #define STA(b, h, half, kt) STAGE(((b) * 2 + (h)) * G_HT * 2, pA, ((size_t)(half) * G_HALF * lda + (size_t)(kt) * G_BK) * 2, lda)
; #define STB(b, h, half, kt) STAGE((4 + (b) * 2 + (h)) * G_HT * 2, pB, ((size_t)(half) * G_HALF * K + (size_t)(kt) * G_BK) * 2, K)
; #define LDA(dst, b, h) for (int m = 0; m < 4; ++m) for (int k = 0; k < 2; ++k) \
;     dst[m][k] = *reinterpret_cast<const bf16x8*>(aRd + (((b) * 2 + (h)) * G_HT * 2 + m * 2048 + k * 1024))
; #define LDB(dst, b, h) for (int n = 0; n < 2; ++n) for (int k = 0; k < 2; ++k) \
;     dst[n][k] = *reinterpret_cast<const bf16x8*>(bRd + (((b) * 2 + (h)) * G_HT * 2 + n * 2048 + k * 1024))
; #define MMA(ai, bj, At, Bx) do { __builtin_amdgcn_s_setprio(1); \
;     for (int m = 0; m < 4; ++m) for (int n = 0; n < 2; ++n) for (int k = 0; k < 2; ++k) \
;       acc[ai][bj][m][n] = __builtin_amdgcn_mfma_f32_16x16x32_bf16(Bx[n][k], At[m][k], acc[ai][bj][m][n], 0, 0, 0);     \
;     __builtin_amdgcn_s_setprio(0); } while (0)
; #define WAIT_V(n) asm volatile("s_waitcnt vmcnt(" #n ")" ::: "memory")
; #define WAIT_L(n) asm volatile("s_waitcnt lgkmcnt(" #n ")" ::: "memory")
; #define BAR __builtin_amdgcn_s_barrier()
; #define SCHED __builtin_amdgcn_sched_barrier(0)
; template <int EPI>
; __device__ __forceinline__ void gemm_tile(const bf16* __restrict__ A, int lda, const bf16* __restrict__ Bt, int K,
;                                           int brow, int bcol, const EpiArgs& ea, char* shmc, bool has_next, int nbrow, int nbcol, bool first_tile) {
;     ...
;     BAR; WAIT_L(0); MMA(1, 0, At, B0); BAR; SCHED;
;     STB(1, 1, 1, t + 3);
;     WAIT_V(6); BAR; MMA(1, 1, At, B1); BAR;
;   }
;   { LDB(B0, 0, 0); LDA(At, 0, 0); STA(1, 1, 1, nt - 1);
;     BAR; WAIT_L(0); MMA(0, 0, At, B0); BAR;
;     LDB(B1, 0, 1); BAR; WAIT_L(0); MMA(0, 1, At, B1); BAR;
;     LDA(At, 0, 1); WAIT_V(4); BAR; WAIT_L(0); MMA(1, 0, At, B0); MMA(1, 1, At, B1); BAR; }
	s_waitcnt lgkmcnt(0)
	s_setprio 1
	v_mfma_f32_16x16x32_bf16 v[60:63], v[140:143], v[178:181], v[60:63]
	v_mfma_f32_16x16x32_bf16 v[56:59], v[170:173], v[178:181], v[56:59]
	v_mfma_f32_16x16x32_bf16 v[52:55], v[140:143], v[186:189], v[52:55]
	v_mfma_f32_16x16x32_bf16 v[48:51], v[170:173], v[186:189], v[48:51]
	v_mfma_f32_16x16x32_bf16 v[44:47], v[140:143], v[194:197], v[44:47]
	v_mfma_f32_16x16x32_bf16 v[40:43], v[170:173], v[194:197], v[40:43]
	v_mfma_f32_16x16x32_bf16 v[36:39], v[140:143], v[202:205], v[36:39]
	v_mfma_f32_16x16x32_bf16 v[32:35], v[170:173], v[202:205], v[32:35]
	v_mfma_f32_16x16x32_bf16 v[60:63], v[166:169], v[182:185], v[60:63]
	v_mfma_f32_16x16x32_bf16 v[56:59], v[174:177], v[182:185], v[56:59]
	v_mfma_f32_16x16x32_bf16 v[52:55], v[166:169], v[190:193], v[52:55]
	v_mfma_f32_16x16x32_bf16 v[48:51], v[174:177], v[190:193], v[48:51]
	v_mfma_f32_16x16x32_bf16 v[44:47], v[166:169], v[198:201], v[44:47]
	v_mfma_f32_16x16x32_bf16 v[40:43], v[174:177], v[198:201], v[40:43]
	v_mfma_f32_16x16x32_bf16 v[36:39], v[166:169], v[206:209], v[36:39]
	v_mfma_f32_16x16x32_bf16 v[32:35], v[174:177], v[206:209], v[32:35]
	s_setprio 0
	s_barrier
	s_mov_b64 s[42:43], s[14:15]
	s_mov_b32 m0, s22
	v_lshl_add_u64 v[140:141], v[138:139], 0, s[42:43]
	global_load_lds_dwordx4 v[140:141], off
	v_lshl_add_u64 v[140:141], v[140:141], 0, s[10:11]
	s_mov_b32 m0, s23
	s_nop 0
	global_load_lds_dwordx4 v[140:141], off
	s_waitcnt vmcnt(6)
	s_barrier
	s_setprio 1
	v_mfma_f32_16x16x32_bf16 v[28:31], v[210:213], v[178:181], v[28:31]
	v_mfma_f32_16x16x32_bf16 v[24:27], v[218:221], v[178:181], v[24:27]
	v_mfma_f32_16x16x32_bf16 v[20:23], v[210:213], v[186:189], v[20:23]
	v_mfma_f32_16x16x32_bf16 v[16:19], v[218:221], v[186:189], v[16:19]
	v_mfma_f32_16x16x32_bf16 v[12:15], v[210:213], v[194:197], v[12:15]
	v_mfma_f32_16x16x32_bf16 v[8:11], v[218:221], v[194:197], v[8:11]
	v_mfma_f32_16x16x32_bf16 v[4:7], v[210:213], v[202:205], v[4:7]
	v_mfma_f32_16x16x32_bf16 v[0:3], v[218:221], v[202:205], v[0:3]
	v_mfma_f32_16x16x32_bf16 v[28:31], v[214:217], v[182:185], v[28:31]
	v_mfma_f32_16x16x32_bf16 v[24:27], v[222:225], v[182:185], v[24:27]
	v_mfma_f32_16x16x32_bf16 v[20:23], v[214:217], v[190:193], v[20:23]
	v_mfma_f32_16x16x32_bf16 v[16:19], v[222:225], v[190:193], v[16:19]
	v_mfma_f32_16x16x32_bf16 v[12:15], v[214:217], v[198:201], v[12:15]
	v_mfma_f32_16x16x32_bf16 v[8:11], v[222:225], v[198:201], v[8:11]
	v_mfma_f32_16x16x32_bf16 v[4:7], v[214:217], v[206:209], v[4:7]
	v_mfma_f32_16x16x32_bf16 v[0:3], v[222:225], v[206:209], v[0:3]
	s_setprio 0
	s_add_i32 s28, s28, 2
	s_add_u32 s14, s14, 0x100
	s_addc_u32 s15, s15, 0
	s_cmp_lt_u32 s28, 60
	s_barrier
	s_cbranch_scc1 .LBB0_654
	s_mov_b64 s[14:15], 0x101f80
	s_mov_b32 m0, s29
	ds_read_b128 v[138:141], v145
	ds_read_b128 v[166:169], v146
	ds_read_b128 v[170:173], v147
	ds_read_b128 v[174:177], v148
	ds_read_b128 v[178:181], v164
	ds_read_b128 v[182:185], v164 offset:1024
	ds_read_b128 v[186:189], v164 offset:2048
	ds_read_b128 v[190:193], v164 offset:3072
	ds_read_b128 v[194:197], v164 offset:4096
	ds_read_b128 v[198:201], v164 offset:5120
	ds_read_b128 v[202:205], v164 offset:6144
	ds_read_b128 v[206:209], v164 offset:7168
	s_nop 0
	v_lshl_add_u64 v[136:137], v[136:137], 0, s[14:15]
	global_load_lds_dwordx4 v[136:137], off
	v_lshl_add_u64 v[136:137], v[136:137], 0, s[10:11]
	s_mov_b32 m0, s21
	s_nop 0
	global_load_lds_dwordx4 v[136:137], off
	s_barrier
	s_waitcnt lgkmcnt(0)
	s_setprio 1
	s_waitcnt lgkmcnt(0)
	v_mfma_f32_16x16x32_bf16 v[124:127], v[138:141], v[178:181], v[124:127]
	v_mfma_f32_16x16x32_bf16 v[116:119], v[138:141], v[186:189], v[116:119]
	v_mfma_f32_16x16x32_bf16 v[112:115], v[170:173], v[186:189], v[112:115]
	v_mfma_f32_16x16x32_bf16 v[100:103], v[138:141], v[202:205], v[100:103]
	v_mfma_f32_16x16x32_bf16 v[96:99], v[170:173], v[202:205], v[96:99]
	v_mfma_f32_16x16x32_bf16 v[124:127], v[166:169], v[182:185], v[124:127]
	v_mfma_f32_16x16x32_bf16 v[120:123], v[170:173], v[178:181], v[120:123]
	v_mfma_f32_16x16x32_bf16 v[116:119], v[166:169], v[190:193], v[116:119]
	v_mfma_f32_16x16x32_bf16 v[112:115], v[174:177], v[190:193], v[112:115]
	v_mfma_f32_16x16x32_bf16 v[108:111], v[138:141], v[194:197], v[108:111]
	v_mfma_f32_16x16x32_bf16 v[104:107], v[170:173], v[194:197], v[104:107]
	v_mfma_f32_16x16x32_bf16 v[100:103], v[166:169], v[206:209], v[100:103]
	v_mfma_f32_16x16x32_bf16 v[96:99], v[174:177], v[206:209], v[96:99]
	v_mfma_f32_16x16x32_bf16 v[210:213], v[174:177], v[182:185], v[120:123]
	v_mfma_f32_16x16x32_bf16 v[214:217], v[166:169], v[198:201], v[108:111]
	v_mfma_f32_16x16x32_bf16 v[218:221], v[174:177], v[198:201], v[104:107]
	s_setprio 0
	s_barrier
	s_nop 0
	ds_read_b128 v[104:107], v149
	ds_read_b128 v[108:111], v150
	ds_read_b128 v[120:123], v151
	ds_read_b128 v[222:225], v152
	s_barrier
	s_waitcnt lgkmcnt(0)
	s_setprio 1
	s_waitcnt lgkmcnt(0)
	v_mfma_f32_16x16x32_bf16 v[84:87], v[104:107], v[186:189], v[84:87]
	v_mfma_f32_16x16x32_bf16 v[80:83], v[120:123], v[186:189], v[80:83]
	v_mfma_f32_16x16x32_bf16 v[68:71], v[104:107], v[202:205], v[68:71]
	v_mfma_f32_16x16x32_bf16 v[92:95], v[104:107], v[178:181], v[92:95]
	v_mfma_f32_16x16x32_bf16 v[88:91], v[120:123], v[178:181], v[88:91]
	v_mfma_f32_16x16x32_bf16 v[84:87], v[108:111], v[190:193], v[84:87]
	v_mfma_f32_16x16x32_bf16 v[80:83], v[222:225], v[190:193], v[80:83]
	v_mfma_f32_16x16x32_bf16 v[76:79], v[104:107], v[194:197], v[76:79]
	v_mfma_f32_16x16x32_bf16 v[72:75], v[120:123], v[194:197], v[72:75]
	v_mfma_f32_16x16x32_bf16 v[68:71], v[108:111], v[206:209], v[68:71]
	v_mfma_f32_16x16x32_bf16 v[64:67], v[120:123], v[202:205], v[64:67]
	v_mfma_f32_16x16x32_bf16 v[226:229], v[108:111], v[182:185], v[92:95]
	v_mfma_f32_16x16x32_bf16 v[178:181], v[222:225], v[182:185], v[88:91]
	v_mfma_f32_16x16x32_bf16 v[182:185], v[108:111], v[198:201], v[76:79]
	v_mfma_f32_16x16x32_bf16 v[186:189], v[222:225], v[198:201], v[72:75]
	v_mfma_f32_16x16x32_bf16 v[190:193], v[222:225], v[206:209], v[64:67]
	s_setprio 0
	s_barrier
; #define LDA(dst, b, h) for (int m = 0; m < 4; ++m) for (int k = 0; k < 2; ++k) \
;     dst[m][k] = *reinterpret_cast<const bf16x8*>(aRd + (((b) * 2 + (h)) * G_HT * 2 + m * 2048 + k * 1024))
; #define LDB(dst, b, h) for (int n = 0; n < 2; ++n) for (int k = 0; k < 2; ++k) \
;     dst[n][k] = *reinterpret_cast<const bf16x8*>(bRd + (((b) * 2 + (h)) * G_HT * 2 + n * 2048 + k * 1024))
; #define MMA(ai, bj, At, Bx) do { __builtin_amdgcn_s_setprio(1); \
;     for (int m = 0; m < 4; ++m) for (int n = 0; n < 2; ++n) for (int k = 0; k < 2; ++k) \
;       acc[ai][bj][m][n] = __builtin_amdgcn_mfma_f32_16x16x32_bf16(Bx[n][k], At[m][k], acc[ai][bj][m][n], 0, 0, 0);     \
;     __builtin_amdgcn_s_setprio(0); } while (0)
; #define WAIT_V(n) asm volatile("s_waitcnt vmcnt(" #n ")" ::: "memory")
; #define WAIT_L(n) asm volatile("s_waitcnt lgkmcnt(" #n ")" ::: "memory")
; #define BAR __builtin_amdgcn_s_barrier()
; template <int EPI>
; __device__ __forceinline__ void gemm_tile(const bf16* __restrict__ A, int lda, const bf16* __restrict__ Bt, int K,
;                                           int brow, int bcol, const EpiArgs& ea, char* shmc, bool has_next, int nbrow, int nbcol, bool first_tile) {
;     ...
;     LDA(At, 0, 1); WAIT_V(4); BAR; WAIT_L(0); MMA(1, 0, At, B0); MMA(1, 1, At, B1); BAR; }
;   { LDB(B0, 1, 0); LDA(At, 1, 0); WAIT_V(2); BAR; WAIT_L(0); MMA(0, 0, At, B0); BAR;
	s_nop 0
	ds_read_b128 v[64:67], v164 offset:16384
	ds_read_b128 v[72:75], v164 offset:17408
	ds_read_b128 v[76:79], v164 offset:18432
	ds_read_b128 v[88:91], v164 offset:19456
	ds_read_b128 v[92:95], v164 offset:20480
	ds_read_b128 v[194:197], v164 offset:21504
	ds_read_b128 v[198:201], v164 offset:22528
	ds_read_b128 v[202:205], v164 offset:23552
	s_waitcnt vmcnt(4)
	s_barrier
	s_waitcnt lgkmcnt(0)
	s_setprio 1
	s_waitcnt lgkmcnt(0)
	v_mfma_f32_16x16x32_bf16 v[60:63], v[138:141], v[64:67], v[60:63]
	v_mfma_f32_16x16x32_bf16 v[52:55], v[138:141], v[76:79], v[52:55]
	v_mfma_f32_16x16x32_bf16 v[48:51], v[170:173], v[76:79], v[48:51]
	v_mfma_f32_16x16x32_bf16 v[36:39], v[138:141], v[198:201], v[36:39]
	v_mfma_f32_16x16x32_bf16 v[32:35], v[170:173], v[198:201], v[32:35]
	v_mfma_f32_16x16x32_bf16 v[60:63], v[166:169], v[72:75], v[60:63]
	v_mfma_f32_16x16x32_bf16 v[56:59], v[170:173], v[64:67], v[56:59]
	v_mfma_f32_16x16x32_bf16 v[52:55], v[166:169], v[88:91], v[52:55]
	v_mfma_f32_16x16x32_bf16 v[48:51], v[174:177], v[88:91], v[48:51]
	v_mfma_f32_16x16x32_bf16 v[44:47], v[138:141], v[92:95], v[44:47]
	v_mfma_f32_16x16x32_bf16 v[40:43], v[170:173], v[92:95], v[40:43]
	v_mfma_f32_16x16x32_bf16 v[36:39], v[166:169], v[202:205], v[36:39]
	v_mfma_f32_16x16x32_bf16 v[32:35], v[174:177], v[202:205], v[32:35]
	v_mfma_f32_16x16x32_bf16 v[206:209], v[174:177], v[72:75], v[56:59]
	v_mfma_f32_16x16x32_bf16 v[230:233], v[166:169], v[194:197], v[44:47]
	v_mfma_f32_16x16x32_bf16 v[234:237], v[174:177], v[194:197], v[40:43]
	s_setprio 0
	s_setprio 1
	v_mfma_f32_16x16x32_bf16 v[20:23], v[104:107], v[76:79], v[20:23]
	v_mfma_f32_16x16x32_bf16 v[16:19], v[120:123], v[76:79], v[16:19]
	v_mfma_f32_16x16x32_bf16 v[4:7], v[104:107], v[198:201], v[4:7]
	v_mfma_f32_16x16x32_bf16 v[28:31], v[104:107], v[64:67], v[28:31]
	v_mfma_f32_16x16x32_bf16 v[24:27], v[120:123], v[64:67], v[24:27]
	v_mfma_f32_16x16x32_bf16 v[20:23], v[108:111], v[88:91], v[20:23]
	v_mfma_f32_16x16x32_bf16 v[16:19], v[222:225], v[88:91], v[16:19]
	v_mfma_f32_16x16x32_bf16 v[12:15], v[104:107], v[92:95], v[12:15]
	v_mfma_f32_16x16x32_bf16 v[8:11], v[120:123], v[92:95], v[8:11]
	v_mfma_f32_16x16x32_bf16 v[4:7], v[108:111], v[202:205], v[4:7]
	v_mfma_f32_16x16x32_bf16 v[0:3], v[120:123], v[198:201], v[0:3]
	v_mfma_f32_16x16x32_bf16 v[136:139], v[108:111], v[72:75], v[28:31]
	v_mfma_f32_16x16x32_bf16 v[140:143], v[222:225], v[72:75], v[24:27]
	v_mfma_f32_16x16x32_bf16 v[166:169], v[108:111], v[194:197], v[12:15]
	v_mfma_f32_16x16x32_bf16 v[170:173], v[222:225], v[194:197], v[8:11]
	v_mfma_f32_16x16x32_bf16 v[174:177], v[222:225], v[202:205], v[0:3]
	s_setprio 0
	s_barrier
	s_nop 0
	ds_read_b128 v[0:3], v153
	ds_read_b128 v[8:11], v154
	ds_read_b128 v[12:15], v155
	ds_read_b128 v[194:197], v156
	ds_read_b128 v[24:27], v164 offset:32768
	ds_read_b128 v[28:31], v164 offset:33792
	ds_read_b128 v[40:43], v164 offset:34816
	ds_read_b128 v[44:47], v164 offset:35840
	ds_read_b128 v[56:59], v164 offset:36864
	ds_read_b128 v[64:67], v164 offset:37888
	ds_read_b128 v[198:201], v164 offset:38912
	ds_read_b128 v[202:205], v164 offset:39936
	s_waitcnt vmcnt(2)
	s_barrier
	s_waitcnt lgkmcnt(0)
	s_setprio 1
	s_waitcnt lgkmcnt(0)
	v_mfma_f32_16x16x32_bf16 v[72:75], v[0:3], v[24:27], v[124:127]
	v_mfma_f32_16x16x32_bf16 v[120:123], v[8:11], v[28:31], v[72:75]
	v_mfma_f32_16x16x32_bf16 v[72:75], v[12:15], v[24:27], v[210:213]
	v_mfma_f32_16x16x32_bf16 v[124:127], v[194:197], v[28:31], v[72:75]
	v_mfma_f32_16x16x32_bf16 v[72:75], v[0:3], v[40:43], v[116:119]
	v_mfma_f32_16x16x32_bf16 v[104:107], v[8:11], v[44:47], v[72:75]
	v_mfma_f32_16x16x32_bf16 v[72:75], v[12:15], v[40:43], v[112:115]
	v_mfma_f32_16x16x32_bf16 v[108:111], v[194:197], v[44:47], v[72:75]
	v_mfma_f32_16x16x32_bf16 v[72:75], v[0:3], v[56:59], v[214:217]
	v_mfma_f32_16x16x32_bf16 v[88:91], v[8:11], v[64:67], v[72:75]
	v_mfma_f32_16x16x32_bf16 v[72:75], v[12:15], v[56:59], v[218:221]
	v_mfma_f32_16x16x32_bf16 v[92:95], v[194:197], v[64:67], v[72:75]
	v_mfma_f32_16x16x32_bf16 v[72:75], v[0:3], v[198:201], v[100:103]
	v_mfma_f32_16x16x32_bf16 v[76:79], v[12:15], v[198:201], v[96:99]
	v_mfma_f32_16x16x32_bf16 v[72:75], v[8:11], v[202:205], v[72:75]
	v_mfma_f32_16x16x32_bf16 v[76:79], v[194:197], v[202:205], v[76:79]
	s_setprio 0
	s_barrier
; #define LDA(dst, b, h) for (int m = 0; m < 4; ++m) for (int k = 0; k < 2; ++k) \
;     dst[m][k] = *reinterpret_cast<const bf16x8*>(aRd + (((b) * 2 + (h)) * G_HT * 2 + m * 2048 + k * 1024))
; #define LDB(dst, b, h) for (int n = 0; n < 2; ++n) for (int k = 0; k < 2; ++k) \
;     dst[n][k] = *reinterpret_cast<const bf16x8*>(bRd + (((b) * 2 + (h)) * G_HT * 2 + n * 2048 + k * 1024))
; #define MMA(ai, bj, At, Bx) do { __builtin_amdgcn_s_setprio(1); \
;     for (int m = 0; m < 4; ++m) for (int n = 0; n < 2; ++n) for (int k = 0; k < 2; ++k) \
;       acc[ai][bj][m][n] = __builtin_amdgcn_mfma_f32_16x16x32_bf16(Bx[n][k], At[m][k], acc[ai][bj][m][n], 0, 0, 0);     \
;     __builtin_amdgcn_s_setprio(0); } while (0)
; #define WAIT_V(n) asm volatile("s_waitcnt vmcnt(" #n ")" ::: "memory")
; #define WAIT_L(n) asm volatile("s_waitcnt lgkmcnt(" #n ")" ::: "memory")
; #define BAR __builtin_amdgcn_s_barrier()
; template <int EPI>
; __device__ __forceinline__ void gemm_tile(const bf16* __restrict__ A, int lda, const bf16* __restrict__ Bt, int K,
;                                           int brow, int bcol, const EpiArgs& ea, char* shmc, bool has_next, int nbrow, int nbcol, bool first_tile) {
;     ...
;     LDB(B1, 1, 1); WAIT_V(0); BAR; WAIT_L(0); MMA(0, 1, At, B1); BAR;
;     LDA(At, 1, 1); BAR; WAIT_L(0); MMA(1, 0, At, B0); MMA(1, 1, At, B1); BAR; }
;   if (wr == 0) BAR;
	ds_read_b128 v[210:213], v158
	ds_read_b128 v[214:217], v159
	ds_read_b128 v[218:221], v160
	ds_read_b128 v[222:225], v161
	s_waitcnt vmcnt(0)
	s_barrier
	s_waitcnt lgkmcnt(0)
	s_setprio 1
	s_waitcnt lgkmcnt(0)
	v_mfma_f32_16x16x32_bf16 v[96:99], v[210:213], v[24:27], v[226:229]
	v_mfma_f32_16x16x32_bf16 v[24:27], v[218:221], v[24:27], v[178:181]
	v_mfma_f32_16x16x32_bf16 v[116:119], v[222:225], v[28:31], v[24:27]
	v_mfma_f32_16x16x32_bf16 v[24:27], v[210:213], v[40:43], v[84:87]
	v_mfma_f32_16x16x32_bf16 v[112:115], v[214:217], v[28:31], v[96:99]
	v_mfma_f32_16x16x32_bf16 v[96:99], v[214:217], v[44:47], v[24:27]
	v_mfma_f32_16x16x32_bf16 v[24:27], v[218:221], v[40:43], v[80:83]
	v_mfma_f32_16x16x32_bf16 v[100:103], v[222:225], v[44:47], v[24:27]
	v_mfma_f32_16x16x32_bf16 v[24:27], v[210:213], v[56:59], v[182:185]
	v_mfma_f32_16x16x32_bf16 v[80:83], v[214:217], v[64:67], v[24:27]
	v_mfma_f32_16x16x32_bf16 v[24:27], v[218:221], v[56:59], v[186:189]
	v_mfma_f32_16x16x32_bf16 v[84:87], v[222:225], v[64:67], v[24:27]
	v_mfma_f32_16x16x32_bf16 v[24:27], v[210:213], v[198:201], v[68:71]
	v_mfma_f32_16x16x32_bf16 v[64:67], v[214:217], v[202:205], v[24:27]
	v_mfma_f32_16x16x32_bf16 v[24:27], v[218:221], v[198:201], v[190:193]
	v_mfma_f32_16x16x32_bf16 v[68:71], v[222:225], v[202:205], v[24:27]
	s_setprio 0
	s_barrier
	ds_read_b128 v[178:181], v164 offset:49152
	ds_read_b128 v[182:185], v164 offset:50176
	ds_read_b128 v[186:189], v164 offset:51200
	ds_read_b128 v[190:193], v164 offset:52224
	ds_read_b128 v[198:201], v164 offset:53248
	ds_read_b128 v[202:205], v164 offset:54272
	ds_read_b128 v[226:229], v164 offset:55296
	ds_read_b128 v[238:241], v164 offset:56320
	s_barrier
	s_waitcnt lgkmcnt(0)
	s_setprio 1
	s_waitcnt lgkmcnt(0)
	v_mfma_f32_16x16x32_bf16 v[24:27], v[0:3], v[178:181], v[60:63]
	v_mfma_f32_16x16x32_bf16 v[56:59], v[8:11], v[182:185], v[24:27]
	v_mfma_f32_16x16x32_bf16 v[24:27], v[12:15], v[178:181], v[206:209]
	v_mfma_f32_16x16x32_bf16 v[60:63], v[194:197], v[182:185], v[24:27]
	v_mfma_f32_16x16x32_bf16 v[24:27], v[0:3], v[186:189], v[52:55]
	v_mfma_f32_16x16x32_bf16 v[40:43], v[8:11], v[190:193], v[24:27]
	v_mfma_f32_16x16x32_bf16 v[24:27], v[12:15], v[186:189], v[48:51]
	v_mfma_f32_16x16x32_bf16 v[44:47], v[194:197], v[190:193], v[24:27]
	v_mfma_f32_16x16x32_bf16 v[24:27], v[0:3], v[198:201], v[230:233]
	v_mfma_f32_16x16x32_bf16 v[0:3], v[0:3], v[226:229], v[36:39]
	v_mfma_f32_16x16x32_bf16 v[24:27], v[8:11], v[202:205], v[24:27]
	v_mfma_f32_16x16x32_bf16 v[28:31], v[12:15], v[198:201], v[234:237]
	v_mfma_f32_16x16x32_bf16 v[8:11], v[8:11], v[238:241], v[0:3]
	v_mfma_f32_16x16x32_bf16 v[0:3], v[12:15], v[226:229], v[32:35]
	v_mfma_f32_16x16x32_bf16 v[28:31], v[194:197], v[202:205], v[28:31]
	v_mfma_f32_16x16x32_bf16 v[12:15], v[194:197], v[238:241], v[0:3]
	s_setprio 0
	s_setprio 1
	v_mfma_f32_16x16x32_bf16 v[0:3], v[210:213], v[178:181], v[136:139]
	v_mfma_f32_16x16x32_bf16 v[48:51], v[214:217], v[182:185], v[0:3]
	v_mfma_f32_16x16x32_bf16 v[0:3], v[218:221], v[178:181], v[140:143]
	v_mfma_f32_16x16x32_bf16 v[52:55], v[222:225], v[182:185], v[0:3]
	v_mfma_f32_16x16x32_bf16 v[0:3], v[210:213], v[186:189], v[20:23]
	v_mfma_f32_16x16x32_bf16 v[32:35], v[214:217], v[190:193], v[0:3]
	v_mfma_f32_16x16x32_bf16 v[0:3], v[218:221], v[186:189], v[16:19]
	v_mfma_f32_16x16x32_bf16 v[36:39], v[222:225], v[190:193], v[0:3]
	v_mfma_f32_16x16x32_bf16 v[0:3], v[210:213], v[198:201], v[166:169]
	v_mfma_f32_16x16x32_bf16 v[16:19], v[214:217], v[202:205], v[0:3]
	v_mfma_f32_16x16x32_bf16 v[0:3], v[218:221], v[198:201], v[170:173]
	v_mfma_f32_16x16x32_bf16 v[20:23], v[222:225], v[202:205], v[0:3]
	v_mfma_f32_16x16x32_bf16 v[0:3], v[210:213], v[226:229], v[4:7]
	v_mfma_f32_16x16x32_bf16 v[4:7], v[218:221], v[226:229], v[174:177]
	v_mfma_f32_16x16x32_bf16 v[0:3], v[214:217], v[238:241], v[0:3]
	v_mfma_f32_16x16x32_bf16 v[4:7], v[222:225], v[238:241], v[4:7]
	s_setprio 0
	s_barrier
	s_and_saveexec_b64 s[14:15], s[4:5]
	s_cbranch_execz .LBB0_657
	s_barrier

; #define STA(b, h, half, kt) STAGE(((b) * 2 + (h)) * G_HT * 2, pA, ((size_t)(half) * G_HALF * lda + (size_t)(kt) * G_BK) * 2, lda)
; #define STB(b, h, half, kt) STAGE((4 + (b) * 2 + (h)) * G_HT * 2, pB, ((size_t)(half) * G_HALF * K + (size_t)(kt) * G_BK) * 2, K)
; #define LDA(dst, b, h) for (int m = 0; m < 4; ++m) for (int k = 0; k < 2; ++k) \
;     dst[m][k] = *reinterpret_cast<const bf16x8*>(aRd + (((b) * 2 + (h)) * G_HT * 2 + m * 2048 + k * 1024))
; #define LDB(dst, b, h) for (int n = 0; n < 2; ++n) for (int k = 0; k < 2; ++k) \
;     dst[n][k] = *reinterpret_cast<const bf16x8*>(bRd + (((b) * 2 + (h)) * G_HT * 2 + n * 2048 + k * 1024))
; #define MMA(ai, bj, At, Bx) do { __builtin_amdgcn_s_setprio(1); \
;     for (int m = 0; m < 4; ++m) for (int n = 0; n < 2; ++n) for (int k = 0; k < 2; ++k) \
;       acc[ai][bj][m][n] = __builtin_amdgcn_mfma_f32_16x16x32_bf16(Bx[n][k], At[m][k], acc[ai][bj][m][n], 0, 0, 0);     \
;     __builtin_amdgcn_s_setprio(0); } while (0)
; #define WAIT_V(n) asm volatile("s_waitcnt vmcnt(" #n ")" ::: "memory")
; #define WAIT_L(n) asm volatile("s_waitcnt lgkmcnt(" #n ")" ::: "memory")
; #define BAR __builtin_amdgcn_s_barrier()
; #define SCHED __builtin_amdgcn_sched_barrier(0)
; template <int EPI>
; __device__ __forceinline__ void gemm_tile(const bf16* __restrict__ A, int lda, const bf16* __restrict__ Bt, int K,
;                                           int brow, int bcol, const EpiArgs& ea, char* shmc, bool has_next, int nbrow, int nbcol, bool first_tile) {
;     ...
;     LDB(B0, 0, 0); SCHED; LDA(At, 0, 0); STA(1, 1, 1, t + 1);
;     WAIT_L(8); BAR; WAIT_L(0); MMA(0, 0, At, B0); BAR; SCHED;
;     LDB(B1, 0, 1); STB(0, 0, 0, t + 2);
;     BAR; WAIT_L(0); MMA(0, 1, At, B1); BAR;
;     LDA(At, 0, 1); STA(0, 0, 0, t + 2);
;     BAR; WAIT_L(0); MMA(1, 0, At, B0); BAR; SCHED;
;     STB(0, 1, 1, t + 2);
;     WAIT_V(6); BAR; MMA(1, 1, At, B1); BAR;
.LBB0_727:
	ds_read_b128 v[136:139], v141
	ds_read_b128 v[162:165], v142
	ds_read_b128 v[166:169], v143
	ds_read_b128 v[170:173], v144
	s_add_u32 s52, s20, 0xffffff00
	s_addc_u32 s53, s21, -1
	s_mov_b32 m0, s50
	ds_read_b128 v[174:177], v160
	ds_read_b128 v[178:181], v160 offset:1024
	ds_read_b128 v[182:185], v160 offset:2048
	ds_read_b128 v[186:189], v160 offset:3072
	ds_read_b128 v[190:193], v160 offset:4096
	ds_read_b128 v[194:197], v160 offset:5120
	ds_read_b128 v[198:201], v160 offset:6144
	ds_read_b128 v[202:205], v160 offset:7168
	v_lshl_add_u64 v[206:207], v[132:133], 0, s[52:53]
	global_load_lds_dwordx4 v[206:207], off
	v_lshl_add_u64 v[206:207], v[206:207], 0, s[10:11]
	s_mov_b32 m0, s34
	s_nop 0
	global_load_lds_dwordx4 v[206:207], off
	s_waitcnt lgkmcnt(8)
	s_barrier
	s_waitcnt lgkmcnt(0)
	s_setprio 1
	v_mfma_f32_16x16x32_bf16 v[124:127], v[136:139], v[174:177], v[124:127]
	v_mfma_f32_16x16x32_bf16 v[120:123], v[166:169], v[174:177], v[120:123]
	v_mfma_f32_16x16x32_bf16 v[116:119], v[136:139], v[182:185], v[116:119]
	v_mfma_f32_16x16x32_bf16 v[112:115], v[166:169], v[182:185], v[112:115]
	v_mfma_f32_16x16x32_bf16 v[108:111], v[136:139], v[190:193], v[108:111]
	v_mfma_f32_16x16x32_bf16 v[104:107], v[166:169], v[190:193], v[104:107]
	v_mfma_f32_16x16x32_bf16 v[100:103], v[136:139], v[198:201], v[100:103]
	v_mfma_f32_16x16x32_bf16 v[96:99], v[166:169], v[198:201], v[96:99]
	v_mfma_f32_16x16x32_bf16 v[124:127], v[162:165], v[178:181], v[124:127]
	v_mfma_f32_16x16x32_bf16 v[120:123], v[170:173], v[178:181], v[120:123]
	v_mfma_f32_16x16x32_bf16 v[116:119], v[162:165], v[186:189], v[116:119]
	v_mfma_f32_16x16x32_bf16 v[112:115], v[170:173], v[186:189], v[112:115]
	v_mfma_f32_16x16x32_bf16 v[108:111], v[162:165], v[194:197], v[108:111]
	v_mfma_f32_16x16x32_bf16 v[104:107], v[170:173], v[194:197], v[104:107]
	v_mfma_f32_16x16x32_bf16 v[100:103], v[162:165], v[202:205], v[100:103]
	v_mfma_f32_16x16x32_bf16 v[96:99], v[170:173], v[202:205], v[96:99]
	s_setprio 0
	s_barrier
	s_add_u32 s52, s20, 0xffefff80
	s_addc_u32 s53, s21, -1
	s_mov_b64 s[54:55], s[52:53]
	s_mov_b32 m0, s41
	ds_read_b128 v[206:209], v145
	ds_read_b128 v[210:213], v146
	ds_read_b128 v[214:217], v147
	ds_read_b128 v[218:221], v148
	v_lshl_add_u64 v[222:223], v[134:135], 0, s[54:55]
	global_load_lds_dwordx4 v[222:223], off
	v_lshl_add_u64 v[222:223], v[222:223], 0, s[10:11]
	s_mov_b32 m0, s42
	s_nop 0
	global_load_lds_dwordx4 v[222:223], off
	s_barrier
	s_waitcnt lgkmcnt(0)
	s_setprio 1
	v_mfma_f32_16x16x32_bf16 v[92:95], v[206:209], v[174:177], v[92:95]
	v_mfma_f32_16x16x32_bf16 v[88:91], v[214:217], v[174:177], v[88:91]
	v_mfma_f32_16x16x32_bf16 v[84:87], v[206:209], v[182:185], v[84:87]
	v_mfma_f32_16x16x32_bf16 v[80:83], v[214:217], v[182:185], v[80:83]
	v_mfma_f32_16x16x32_bf16 v[76:79], v[206:209], v[190:193], v[76:79]
	v_mfma_f32_16x16x32_bf16 v[72:75], v[214:217], v[190:193], v[72:75]
	v_mfma_f32_16x16x32_bf16 v[68:71], v[206:209], v[198:201], v[68:71]
	v_mfma_f32_16x16x32_bf16 v[64:67], v[214:217], v[198:201], v[64:67]
	v_mfma_f32_16x16x32_bf16 v[92:95], v[210:213], v[178:181], v[92:95]
	v_mfma_f32_16x16x32_bf16 v[88:91], v[218:221], v[178:181], v[88:91]
	v_mfma_f32_16x16x32_bf16 v[84:87], v[210:213], v[186:189], v[84:87]
	v_mfma_f32_16x16x32_bf16 v[80:83], v[218:221], v[186:189], v[80:83]
	v_mfma_f32_16x16x32_bf16 v[76:79], v[210:213], v[194:197], v[76:79]
	v_mfma_f32_16x16x32_bf16 v[72:75], v[218:221], v[194:197], v[72:75]
	v_mfma_f32_16x16x32_bf16 v[68:71], v[210:213], v[202:205], v[68:71]
	v_mfma_f32_16x16x32_bf16 v[64:67], v[218:221], v[202:205], v[64:67]
	s_setprio 0
	s_mov_b32 m0, s1
	s_barrier
	ds_read_b128 v[174:177], v160 offset:16384
	ds_read_b128 v[178:181], v160 offset:17408
	ds_read_b128 v[182:185], v160 offset:18432
	ds_read_b128 v[186:189], v160 offset:19456
	ds_read_b128 v[190:193], v160 offset:20480
	ds_read_b128 v[194:197], v160 offset:21504
	ds_read_b128 v[198:201], v160 offset:22528
	ds_read_b128 v[202:205], v160 offset:23552
	v_lshl_add_u64 v[222:223], v[132:133], 0, s[52:53]
	global_load_lds_dwordx4 v[222:223], off
	v_lshl_add_u64 v[222:223], v[222:223], 0, s[10:11]
	s_add_i32 m0, s1, 0x2000
	s_nop 0
	global_load_lds_dwordx4 v[222:223], off
	s_barrier
	s_waitcnt lgkmcnt(0)
	s_setprio 1
	v_mfma_f32_16x16x32_bf16 v[60:63], v[136:139], v[174:177], v[60:63]
	v_mfma_f32_16x16x32_bf16 v[56:59], v[166:169], v[174:177], v[56:59]
	v_mfma_f32_16x16x32_bf16 v[52:55], v[136:139], v[182:185], v[52:55]
	v_mfma_f32_16x16x32_bf16 v[48:51], v[166:169], v[182:185], v[48:51]
	v_mfma_f32_16x16x32_bf16 v[44:47], v[136:139], v[190:193], v[44:47]
	v_mfma_f32_16x16x32_bf16 v[40:43], v[166:169], v[190:193], v[40:43]
	v_mfma_f32_16x16x32_bf16 v[36:39], v[136:139], v[198:201], v[36:39]
	v_mfma_f32_16x16x32_bf16 v[32:35], v[166:169], v[198:201], v[32:35]
	v_mfma_f32_16x16x32_bf16 v[60:63], v[162:165], v[178:181], v[60:63]
	v_mfma_f32_16x16x32_bf16 v[56:59], v[170:173], v[178:181], v[56:59]
	v_mfma_f32_16x16x32_bf16 v[52:55], v[162:165], v[186:189], v[52:55]
	v_mfma_f32_16x16x32_bf16 v[48:51], v[170:173], v[186:189], v[48:51]
	v_mfma_f32_16x16x32_bf16 v[44:47], v[162:165], v[194:197], v[44:47]
	v_mfma_f32_16x16x32_bf16 v[40:43], v[170:173], v[194:197], v[40:43]
	v_mfma_f32_16x16x32_bf16 v[36:39], v[162:165], v[202:205], v[36:39]
	v_mfma_f32_16x16x32_bf16 v[32:35], v[170:173], v[202:205], v[32:35]
	s_setprio 0
	s_barrier
	s_add_u32 s52, s20, 0xffffff80
	s_addc_u32 s53, s21, -1
	s_mov_b64 s[54:55], s[52:53]
	s_mov_b32 m0, s43
	v_lshl_add_u64 v[136:137], v[134:135], 0, s[54:55]
	global_load_lds_dwordx4 v[136:137], off
	v_lshl_add_u64 v[136:137], v[136:137], 0, s[10:11]
	s_mov_b32 m0, s48
	s_nop 0
	global_load_lds_dwordx4 v[136:137], off
	s_waitcnt vmcnt(6)
	s_barrier
; #define STA(b, h, half, kt) STAGE(((b) * 2 + (h)) * G_HT * 2, pA, ((size_t)(half) * G_HALF * lda + (size_t)(kt) * G_BK) * 2, lda)
; #define STB(b, h, half, kt) STAGE((4 + (b) * 2 + (h)) * G_HT * 2, pB, ((size_t)(half) * G_HALF * K + (size_t)(kt) * G_BK) * 2, K)
; #define LDA(dst, b, h) for (int m = 0; m < 4; ++m) for (int k = 0; k < 2; ++k) \
;     dst[m][k] = *reinterpret_cast<const bf16x8*>(aRd + (((b) * 2 + (h)) * G_HT * 2 + m * 2048 + k * 1024))
; #define LDB(dst, b, h) for (int n = 0; n < 2; ++n) for (int k = 0; k < 2; ++k) \
;     dst[n][k] = *reinterpret_cast<const bf16x8*>(bRd + (((b) * 2 + (h)) * G_HT * 2 + n * 2048 + k * 1024))
; #define MMA(ai, bj, At, Bx) do { __builtin_amdgcn_s_setprio(1); \
;     for (int m = 0; m < 4; ++m) for (int n = 0; n < 2; ++n) for (int k = 0; k < 2; ++k) \
;       acc[ai][bj][m][n] = __builtin_amdgcn_mfma_f32_16x16x32_bf16(Bx[n][k], At[m][k], acc[ai][bj][m][n], 0, 0, 0);     \
;     __builtin_amdgcn_s_setprio(0); } while (0)
; #define WAIT_V(n) asm volatile("s_waitcnt vmcnt(" #n ")" ::: "memory")
; #define WAIT_L(n) asm volatile("s_waitcnt lgkmcnt(" #n ")" ::: "memory")
; #define BAR __builtin_amdgcn_s_barrier()
; #define SCHED __builtin_amdgcn_sched_barrier(0)
; template <int EPI>
; __device__ __forceinline__ void gemm_tile(const bf16* __restrict__ A, int lda, const bf16* __restrict__ Bt, int K,
;                                           int brow, int bcol, const EpiArgs& ea, char* shmc, bool has_next, int nbrow, int nbcol, bool first_tile) {
;     ...
;     WAIT_V(6); BAR; MMA(1, 1, At, B1); BAR;
;     LDB(B0, 1, 0); SCHED; LDA(At, 1, 0); STA(0, 1, 1, t + 2);
;     WAIT_L(8); BAR; WAIT_L(0); MMA(0, 0, At, B0); BAR; SCHED;
;     LDB(B1, 1, 1); STB(1, 0, 0, t + 3);
;     BAR; WAIT_L(0); MMA(0, 1, At, B1); BAR;
;     LDA(At, 1, 1); STA(1, 0, 0, t + 3);
;     BAR; WAIT_L(0); MMA(1, 0, At, B0); BAR; SCHED;
	s_setprio 1
	v_mfma_f32_16x16x32_bf16 v[28:31], v[206:209], v[174:177], v[28:31]
	v_mfma_f32_16x16x32_bf16 v[24:27], v[214:217], v[174:177], v[24:27]
	v_mfma_f32_16x16x32_bf16 v[20:23], v[206:209], v[182:185], v[20:23]
	v_mfma_f32_16x16x32_bf16 v[16:19], v[214:217], v[182:185], v[16:19]
	v_mfma_f32_16x16x32_bf16 v[12:15], v[206:209], v[190:193], v[12:15]
	v_mfma_f32_16x16x32_bf16 v[8:11], v[214:217], v[190:193], v[8:11]
	v_mfma_f32_16x16x32_bf16 v[4:7], v[206:209], v[198:201], v[4:7]
	v_mfma_f32_16x16x32_bf16 v[0:3], v[214:217], v[198:201], v[0:3]
	v_mfma_f32_16x16x32_bf16 v[28:31], v[210:213], v[178:181], v[28:31]
	v_mfma_f32_16x16x32_bf16 v[24:27], v[218:221], v[178:181], v[24:27]
	v_mfma_f32_16x16x32_bf16 v[20:23], v[210:213], v[186:189], v[20:23]
	v_mfma_f32_16x16x32_bf16 v[16:19], v[218:221], v[186:189], v[16:19]
	v_mfma_f32_16x16x32_bf16 v[12:15], v[210:213], v[194:197], v[12:15]
	v_mfma_f32_16x16x32_bf16 v[8:11], v[218:221], v[194:197], v[8:11]
	v_mfma_f32_16x16x32_bf16 v[4:7], v[210:213], v[202:205], v[4:7]
	v_mfma_f32_16x16x32_bf16 v[0:3], v[218:221], v[202:205], v[0:3]
	s_setprio 0
	s_barrier
	ds_read_b128 v[136:139], v149
	ds_read_b128 v[162:165], v150
	ds_read_b128 v[166:169], v151
	ds_read_b128 v[170:173], v152
	ds_read_b128 v[174:177], v160 offset:32768
	ds_read_b128 v[178:181], v160 offset:33792
	ds_read_b128 v[182:185], v160 offset:34816
	ds_read_b128 v[186:189], v160 offset:35840
	ds_read_b128 v[190:193], v160 offset:36864
	ds_read_b128 v[194:197], v160 offset:37888
	ds_read_b128 v[198:201], v160 offset:38912
	ds_read_b128 v[202:205], v160 offset:39936
	s_add_i32 m0, s1, 0x4000
	v_lshl_add_u64 v[206:207], v[132:133], 0, s[52:53]
	global_load_lds_dwordx4 v[206:207], off
	v_lshl_add_u64 v[206:207], v[206:207], 0, s[10:11]
	s_add_i32 m0, s1, 0x6000
	s_nop 0
	global_load_lds_dwordx4 v[206:207], off
	s_waitcnt lgkmcnt(8)
	s_barrier
	s_waitcnt lgkmcnt(0)
	s_setprio 1
	v_mfma_f32_16x16x32_bf16 v[124:127], v[136:139], v[174:177], v[124:127]
	v_mfma_f32_16x16x32_bf16 v[120:123], v[166:169], v[174:177], v[120:123]
	v_mfma_f32_16x16x32_bf16 v[116:119], v[136:139], v[182:185], v[116:119]
	v_mfma_f32_16x16x32_bf16 v[112:115], v[166:169], v[182:185], v[112:115]
	v_mfma_f32_16x16x32_bf16 v[108:111], v[136:139], v[190:193], v[108:111]
	v_mfma_f32_16x16x32_bf16 v[104:107], v[166:169], v[190:193], v[104:107]
	v_mfma_f32_16x16x32_bf16 v[100:103], v[136:139], v[198:201], v[100:103]
	v_mfma_f32_16x16x32_bf16 v[96:99], v[166:169], v[198:201], v[96:99]
	v_mfma_f32_16x16x32_bf16 v[124:127], v[162:165], v[178:181], v[124:127]
	v_mfma_f32_16x16x32_bf16 v[120:123], v[170:173], v[178:181], v[120:123]
	v_mfma_f32_16x16x32_bf16 v[116:119], v[162:165], v[186:189], v[116:119]
	v_mfma_f32_16x16x32_bf16 v[112:115], v[170:173], v[186:189], v[112:115]
	v_mfma_f32_16x16x32_bf16 v[108:111], v[162:165], v[194:197], v[108:111]
	v_mfma_f32_16x16x32_bf16 v[104:107], v[170:173], v[194:197], v[104:107]
	v_mfma_f32_16x16x32_bf16 v[100:103], v[162:165], v[202:205], v[100:103]
	v_mfma_f32_16x16x32_bf16 v[96:99], v[170:173], v[202:205], v[96:99]
	s_setprio 0
	s_barrier
	s_add_u32 s52, s20, 0xfff00000
	s_addc_u32 s53, s21, -1
	s_mov_b64 s[54:55], s[52:53]
	s_mov_b32 m0, s7
	ds_read_b128 v[206:209], v153
	ds_read_b128 v[210:213], v154
	ds_read_b128 v[214:217], v155
	ds_read_b128 v[218:221], v156
	v_lshl_add_u64 v[222:223], v[134:135], 0, s[54:55]
	global_load_lds_dwordx4 v[222:223], off
	v_lshl_add_u64 v[222:223], v[222:223], 0, s[10:11]
	s_mov_b32 m0, s29
	s_nop 0
	global_load_lds_dwordx4 v[222:223], off
	s_barrier
	s_waitcnt lgkmcnt(0)
	s_setprio 1
	v_mfma_f32_16x16x32_bf16 v[92:95], v[206:209], v[174:177], v[92:95]
	v_mfma_f32_16x16x32_bf16 v[88:91], v[214:217], v[174:177], v[88:91]
	v_mfma_f32_16x16x32_bf16 v[84:87], v[206:209], v[182:185], v[84:87]
	v_mfma_f32_16x16x32_bf16 v[80:83], v[214:217], v[182:185], v[80:83]
	v_mfma_f32_16x16x32_bf16 v[76:79], v[206:209], v[190:193], v[76:79]
	v_mfma_f32_16x16x32_bf16 v[72:75], v[214:217], v[190:193], v[72:75]
	v_mfma_f32_16x16x32_bf16 v[68:71], v[206:209], v[198:201], v[68:71]
	v_mfma_f32_16x16x32_bf16 v[64:67], v[214:217], v[198:201], v[64:67]
	v_mfma_f32_16x16x32_bf16 v[92:95], v[210:213], v[178:181], v[92:95]
	v_mfma_f32_16x16x32_bf16 v[88:91], v[218:221], v[178:181], v[88:91]
	v_mfma_f32_16x16x32_bf16 v[84:87], v[210:213], v[186:189], v[84:87]
	v_mfma_f32_16x16x32_bf16 v[80:83], v[218:221], v[186:189], v[80:83]
	v_mfma_f32_16x16x32_bf16 v[76:79], v[210:213], v[194:197], v[76:79]
	v_mfma_f32_16x16x32_bf16 v[72:75], v[218:221], v[194:197], v[72:75]
	v_mfma_f32_16x16x32_bf16 v[68:71], v[210:213], v[202:205], v[68:71]
	v_mfma_f32_16x16x32_bf16 v[64:67], v[218:221], v[202:205], v[64:67]
	s_setprio 0
	s_mov_b32 m0, s30
	s_barrier
	ds_read_b128 v[174:177], v160 offset:49152
	ds_read_b128 v[178:181], v160 offset:50176
	ds_read_b128 v[182:185], v160 offset:51200
	ds_read_b128 v[186:189], v160 offset:52224
	ds_read_b128 v[190:193], v160 offset:53248
	ds_read_b128 v[194:197], v160 offset:54272
	ds_read_b128 v[198:201], v160 offset:55296
	ds_read_b128 v[202:205], v160 offset:56320
	v_lshl_add_u64 v[222:223], v[132:133], 0, s[52:53]
	global_load_lds_dwordx4 v[222:223], off
	v_lshl_add_u64 v[222:223], v[222:223], 0, s[10:11]
	s_mov_b32 m0, s31
	s_nop 0
	global_load_lds_dwordx4 v[222:223], off
	s_barrier
; #define STA(b, h, half, kt) STAGE(((b) * 2 + (h)) * G_HT * 2, pA, ((size_t)(half) * G_HALF * lda + (size_t)(kt) * G_BK) * 2, lda)
; #define STB(b, h, half, kt) STAGE((4 + (b) * 2 + (h)) * G_HT * 2, pB, ((size_t)(half) * G_HALF * K + (size_t)(kt) * G_BK) * 2, K)
; #define LDA(dst, b, h) for (int m = 0; m < 4; ++m) for (int k = 0; k < 2; ++k) \
;     dst[m][k] = *reinterpret_cast<const bf16x8*>(aRd + (((b) * 2 + (h)) * G_HT * 2 + m * 2048 + k * 1024))
; #define LDB(dst, b, h) for (int n = 0; n < 2; ++n) for (int k = 0; k < 2; ++k) \
;     dst[n][k] = *reinterpret_cast<const bf16x8*>(bRd + (((b) * 2 + (h)) * G_HT * 2 + n * 2048 + k * 1024))
; #define MMA(ai, bj, At, Bx) do { __builtin_amdgcn_s_setprio(1); \
;     for (int m = 0; m < 4; ++m) for (int n = 0; n < 2; ++n) for (int k = 0; k < 2; ++k) \
;       acc[ai][bj][m][n] = __builtin_amdgcn_mfma_f32_16x16x32_bf16(Bx[n][k], At[m][k], acc[ai][bj][m][n], 0, 0, 0);     \
;     __builtin_amdgcn_s_setprio(0); } while (0)
; #define WAIT_V(n) asm volatile("s_waitcnt vmcnt(" #n ")" ::: "memory")
; #define WAIT_L(n) asm volatile("s_waitcnt lgkmcnt(" #n ")" ::: "memory")
; #define BAR __builtin_amdgcn_s_barrier()
; #define SCHED __builtin_amdgcn_sched_barrier(0)
; template <int EPI>
; __device__ __forceinline__ void gemm_tile(const bf16* __restrict__ A, int lda, const bf16* __restrict__ Bt, int K,
;                                           int brow, int bcol, const EpiArgs& ea, char* shmc, bool has_next, int nbrow, int nbcol, bool first_tile) {
;     ...
;     BAR; WAIT_L(0); MMA(1, 0, At, B0); BAR; SCHED;
;     STB(1, 1, 1, t + 3);
;     WAIT_V(6); BAR; MMA(1, 1, At, B1); BAR;
;   }
;   { LDB(B0, 0, 0); LDA(At, 0, 0); STA(1, 1, 1, nt - 1);
;     BAR; WAIT_L(0); MMA(0, 0, At, B0); BAR;
;     LDB(B1, 0, 1); BAR; WAIT_L(0); MMA(0, 1, At, B1); BAR;
;     LDA(At, 0, 1); WAIT_V(4); BAR; WAIT_L(0); MMA(1, 0, At, B0); MMA(1, 1, At, B1); BAR; }
	s_waitcnt lgkmcnt(0)
	s_setprio 1
	v_mfma_f32_16x16x32_bf16 v[60:63], v[136:139], v[174:177], v[60:63]
	v_mfma_f32_16x16x32_bf16 v[56:59], v[166:169], v[174:177], v[56:59]
	v_mfma_f32_16x16x32_bf16 v[52:55], v[136:139], v[182:185], v[52:55]
	v_mfma_f32_16x16x32_bf16 v[48:51], v[166:169], v[182:185], v[48:51]
	v_mfma_f32_16x16x32_bf16 v[44:47], v[136:139], v[190:193], v[44:47]
	v_mfma_f32_16x16x32_bf16 v[40:43], v[166:169], v[190:193], v[40:43]
	v_mfma_f32_16x16x32_bf16 v[36:39], v[136:139], v[198:201], v[36:39]
	v_mfma_f32_16x16x32_bf16 v[32:35], v[166:169], v[198:201], v[32:35]
	v_mfma_f32_16x16x32_bf16 v[60:63], v[162:165], v[178:181], v[60:63]
	v_mfma_f32_16x16x32_bf16 v[56:59], v[170:173], v[178:181], v[56:59]
	v_mfma_f32_16x16x32_bf16 v[52:55], v[162:165], v[186:189], v[52:55]
	v_mfma_f32_16x16x32_bf16 v[48:51], v[170:173], v[186:189], v[48:51]
	v_mfma_f32_16x16x32_bf16 v[44:47], v[162:165], v[194:197], v[44:47]
	v_mfma_f32_16x16x32_bf16 v[40:43], v[170:173], v[194:197], v[40:43]
	v_mfma_f32_16x16x32_bf16 v[36:39], v[162:165], v[202:205], v[36:39]
	v_mfma_f32_16x16x32_bf16 v[32:35], v[170:173], v[202:205], v[32:35]
	s_setprio 0
	s_barrier
	s_mov_b64 s[52:53], s[20:21]
	s_mov_b32 m0, s35
	v_lshl_add_u64 v[136:137], v[134:135], 0, s[52:53]
	global_load_lds_dwordx4 v[136:137], off
	v_lshl_add_u64 v[136:137], v[136:137], 0, s[10:11]
	s_mov_b32 m0, s40
	s_nop 0
	global_load_lds_dwordx4 v[136:137], off
	s_waitcnt vmcnt(6)
	s_barrier
	s_setprio 1
	v_mfma_f32_16x16x32_bf16 v[28:31], v[206:209], v[174:177], v[28:31]
	v_mfma_f32_16x16x32_bf16 v[24:27], v[214:217], v[174:177], v[24:27]
	v_mfma_f32_16x16x32_bf16 v[20:23], v[206:209], v[182:185], v[20:23]
	v_mfma_f32_16x16x32_bf16 v[16:19], v[214:217], v[182:185], v[16:19]
	v_mfma_f32_16x16x32_bf16 v[12:15], v[206:209], v[190:193], v[12:15]
	v_mfma_f32_16x16x32_bf16 v[8:11], v[214:217], v[190:193], v[8:11]
	v_mfma_f32_16x16x32_bf16 v[4:7], v[206:209], v[198:201], v[4:7]
	v_mfma_f32_16x16x32_bf16 v[0:3], v[214:217], v[198:201], v[0:3]
	v_mfma_f32_16x16x32_bf16 v[28:31], v[210:213], v[178:181], v[28:31]
	v_mfma_f32_16x16x32_bf16 v[24:27], v[218:221], v[178:181], v[24:27]
	v_mfma_f32_16x16x32_bf16 v[20:23], v[210:213], v[186:189], v[20:23]
	v_mfma_f32_16x16x32_bf16 v[16:19], v[218:221], v[186:189], v[16:19]
	v_mfma_f32_16x16x32_bf16 v[12:15], v[210:213], v[194:197], v[12:15]
	v_mfma_f32_16x16x32_bf16 v[8:11], v[218:221], v[194:197], v[8:11]
	v_mfma_f32_16x16x32_bf16 v[4:7], v[210:213], v[202:205], v[4:7]
	v_mfma_f32_16x16x32_bf16 v[0:3], v[218:221], v[202:205], v[0:3]
	s_setprio 0
	s_add_i32 s49, s49, 2
	s_add_u32 s20, s20, 0x100
	s_addc_u32 s21, s21, 0
	s_cmp_lt_u32 s49, 60
	s_barrier
	s_cbranch_scc1 .LBB0_727
	s_mov_b64 s[20:21], 0x101f80
	s_mov_b32 m0, s50
	ds_read_b128 v[134:137], v141
	ds_read_b128 v[162:165], v142
	ds_read_b128 v[166:169], v143
	ds_read_b128 v[170:173], v144
	ds_read_b128 v[174:177], v160
	ds_read_b128 v[178:181], v160 offset:1024
	ds_read_b128 v[182:185], v160 offset:2048
	ds_read_b128 v[186:189], v160 offset:3072
	ds_read_b128 v[190:193], v160 offset:4096
	ds_read_b128 v[194:197], v160 offset:5120
	ds_read_b128 v[198:201], v160 offset:6144
	ds_read_b128 v[202:205], v160 offset:7168
	s_nop 0
	v_lshl_add_u64 v[132:133], v[132:133], 0, s[20:21]
	global_load_lds_dwordx4 v[132:133], off
	v_lshl_add_u64 v[132:133], v[132:133], 0, s[10:11]
	s_mov_b32 m0, s34
	s_nop 0
	global_load_lds_dwordx4 v[132:133], off
	s_barrier
	s_waitcnt lgkmcnt(0)
	s_setprio 1
	s_waitcnt lgkmcnt(0)
	v_mfma_f32_16x16x32_bf16 v[124:127], v[134:137], v[174:177], v[124:127]
	v_mfma_f32_16x16x32_bf16 v[120:123], v[166:169], v[174:177], v[120:123]
	v_mfma_f32_16x16x32_bf16 v[108:111], v[134:137], v[190:193], v[108:111]
	v_mfma_f32_16x16x32_bf16 v[104:107], v[166:169], v[190:193], v[104:107]
	v_mfma_f32_16x16x32_bf16 v[124:127], v[162:165], v[178:181], v[124:127]
	v_mfma_f32_16x16x32_bf16 v[120:123], v[170:173], v[178:181], v[120:123]
	v_mfma_f32_16x16x32_bf16 v[116:119], v[134:137], v[182:185], v[116:119]
	v_mfma_f32_16x16x32_bf16 v[112:115], v[166:169], v[182:185], v[112:115]
	v_mfma_f32_16x16x32_bf16 v[108:111], v[162:165], v[194:197], v[108:111]
	v_mfma_f32_16x16x32_bf16 v[104:107], v[170:173], v[194:197], v[104:107]
	v_mfma_f32_16x16x32_bf16 v[100:103], v[134:137], v[198:201], v[100:103]
	v_mfma_f32_16x16x32_bf16 v[96:99], v[166:169], v[198:201], v[96:99]
	v_mfma_f32_16x16x32_bf16 v[206:209], v[162:165], v[186:189], v[116:119]
	v_mfma_f32_16x16x32_bf16 v[210:213], v[170:173], v[186:189], v[112:115]
	v_mfma_f32_16x16x32_bf16 v[214:217], v[162:165], v[202:205], v[100:103]
	v_mfma_f32_16x16x32_bf16 v[218:221], v[170:173], v[202:205], v[96:99]
	s_setprio 0
	s_barrier
	s_nop 1
	ds_read_b128 v[96:99], v145
	ds_read_b128 v[100:103], v146
	ds_read_b128 v[112:115], v147
	ds_read_b128 v[116:119], v148
	s_barrier
	s_waitcnt lgkmcnt(0)
	s_setprio 1
	s_waitcnt lgkmcnt(0)
	v_mfma_f32_16x16x32_bf16 v[92:95], v[96:99], v[174:177], v[92:95]
	v_mfma_f32_16x16x32_bf16 v[88:91], v[112:115], v[174:177], v[88:91]
	v_mfma_f32_16x16x32_bf16 v[76:79], v[96:99], v[190:193], v[76:79]
	v_mfma_f32_16x16x32_bf16 v[72:75], v[112:115], v[190:193], v[72:75]
	v_mfma_f32_16x16x32_bf16 v[92:95], v[100:103], v[178:181], v[92:95]
	v_mfma_f32_16x16x32_bf16 v[88:91], v[116:119], v[178:181], v[88:91]
	v_mfma_f32_16x16x32_bf16 v[84:87], v[96:99], v[182:185], v[84:87]
	v_mfma_f32_16x16x32_bf16 v[80:83], v[112:115], v[182:185], v[80:83]
	v_mfma_f32_16x16x32_bf16 v[76:79], v[100:103], v[194:197], v[76:79]
	v_mfma_f32_16x16x32_bf16 v[72:75], v[116:119], v[194:197], v[72:75]
	v_mfma_f32_16x16x32_bf16 v[68:71], v[96:99], v[198:201], v[68:71]
	v_mfma_f32_16x16x32_bf16 v[64:67], v[112:115], v[198:201], v[64:67]
	v_mfma_f32_16x16x32_bf16 v[174:177], v[100:103], v[186:189], v[84:87]
	v_mfma_f32_16x16x32_bf16 v[178:181], v[116:119], v[186:189], v[80:83]
	v_mfma_f32_16x16x32_bf16 v[182:185], v[100:103], v[202:205], v[68:71]
	v_mfma_f32_16x16x32_bf16 v[186:189], v[116:119], v[202:205], v[64:67]
	s_setprio 0
	s_barrier
; #define LDA(dst, b, h) for (int m = 0; m < 4; ++m) for (int k = 0; k < 2; ++k) \
;     dst[m][k] = *reinterpret_cast<const bf16x8*>(aRd + (((b) * 2 + (h)) * G_HT * 2 + m * 2048 + k * 1024))
; #define LDB(dst, b, h) for (int n = 0; n < 2; ++n) for (int k = 0; k < 2; ++k) \
;     dst[n][k] = *reinterpret_cast<const bf16x8*>(bRd + (((b) * 2 + (h)) * G_HT * 2 + n * 2048 + k * 1024))
; #define MMA(ai, bj, At, Bx) do { __builtin_amdgcn_s_setprio(1); \
;     for (int m = 0; m < 4; ++m) for (int n = 0; n < 2; ++n) for (int k = 0; k < 2; ++k) \
;       acc[ai][bj][m][n] = __builtin_amdgcn_mfma_f32_16x16x32_bf16(Bx[n][k], At[m][k], acc[ai][bj][m][n], 0, 0, 0);     \
;     __builtin_amdgcn_s_setprio(0); } while (0)
; #define WAIT_V(n) asm volatile("s_waitcnt vmcnt(" #n ")" ::: "memory")
; #define WAIT_L(n) asm volatile("s_waitcnt lgkmcnt(" #n ")" ::: "memory")
; #define BAR __builtin_amdgcn_s_barrier()
; template <int EPI>
; __device__ __forceinline__ void gemm_tile(const bf16* __restrict__ A, int lda, const bf16* __restrict__ Bt, int K,
;                                           int brow, int bcol, const EpiArgs& ea, char* shmc, bool has_next, int nbrow, int nbcol, bool first_tile) {
;     ...
;     LDA(At, 0, 1); WAIT_V(4); BAR; WAIT_L(0); MMA(1, 0, At, B0); MMA(1, 1, At, B1); BAR; }
;   { LDB(B0, 1, 0); LDA(At, 1, 0); WAIT_V(2); BAR; WAIT_L(0); MMA(0, 0, At, B0); BAR;
	s_nop 1
	ds_read_b128 v[64:67], v160 offset:16384
	ds_read_b128 v[68:71], v160 offset:17408
	ds_read_b128 v[80:83], v160 offset:18432
	ds_read_b128 v[84:87], v160 offset:19456
	ds_read_b128 v[190:193], v160 offset:20480
	ds_read_b128 v[194:197], v160 offset:21504
	ds_read_b128 v[198:201], v160 offset:22528
	ds_read_b128 v[202:205], v160 offset:23552
	s_waitcnt vmcnt(4)
	s_barrier
	s_waitcnt lgkmcnt(0)
	s_setprio 1
	s_waitcnt lgkmcnt(0)
	v_mfma_f32_16x16x32_bf16 v[60:63], v[134:137], v[64:67], v[60:63]
	v_mfma_f32_16x16x32_bf16 v[52:55], v[134:137], v[80:83], v[52:55]
	v_mfma_f32_16x16x32_bf16 v[48:51], v[166:169], v[80:83], v[48:51]
	v_mfma_f32_16x16x32_bf16 v[36:39], v[134:137], v[198:201], v[36:39]
	v_mfma_f32_16x16x32_bf16 v[32:35], v[166:169], v[198:201], v[32:35]
	v_mfma_f32_16x16x32_bf16 v[60:63], v[162:165], v[68:71], v[60:63]
	v_mfma_f32_16x16x32_bf16 v[56:59], v[166:169], v[64:67], v[56:59]
	v_mfma_f32_16x16x32_bf16 v[52:55], v[162:165], v[84:87], v[52:55]
	v_mfma_f32_16x16x32_bf16 v[48:51], v[170:173], v[84:87], v[48:51]
	v_mfma_f32_16x16x32_bf16 v[44:47], v[134:137], v[190:193], v[44:47]
	v_mfma_f32_16x16x32_bf16 v[40:43], v[166:169], v[190:193], v[40:43]
	v_mfma_f32_16x16x32_bf16 v[36:39], v[162:165], v[202:205], v[36:39]
	v_mfma_f32_16x16x32_bf16 v[32:35], v[170:173], v[202:205], v[32:35]
	v_mfma_f32_16x16x32_bf16 v[222:225], v[170:173], v[68:71], v[56:59]
	v_mfma_f32_16x16x32_bf16 v[226:229], v[162:165], v[194:197], v[44:47]
	v_mfma_f32_16x16x32_bf16 v[230:233], v[170:173], v[194:197], v[40:43]
	s_setprio 0
	s_setprio 1
	v_mfma_f32_16x16x32_bf16 v[20:23], v[96:99], v[80:83], v[20:23]
	v_mfma_f32_16x16x32_bf16 v[16:19], v[112:115], v[80:83], v[16:19]
	v_mfma_f32_16x16x32_bf16 v[12:15], v[96:99], v[190:193], v[12:15]
	v_mfma_f32_16x16x32_bf16 v[8:11], v[112:115], v[190:193], v[8:11]
	v_mfma_f32_16x16x32_bf16 v[28:31], v[96:99], v[64:67], v[28:31]
	v_mfma_f32_16x16x32_bf16 v[24:27], v[112:115], v[64:67], v[24:27]
	v_mfma_f32_16x16x32_bf16 v[20:23], v[100:103], v[84:87], v[20:23]
	v_mfma_f32_16x16x32_bf16 v[16:19], v[116:119], v[84:87], v[16:19]
	v_mfma_f32_16x16x32_bf16 v[12:15], v[100:103], v[194:197], v[12:15]
	v_mfma_f32_16x16x32_bf16 v[8:11], v[116:119], v[194:197], v[8:11]
	v_mfma_f32_16x16x32_bf16 v[4:7], v[96:99], v[198:201], v[4:7]
	v_mfma_f32_16x16x32_bf16 v[0:3], v[112:115], v[198:201], v[0:3]
	v_mfma_f32_16x16x32_bf16 v[132:135], v[100:103], v[68:71], v[28:31]
	v_mfma_f32_16x16x32_bf16 v[136:139], v[116:119], v[68:71], v[24:27]
	v_mfma_f32_16x16x32_bf16 v[162:165], v[100:103], v[202:205], v[4:7]
	v_mfma_f32_16x16x32_bf16 v[166:169], v[116:119], v[202:205], v[0:3]
	s_setprio 0
	s_barrier
	s_nop 1
	ds_read_b128 v[0:3], v149
	ds_read_b128 v[4:7], v150
	ds_read_b128 v[170:173], v151
	ds_read_b128 v[190:193], v152
	ds_read_b128 v[24:27], v160 offset:32768
	ds_read_b128 v[28:31], v160 offset:33792
	ds_read_b128 v[40:43], v160 offset:34816
	ds_read_b128 v[44:47], v160 offset:35840
	ds_read_b128 v[56:59], v160 offset:36864
	ds_read_b128 v[194:197], v160 offset:37888
	ds_read_b128 v[198:201], v160 offset:38912
	ds_read_b128 v[202:205], v160 offset:39936
	s_waitcnt vmcnt(2)
	s_barrier
	s_waitcnt lgkmcnt(0)
	s_setprio 1
	s_waitcnt lgkmcnt(0)
	v_mfma_f32_16x16x32_bf16 v[64:67], v[0:3], v[24:27], v[124:127]
	v_mfma_f32_16x16x32_bf16 v[112:115], v[4:7], v[28:31], v[64:67]
	v_mfma_f32_16x16x32_bf16 v[64:67], v[170:173], v[24:27], v[120:123]
	v_mfma_f32_16x16x32_bf16 v[116:119], v[190:193], v[28:31], v[64:67]
	v_mfma_f32_16x16x32_bf16 v[64:67], v[0:3], v[40:43], v[206:209]
	v_mfma_f32_16x16x32_bf16 v[96:99], v[4:7], v[44:47], v[64:67]
	v_mfma_f32_16x16x32_bf16 v[64:67], v[170:173], v[40:43], v[210:213]
	v_mfma_f32_16x16x32_bf16 v[100:103], v[190:193], v[44:47], v[64:67]
	v_mfma_f32_16x16x32_bf16 v[64:67], v[0:3], v[56:59], v[108:111]
	v_mfma_f32_16x16x32_bf16 v[80:83], v[4:7], v[194:197], v[64:67]
	v_mfma_f32_16x16x32_bf16 v[64:67], v[170:173], v[56:59], v[104:107]
	v_mfma_f32_16x16x32_bf16 v[84:87], v[190:193], v[194:197], v[64:67]
	v_mfma_f32_16x16x32_bf16 v[64:67], v[0:3], v[198:201], v[214:217]
	v_mfma_f32_16x16x32_bf16 v[68:71], v[170:173], v[198:201], v[218:221]
	v_mfma_f32_16x16x32_bf16 v[64:67], v[4:7], v[202:205], v[64:67]
	v_mfma_f32_16x16x32_bf16 v[68:71], v[190:193], v[202:205], v[68:71]
	s_setprio 0
	s_barrier
; #define LDA(dst, b, h) for (int m = 0; m < 4; ++m) for (int k = 0; k < 2; ++k) \
;     dst[m][k] = *reinterpret_cast<const bf16x8*>(aRd + (((b) * 2 + (h)) * G_HT * 2 + m * 2048 + k * 1024))
; #define LDB(dst, b, h) for (int n = 0; n < 2; ++n) for (int k = 0; k < 2; ++k) \
;     dst[n][k] = *reinterpret_cast<const bf16x8*>(bRd + (((b) * 2 + (h)) * G_HT * 2 + n * 2048 + k * 1024))
; #define MMA(ai, bj, At, Bx) do { __builtin_amdgcn_s_setprio(1); \
;     for (int m = 0; m < 4; ++m) for (int n = 0; n < 2; ++n) for (int k = 0; k < 2; ++k) \
;       acc[ai][bj][m][n] = __builtin_amdgcn_mfma_f32_16x16x32_bf16(Bx[n][k], At[m][k], acc[ai][bj][m][n], 0, 0, 0);     \
;     __builtin_amdgcn_s_setprio(0); } while (0)
; #define WAIT_V(n) asm volatile("s_waitcnt vmcnt(" #n ")" ::: "memory")
; #define WAIT_L(n) asm volatile("s_waitcnt lgkmcnt(" #n ")" ::: "memory")
; #define BAR __builtin_amdgcn_s_barrier()
; template <int EPI>
; __device__ __forceinline__ void gemm_tile(const bf16* __restrict__ A, int lda, const bf16* __restrict__ Bt, int K,
;                                           int brow, int bcol, const EpiArgs& ea, char* shmc, bool has_next, int nbrow, int nbcol, bool first_tile) {
;     ...
;     LDB(B1, 1, 1); WAIT_V(0); BAR; WAIT_L(0); MMA(0, 1, At, B1); BAR;
;     LDA(At, 1, 1); BAR; WAIT_L(0); MMA(1, 0, At, B0); MMA(1, 1, At, B1); BAR; }
;   if (wr == 0) BAR;
	ds_read_b128 v[206:209], v153
	ds_read_b128 v[210:213], v154
	ds_read_b128 v[214:217], v155
	ds_read_b128 v[218:221], v156
	s_waitcnt vmcnt(0)
	s_barrier
	s_waitcnt lgkmcnt(0)
	s_setprio 1
	s_waitcnt lgkmcnt(0)
	v_mfma_f32_16x16x32_bf16 v[92:95], v[206:209], v[24:27], v[92:95]
	v_mfma_f32_16x16x32_bf16 v[24:27], v[214:217], v[24:27], v[88:91]
	v_mfma_f32_16x16x32_bf16 v[124:127], v[218:221], v[28:31], v[24:27]
	v_mfma_f32_16x16x32_bf16 v[24:27], v[206:209], v[40:43], v[174:177]
	v_mfma_f32_16x16x32_bf16 v[104:107], v[210:213], v[44:47], v[24:27]
	v_mfma_f32_16x16x32_bf16 v[24:27], v[214:217], v[40:43], v[178:181]
	v_mfma_f32_16x16x32_bf16 v[108:111], v[218:221], v[44:47], v[24:27]
	v_mfma_f32_16x16x32_bf16 v[24:27], v[206:209], v[56:59], v[76:79]
	v_mfma_f32_16x16x32_bf16 v[88:91], v[210:213], v[194:197], v[24:27]
	v_mfma_f32_16x16x32_bf16 v[24:27], v[214:217], v[56:59], v[72:75]
	v_mfma_f32_16x16x32_bf16 v[120:123], v[210:213], v[28:31], v[92:95]
	v_mfma_f32_16x16x32_bf16 v[92:95], v[218:221], v[194:197], v[24:27]
	v_mfma_f32_16x16x32_bf16 v[24:27], v[206:209], v[198:201], v[182:185]
	v_mfma_f32_16x16x32_bf16 v[72:75], v[210:213], v[202:205], v[24:27]
	v_mfma_f32_16x16x32_bf16 v[24:27], v[214:217], v[198:201], v[186:189]
	v_mfma_f32_16x16x32_bf16 v[76:79], v[218:221], v[202:205], v[24:27]
	s_setprio 0
	s_barrier
	ds_read_b128 v[174:177], v160 offset:49152
	ds_read_b128 v[178:181], v160 offset:50176
	ds_read_b128 v[182:185], v160 offset:51200
	ds_read_b128 v[186:189], v160 offset:52224
	ds_read_b128 v[194:197], v160 offset:53248
	ds_read_b128 v[198:201], v160 offset:54272
	ds_read_b128 v[202:205], v160 offset:55296
	ds_read_b128 v[234:237], v160 offset:56320
	s_barrier
	s_waitcnt lgkmcnt(0)
	s_setprio 1
	s_waitcnt lgkmcnt(0)
	v_mfma_f32_16x16x32_bf16 v[24:27], v[0:3], v[174:177], v[60:63]
	v_mfma_f32_16x16x32_bf16 v[56:59], v[4:7], v[178:181], v[24:27]
	v_mfma_f32_16x16x32_bf16 v[24:27], v[170:173], v[174:177], v[222:225]
	v_mfma_f32_16x16x32_bf16 v[60:63], v[190:193], v[178:181], v[24:27]
	v_mfma_f32_16x16x32_bf16 v[24:27], v[0:3], v[182:185], v[52:55]
	v_mfma_f32_16x16x32_bf16 v[40:43], v[4:7], v[186:189], v[24:27]
	v_mfma_f32_16x16x32_bf16 v[24:27], v[170:173], v[182:185], v[48:51]
	v_mfma_f32_16x16x32_bf16 v[44:47], v[190:193], v[186:189], v[24:27]
	v_mfma_f32_16x16x32_bf16 v[24:27], v[0:3], v[194:197], v[226:229]
	v_mfma_f32_16x16x32_bf16 v[0:3], v[0:3], v[202:205], v[36:39]
	v_mfma_f32_16x16x32_bf16 v[24:27], v[4:7], v[198:201], v[24:27]
	v_mfma_f32_16x16x32_bf16 v[28:31], v[170:173], v[194:197], v[230:233]
	v_mfma_f32_16x16x32_bf16 v[0:3], v[4:7], v[234:237], v[0:3]
	v_mfma_f32_16x16x32_bf16 v[4:7], v[170:173], v[202:205], v[32:35]
	v_mfma_f32_16x16x32_bf16 v[28:31], v[190:193], v[198:201], v[28:31]
	v_mfma_f32_16x16x32_bf16 v[4:7], v[190:193], v[234:237], v[4:7]
	s_setprio 0
	s_setprio 1
	v_mfma_f32_16x16x32_bf16 v[32:35], v[206:209], v[174:177], v[132:135]
	v_mfma_f32_16x16x32_bf16 v[48:51], v[210:213], v[178:181], v[32:35]
	v_mfma_f32_16x16x32_bf16 v[32:35], v[214:217], v[174:177], v[136:139]
	v_mfma_f32_16x16x32_bf16 v[20:23], v[206:209], v[182:185], v[20:23]
	v_mfma_f32_16x16x32_bf16 v[16:19], v[214:217], v[182:185], v[16:19]
	v_mfma_f32_16x16x32_bf16 v[12:15], v[206:209], v[194:197], v[12:15]
	v_mfma_f32_16x16x32_bf16 v[8:11], v[214:217], v[194:197], v[8:11]
	v_mfma_f32_16x16x32_bf16 v[52:55], v[218:221], v[178:181], v[32:35]
	v_mfma_f32_16x16x32_bf16 v[32:35], v[210:213], v[186:189], v[20:23]
	v_mfma_f32_16x16x32_bf16 v[36:39], v[218:221], v[186:189], v[16:19]
	v_mfma_f32_16x16x32_bf16 v[16:19], v[210:213], v[198:201], v[12:15]
	v_mfma_f32_16x16x32_bf16 v[20:23], v[218:221], v[198:201], v[8:11]
	v_mfma_f32_16x16x32_bf16 v[8:11], v[206:209], v[202:205], v[162:165]
	v_mfma_f32_16x16x32_bf16 v[12:15], v[214:217], v[202:205], v[166:169]
	v_mfma_f32_16x16x32_bf16 v[8:11], v[210:213], v[234:237], v[8:11]
	v_mfma_f32_16x16x32_bf16 v[12:15], v[218:221], v[234:237], v[12:15]
	s_setprio 0
	s_barrier
	s_and_saveexec_b64 s[20:21], s[4:5]
	s_cbranch_execz .LBB0_730
	s_barrier

; #define STA(b, h, half, kt) STAGE(((b) * 2 + (h)) * G_HT * 2, pA, ((size_t)(half) * G_HALF * lda + (size_t)(kt) * G_BK) * 2, lda)
; #define STB(b, h, half, kt) STAGE((4 + (b) * 2 + (h)) * G_HT * 2, pB, ((size_t)(half) * G_HALF * K + (size_t)(kt) * G_BK) * 2, K)
; #define LDA(dst, b, h) for (int m = 0; m < 4; ++m) for (int k = 0; k < 2; ++k) \
;     dst[m][k] = *reinterpret_cast<const bf16x8*>(aRd + (((b) * 2 + (h)) * G_HT * 2 + m * 2048 + k * 1024))
; #define LDB(dst, b, h) for (int n = 0; n < 2; ++n) for (int k = 0; k < 2; ++k) \
;     dst[n][k] = *reinterpret_cast<const bf16x8*>(bRd + (((b) * 2 + (h)) * G_HT * 2 + n * 2048 + k * 1024))
; #define MMA(ai, bj, At, Bx) do { __builtin_amdgcn_s_setprio(1); \
;     for (int m = 0; m < 4; ++m) for (int n = 0; n < 2; ++n) for (int k = 0; k < 2; ++k) \
;       acc[ai][bj][m][n] = __builtin_amdgcn_mfma_f32_16x16x32_bf16(Bx[n][k], At[m][k], acc[ai][bj][m][n], 0, 0, 0);     \
;     __builtin_amdgcn_s_setprio(0); } while (0)
; #define WAIT_V(n) asm volatile("s_waitcnt vmcnt(" #n ")" ::: "memory")
; #define WAIT_L(n) asm volatile("s_waitcnt lgkmcnt(" #n ")" ::: "memory")
; #define BAR __builtin_amdgcn_s_barrier()
; #define SCHED __builtin_amdgcn_sched_barrier(0)
; template <int EPI>
; __device__ __forceinline__ void gemm_tile(const bf16* __restrict__ A, int lda, const bf16* __restrict__ Bt, int K,
;                                           int brow, int bcol, const EpiArgs& ea, char* shmc, bool has_next, int nbrow, int nbcol, bool first_tile) {
;     ...
;     LDB(B0, 0, 0); SCHED; LDA(At, 0, 0); STA(1, 1, 1, t + 1);
;     WAIT_L(8); BAR; WAIT_L(0); MMA(0, 0, At, B0); BAR; SCHED;
;     LDB(B1, 0, 1); STB(0, 0, 0, t + 2);
;     BAR; WAIT_L(0); MMA(0, 1, At, B1); BAR;
;     LDA(At, 0, 1); STA(0, 0, 0, t + 2);
;     BAR; WAIT_L(0); MMA(1, 0, At, B0); BAR; SCHED;
;     STB(0, 1, 1, t + 2);
;     WAIT_V(6); BAR; MMA(1, 1, At, B1); BAR;
.LBB0_784:
	ds_read_b128 v[136:139], v141
	ds_read_b128 v[162:165], v142
	ds_read_b128 v[166:169], v143
	ds_read_b128 v[170:173], v144
	s_add_u32 s40, s18, 0xffffff00
	s_addc_u32 s41, s19, -1
	s_mov_b32 m0, s34
	ds_read_b128 v[174:177], v160
	ds_read_b128 v[178:181], v160 offset:1024
	ds_read_b128 v[182:185], v160 offset:2048
	ds_read_b128 v[186:189], v160 offset:3072
	ds_read_b128 v[190:193], v160 offset:4096
	ds_read_b128 v[194:197], v160 offset:5120
	ds_read_b128 v[198:201], v160 offset:6144
	ds_read_b128 v[202:205], v160 offset:7168
	v_lshl_add_u64 v[206:207], v[132:133], 0, s[40:41]
	global_load_lds_dwordx4 v[206:207], off
	v_lshl_add_u64 v[206:207], v[206:207], 0, s[4:5]
	s_mov_b32 m0, s24
	s_nop 0
	global_load_lds_dwordx4 v[206:207], off
	s_waitcnt lgkmcnt(8)
	s_barrier
	s_waitcnt lgkmcnt(0)
	s_setprio 1
	v_mfma_f32_16x16x32_bf16 v[124:127], v[136:139], v[174:177], v[124:127]
	v_mfma_f32_16x16x32_bf16 v[120:123], v[166:169], v[174:177], v[120:123]
	v_mfma_f32_16x16x32_bf16 v[116:119], v[136:139], v[182:185], v[116:119]
	v_mfma_f32_16x16x32_bf16 v[112:115], v[166:169], v[182:185], v[112:115]
	v_mfma_f32_16x16x32_bf16 v[108:111], v[136:139], v[190:193], v[108:111]
	v_mfma_f32_16x16x32_bf16 v[104:107], v[166:169], v[190:193], v[104:107]
	v_mfma_f32_16x16x32_bf16 v[100:103], v[136:139], v[198:201], v[100:103]
	v_mfma_f32_16x16x32_bf16 v[96:99], v[166:169], v[198:201], v[96:99]
	v_mfma_f32_16x16x32_bf16 v[124:127], v[162:165], v[178:181], v[124:127]
	v_mfma_f32_16x16x32_bf16 v[120:123], v[170:173], v[178:181], v[120:123]
	v_mfma_f32_16x16x32_bf16 v[116:119], v[162:165], v[186:189], v[116:119]
	v_mfma_f32_16x16x32_bf16 v[112:115], v[170:173], v[186:189], v[112:115]
	v_mfma_f32_16x16x32_bf16 v[108:111], v[162:165], v[194:197], v[108:111]
	v_mfma_f32_16x16x32_bf16 v[104:107], v[170:173], v[194:197], v[104:107]
	v_mfma_f32_16x16x32_bf16 v[100:103], v[162:165], v[202:205], v[100:103]
	v_mfma_f32_16x16x32_bf16 v[96:99], v[170:173], v[202:205], v[96:99]
	s_setprio 0
	s_barrier
	s_add_u32 s40, s18, 0xffbfff80
	s_addc_u32 s41, s19, -1
	s_mov_b64 s[42:43], s[40:41]
	s_mov_b32 m0, s27
	ds_read_b128 v[206:209], v145
	ds_read_b128 v[210:213], v146
	ds_read_b128 v[214:217], v147
	ds_read_b128 v[218:221], v148
	v_lshl_add_u64 v[222:223], v[134:135], 0, s[42:43]
	global_load_lds_dwordx4 v[222:223], off
	v_lshl_add_u64 v[222:223], v[222:223], 0, s[4:5]
	s_mov_b32 m0, s28
	s_nop 0
	global_load_lds_dwordx4 v[222:223], off
	s_barrier
	s_waitcnt lgkmcnt(0)
	s_setprio 1
	v_mfma_f32_16x16x32_bf16 v[92:95], v[206:209], v[174:177], v[92:95]
	v_mfma_f32_16x16x32_bf16 v[88:91], v[214:217], v[174:177], v[88:91]
	v_mfma_f32_16x16x32_bf16 v[84:87], v[206:209], v[182:185], v[84:87]
	v_mfma_f32_16x16x32_bf16 v[80:83], v[214:217], v[182:185], v[80:83]
	v_mfma_f32_16x16x32_bf16 v[76:79], v[206:209], v[190:193], v[76:79]
	v_mfma_f32_16x16x32_bf16 v[72:75], v[214:217], v[190:193], v[72:75]
	v_mfma_f32_16x16x32_bf16 v[68:71], v[206:209], v[198:201], v[68:71]
	v_mfma_f32_16x16x32_bf16 v[64:67], v[214:217], v[198:201], v[64:67]
	v_mfma_f32_16x16x32_bf16 v[92:95], v[210:213], v[178:181], v[92:95]
	v_mfma_f32_16x16x32_bf16 v[88:91], v[218:221], v[178:181], v[88:91]
	v_mfma_f32_16x16x32_bf16 v[84:87], v[210:213], v[186:189], v[84:87]
	v_mfma_f32_16x16x32_bf16 v[80:83], v[218:221], v[186:189], v[80:83]
	v_mfma_f32_16x16x32_bf16 v[76:79], v[210:213], v[194:197], v[76:79]
	v_mfma_f32_16x16x32_bf16 v[72:75], v[218:221], v[194:197], v[72:75]
	v_mfma_f32_16x16x32_bf16 v[68:71], v[210:213], v[202:205], v[68:71]
	v_mfma_f32_16x16x32_bf16 v[64:67], v[218:221], v[202:205], v[64:67]
	s_setprio 0
	s_mov_b32 m0, s15
	s_barrier
	ds_read_b128 v[174:177], v160 offset:16384
	ds_read_b128 v[178:181], v160 offset:17408
	ds_read_b128 v[182:185], v160 offset:18432
	ds_read_b128 v[186:189], v160 offset:19456
	ds_read_b128 v[190:193], v160 offset:20480
	ds_read_b128 v[194:197], v160 offset:21504
	ds_read_b128 v[198:201], v160 offset:22528
	ds_read_b128 v[202:205], v160 offset:23552
	v_lshl_add_u64 v[222:223], v[132:133], 0, s[40:41]
	global_load_lds_dwordx4 v[222:223], off
	v_lshl_add_u64 v[222:223], v[222:223], 0, s[4:5]
	s_mov_b32 m0, s35
	s_nop 0
	global_load_lds_dwordx4 v[222:223], off
	s_barrier
	s_waitcnt lgkmcnt(0)
	s_setprio 1
	v_mfma_f32_16x16x32_bf16 v[60:63], v[136:139], v[174:177], v[60:63]
	v_mfma_f32_16x16x32_bf16 v[56:59], v[166:169], v[174:177], v[56:59]
	v_mfma_f32_16x16x32_bf16 v[52:55], v[136:139], v[182:185], v[52:55]
	v_mfma_f32_16x16x32_bf16 v[48:51], v[166:169], v[182:185], v[48:51]
	v_mfma_f32_16x16x32_bf16 v[44:47], v[136:139], v[190:193], v[44:47]
	v_mfma_f32_16x16x32_bf16 v[40:43], v[166:169], v[190:193], v[40:43]
	v_mfma_f32_16x16x32_bf16 v[36:39], v[136:139], v[198:201], v[36:39]
	v_mfma_f32_16x16x32_bf16 v[32:35], v[166:169], v[198:201], v[32:35]
	v_mfma_f32_16x16x32_bf16 v[60:63], v[162:165], v[178:181], v[60:63]
	v_mfma_f32_16x16x32_bf16 v[56:59], v[170:173], v[178:181], v[56:59]
	v_mfma_f32_16x16x32_bf16 v[52:55], v[162:165], v[186:189], v[52:55]
	v_mfma_f32_16x16x32_bf16 v[48:51], v[170:173], v[186:189], v[48:51]
	v_mfma_f32_16x16x32_bf16 v[44:47], v[162:165], v[194:197], v[44:47]
	v_mfma_f32_16x16x32_bf16 v[40:43], v[170:173], v[194:197], v[40:43]
	v_mfma_f32_16x16x32_bf16 v[36:39], v[162:165], v[202:205], v[36:39]
	v_mfma_f32_16x16x32_bf16 v[32:35], v[170:173], v[202:205], v[32:35]
	s_setprio 0
	s_barrier
	s_add_u32 s40, s18, 0xffffff80
	s_addc_u32 s41, s19, -1
	s_mov_b64 s[42:43], s[40:41]
	s_mov_b32 m0, s29
	v_lshl_add_u64 v[136:137], v[134:135], 0, s[42:43]
	global_load_lds_dwordx4 v[136:137], off
	v_lshl_add_u64 v[136:137], v[136:137], 0, s[4:5]
	s_mov_b32 m0, s30
	s_nop 0
	global_load_lds_dwordx4 v[136:137], off
	s_waitcnt vmcnt(6)
	s_barrier
; #define STA(b, h, half, kt) STAGE(((b) * 2 + (h)) * G_HT * 2, pA, ((size_t)(half) * G_HALF * lda + (size_t)(kt) * G_BK) * 2, lda)
; #define STB(b, h, half, kt) STAGE((4 + (b) * 2 + (h)) * G_HT * 2, pB, ((size_t)(half) * G_HALF * K + (size_t)(kt) * G_BK) * 2, K)
; #define LDA(dst, b, h) for (int m = 0; m < 4; ++m) for (int k = 0; k < 2; ++k) \
;     dst[m][k] = *reinterpret_cast<const bf16x8*>(aRd + (((b) * 2 + (h)) * G_HT * 2 + m * 2048 + k * 1024))
; #define LDB(dst, b, h) for (int n = 0; n < 2; ++n) for (int k = 0; k < 2; ++k) \
;     dst[n][k] = *reinterpret_cast<const bf16x8*>(bRd + (((b) * 2 + (h)) * G_HT * 2 + n * 2048 + k * 1024))
; #define MMA(ai, bj, At, Bx) do { __builtin_amdgcn_s_setprio(1); \
;     for (int m = 0; m < 4; ++m) for (int n = 0; n < 2; ++n) for (int k = 0; k < 2; ++k) \
;       acc[ai][bj][m][n] = __builtin_amdgcn_mfma_f32_16x16x32_bf16(Bx[n][k], At[m][k], acc[ai][bj][m][n], 0, 0, 0);     \
;     __builtin_amdgcn_s_setprio(0); } while (0)
; #define WAIT_V(n) asm volatile("s_waitcnt vmcnt(" #n ")" ::: "memory")
; #define WAIT_L(n) asm volatile("s_waitcnt lgkmcnt(" #n ")" ::: "memory")
; #define BAR __builtin_amdgcn_s_barrier()
; #define SCHED __builtin_amdgcn_sched_barrier(0)
; template <int EPI>
; __device__ __forceinline__ void gemm_tile(const bf16* __restrict__ A, int lda, const bf16* __restrict__ Bt, int K,
;                                           int brow, int bcol, const EpiArgs& ea, char* shmc, bool has_next, int nbrow, int nbcol, bool first_tile) {
;     ...
;     WAIT_V(6); BAR; MMA(1, 1, At, B1); BAR;
;     LDB(B0, 1, 0); SCHED; LDA(At, 1, 0); STA(0, 1, 1, t + 2);
;     WAIT_L(8); BAR; WAIT_L(0); MMA(0, 0, At, B0); BAR; SCHED;
;     LDB(B1, 1, 1); STB(1, 0, 0, t + 3);
;     BAR; WAIT_L(0); MMA(0, 1, At, B1); BAR;
;     LDA(At, 1, 1); STA(1, 0, 0, t + 3);
;     BAR; WAIT_L(0); MMA(1, 0, At, B0); BAR; SCHED;
	s_setprio 1
	v_mfma_f32_16x16x32_bf16 v[28:31], v[206:209], v[174:177], v[28:31]
	v_mfma_f32_16x16x32_bf16 v[24:27], v[214:217], v[174:177], v[24:27]
	v_mfma_f32_16x16x32_bf16 v[20:23], v[206:209], v[182:185], v[20:23]
	v_mfma_f32_16x16x32_bf16 v[16:19], v[214:217], v[182:185], v[16:19]
	v_mfma_f32_16x16x32_bf16 v[12:15], v[206:209], v[190:193], v[12:15]
	v_mfma_f32_16x16x32_bf16 v[8:11], v[214:217], v[190:193], v[8:11]
	v_mfma_f32_16x16x32_bf16 v[4:7], v[206:209], v[198:201], v[4:7]
	v_mfma_f32_16x16x32_bf16 v[0:3], v[214:217], v[198:201], v[0:3]
	v_mfma_f32_16x16x32_bf16 v[28:31], v[210:213], v[178:181], v[28:31]
	v_mfma_f32_16x16x32_bf16 v[24:27], v[218:221], v[178:181], v[24:27]
	v_mfma_f32_16x16x32_bf16 v[20:23], v[210:213], v[186:189], v[20:23]
	v_mfma_f32_16x16x32_bf16 v[16:19], v[218:221], v[186:189], v[16:19]
	v_mfma_f32_16x16x32_bf16 v[12:15], v[210:213], v[194:197], v[12:15]
	v_mfma_f32_16x16x32_bf16 v[8:11], v[218:221], v[194:197], v[8:11]
	v_mfma_f32_16x16x32_bf16 v[4:7], v[210:213], v[202:205], v[4:7]
	v_mfma_f32_16x16x32_bf16 v[0:3], v[218:221], v[202:205], v[0:3]
	s_setprio 0
	s_barrier
	ds_read_b128 v[136:139], v149
	ds_read_b128 v[162:165], v150
	ds_read_b128 v[166:169], v151
	ds_read_b128 v[170:173], v152
	s_mov_b32 m0, s36
	ds_read_b128 v[174:177], v160 offset:32768
	ds_read_b128 v[178:181], v160 offset:33792
	ds_read_b128 v[182:185], v160 offset:34816
	ds_read_b128 v[186:189], v160 offset:35840
	ds_read_b128 v[190:193], v160 offset:36864
	ds_read_b128 v[194:197], v160 offset:37888
	ds_read_b128 v[198:201], v160 offset:38912
	ds_read_b128 v[202:205], v160 offset:39936
	v_lshl_add_u64 v[206:207], v[132:133], 0, s[40:41]
	global_load_lds_dwordx4 v[206:207], off
	v_lshl_add_u64 v[206:207], v[206:207], 0, s[4:5]
	s_mov_b32 m0, s37
	s_nop 0
	global_load_lds_dwordx4 v[206:207], off
	s_waitcnt lgkmcnt(8)
	s_barrier
	s_waitcnt lgkmcnt(0)
	s_setprio 1
	v_mfma_f32_16x16x32_bf16 v[124:127], v[136:139], v[174:177], v[124:127]
	v_mfma_f32_16x16x32_bf16 v[120:123], v[166:169], v[174:177], v[120:123]
	v_mfma_f32_16x16x32_bf16 v[116:119], v[136:139], v[182:185], v[116:119]
	v_mfma_f32_16x16x32_bf16 v[112:115], v[166:169], v[182:185], v[112:115]
	v_mfma_f32_16x16x32_bf16 v[108:111], v[136:139], v[190:193], v[108:111]
	v_mfma_f32_16x16x32_bf16 v[104:107], v[166:169], v[190:193], v[104:107]
	v_mfma_f32_16x16x32_bf16 v[100:103], v[136:139], v[198:201], v[100:103]
	v_mfma_f32_16x16x32_bf16 v[96:99], v[166:169], v[198:201], v[96:99]
	v_mfma_f32_16x16x32_bf16 v[124:127], v[162:165], v[178:181], v[124:127]
	v_mfma_f32_16x16x32_bf16 v[120:123], v[170:173], v[178:181], v[120:123]
	v_mfma_f32_16x16x32_bf16 v[116:119], v[162:165], v[186:189], v[116:119]
	v_mfma_f32_16x16x32_bf16 v[112:115], v[170:173], v[186:189], v[112:115]
	v_mfma_f32_16x16x32_bf16 v[108:111], v[162:165], v[194:197], v[108:111]
	v_mfma_f32_16x16x32_bf16 v[104:107], v[170:173], v[194:197], v[104:107]
	v_mfma_f32_16x16x32_bf16 v[100:103], v[162:165], v[202:205], v[100:103]
	v_mfma_f32_16x16x32_bf16 v[96:99], v[170:173], v[202:205], v[96:99]
	s_setprio 0
	s_barrier
	s_add_u32 s40, s18, 0xffc00000
	s_addc_u32 s41, s19, -1
	s_mov_b64 s[42:43], s[40:41]
	s_mov_b32 m0, s17
	ds_read_b128 v[206:209], v153
	ds_read_b128 v[210:213], v154
	ds_read_b128 v[214:217], v155
	ds_read_b128 v[218:221], v156
	v_lshl_add_u64 v[222:223], v[134:135], 0, s[42:43]
	global_load_lds_dwordx4 v[222:223], off
	v_lshl_add_u64 v[222:223], v[222:223], 0, s[4:5]
	s_mov_b32 m0, s21
	s_nop 0
	global_load_lds_dwordx4 v[222:223], off
	s_barrier
	s_waitcnt lgkmcnt(0)
	s_setprio 1
	v_mfma_f32_16x16x32_bf16 v[92:95], v[206:209], v[174:177], v[92:95]
	v_mfma_f32_16x16x32_bf16 v[88:91], v[214:217], v[174:177], v[88:91]
	v_mfma_f32_16x16x32_bf16 v[84:87], v[206:209], v[182:185], v[84:87]
	v_mfma_f32_16x16x32_bf16 v[80:83], v[214:217], v[182:185], v[80:83]
	v_mfma_f32_16x16x32_bf16 v[76:79], v[206:209], v[190:193], v[76:79]
	v_mfma_f32_16x16x32_bf16 v[72:75], v[214:217], v[190:193], v[72:75]
	v_mfma_f32_16x16x32_bf16 v[68:71], v[206:209], v[198:201], v[68:71]
	v_mfma_f32_16x16x32_bf16 v[64:67], v[214:217], v[198:201], v[64:67]
	v_mfma_f32_16x16x32_bf16 v[92:95], v[210:213], v[178:181], v[92:95]
	v_mfma_f32_16x16x32_bf16 v[88:91], v[218:221], v[178:181], v[88:91]
	v_mfma_f32_16x16x32_bf16 v[84:87], v[210:213], v[186:189], v[84:87]
	v_mfma_f32_16x16x32_bf16 v[80:83], v[218:221], v[186:189], v[80:83]
	v_mfma_f32_16x16x32_bf16 v[76:79], v[210:213], v[194:197], v[76:79]
	v_mfma_f32_16x16x32_bf16 v[72:75], v[218:221], v[194:197], v[72:75]
	v_mfma_f32_16x16x32_bf16 v[68:71], v[210:213], v[202:205], v[68:71]
	v_mfma_f32_16x16x32_bf16 v[64:67], v[218:221], v[202:205], v[64:67]
	s_setprio 0
	s_mov_b32 m0, s22
	s_barrier
	ds_read_b128 v[174:177], v160 offset:49152
	ds_read_b128 v[178:181], v160 offset:50176
	ds_read_b128 v[182:185], v160 offset:51200
	ds_read_b128 v[186:189], v160 offset:52224
	ds_read_b128 v[190:193], v160 offset:53248
	ds_read_b128 v[194:197], v160 offset:54272
	ds_read_b128 v[198:201], v160 offset:55296
	ds_read_b128 v[202:205], v160 offset:56320
	v_lshl_add_u64 v[222:223], v[132:133], 0, s[40:41]
	global_load_lds_dwordx4 v[222:223], off
	v_lshl_add_u64 v[222:223], v[222:223], 0, s[4:5]
	s_mov_b32 m0, s23
	s_nop 0
	global_load_lds_dwordx4 v[222:223], off
	s_barrier
; #define STA(b, h, half, kt) STAGE(((b) * 2 + (h)) * G_HT * 2, pA, ((size_t)(half) * G_HALF * lda + (size_t)(kt) * G_BK) * 2, lda)
; #define STB(b, h, half, kt) STAGE((4 + (b) * 2 + (h)) * G_HT * 2, pB, ((size_t)(half) * G_HALF * K + (size_t)(kt) * G_BK) * 2, K)
; #define LDA(dst, b, h) for (int m = 0; m < 4; ++m) for (int k = 0; k < 2; ++k) \
;     dst[m][k] = *reinterpret_cast<const bf16x8*>(aRd + (((b) * 2 + (h)) * G_HT * 2 + m * 2048 + k * 1024))
; #define LDB(dst, b, h) for (int n = 0; n < 2; ++n) for (int k = 0; k < 2; ++k) \
;     dst[n][k] = *reinterpret_cast<const bf16x8*>(bRd + (((b) * 2 + (h)) * G_HT * 2 + n * 2048 + k * 1024))
; #define MMA(ai, bj, At, Bx) do { __builtin_amdgcn_s_setprio(1); \
;     for (int m = 0; m < 4; ++m) for (int n = 0; n < 2; ++n) for (int k = 0; k < 2; ++k) \
;       acc[ai][bj][m][n] = __builtin_amdgcn_mfma_f32_16x16x32_bf16(Bx[n][k], At[m][k], acc[ai][bj][m][n], 0, 0, 0);     \
;     __builtin_amdgcn_s_setprio(0); } while (0)
; #define WAIT_V(n) asm volatile("s_waitcnt vmcnt(" #n ")" ::: "memory")
; #define WAIT_L(n) asm volatile("s_waitcnt lgkmcnt(" #n ")" ::: "memory")
; #define BAR __builtin_amdgcn_s_barrier()
; #define SCHED __builtin_amdgcn_sched_barrier(0)
; template <int EPI>
; __device__ __forceinline__ void gemm_tile(const bf16* __restrict__ A, int lda, const bf16* __restrict__ Bt, int K,
;                                           int brow, int bcol, const EpiArgs& ea, char* shmc, bool has_next, int nbrow, int nbcol, bool first_tile) {
;     ...
;     LDA(At, 1, 1); STA(1, 0, 0, t + 3);
;     BAR; WAIT_L(0); MMA(1, 0, At, B0); BAR; SCHED;
;     STB(1, 1, 1, t + 3);
;     WAIT_V(6); BAR; MMA(1, 1, At, B1); BAR;
;   }
;   { LDB(B0, 0, 0); LDA(At, 0, 0); STA(1, 1, 1, nt - 1);
;     BAR; WAIT_L(0); MMA(0, 0, At, B0); BAR;
;     LDB(B1, 0, 1); BAR; WAIT_L(0); MMA(0, 1, At, B1); BAR;
	s_waitcnt lgkmcnt(0)
	s_setprio 1
	v_mfma_f32_16x16x32_bf16 v[60:63], v[136:139], v[174:177], v[60:63]
	v_mfma_f32_16x16x32_bf16 v[56:59], v[166:169], v[174:177], v[56:59]
	v_mfma_f32_16x16x32_bf16 v[52:55], v[136:139], v[182:185], v[52:55]
	v_mfma_f32_16x16x32_bf16 v[48:51], v[166:169], v[182:185], v[48:51]
	v_mfma_f32_16x16x32_bf16 v[44:47], v[136:139], v[190:193], v[44:47]
	v_mfma_f32_16x16x32_bf16 v[40:43], v[166:169], v[190:193], v[40:43]
	v_mfma_f32_16x16x32_bf16 v[36:39], v[136:139], v[198:201], v[36:39]
	v_mfma_f32_16x16x32_bf16 v[32:35], v[166:169], v[198:201], v[32:35]
	v_mfma_f32_16x16x32_bf16 v[60:63], v[162:165], v[178:181], v[60:63]
	v_mfma_f32_16x16x32_bf16 v[56:59], v[170:173], v[178:181], v[56:59]
	v_mfma_f32_16x16x32_bf16 v[52:55], v[162:165], v[186:189], v[52:55]
	v_mfma_f32_16x16x32_bf16 v[48:51], v[170:173], v[186:189], v[48:51]
	v_mfma_f32_16x16x32_bf16 v[44:47], v[162:165], v[194:197], v[44:47]
	v_mfma_f32_16x16x32_bf16 v[40:43], v[170:173], v[194:197], v[40:43]
	v_mfma_f32_16x16x32_bf16 v[36:39], v[162:165], v[202:205], v[36:39]
	v_mfma_f32_16x16x32_bf16 v[32:35], v[170:173], v[202:205], v[32:35]
	s_setprio 0
	s_barrier
	s_mov_b64 s[40:41], s[18:19]
	s_mov_b32 m0, s25
	v_lshl_add_u64 v[136:137], v[134:135], 0, s[40:41]
	global_load_lds_dwordx4 v[136:137], off
	v_lshl_add_u64 v[136:137], v[136:137], 0, s[4:5]
	s_mov_b32 m0, s26
	s_nop 0
	global_load_lds_dwordx4 v[136:137], off
	s_waitcnt vmcnt(6)
	s_barrier
	s_setprio 1
	v_mfma_f32_16x16x32_bf16 v[28:31], v[206:209], v[174:177], v[28:31]
	v_mfma_f32_16x16x32_bf16 v[24:27], v[214:217], v[174:177], v[24:27]
	v_mfma_f32_16x16x32_bf16 v[20:23], v[206:209], v[182:185], v[20:23]
	v_mfma_f32_16x16x32_bf16 v[16:19], v[214:217], v[182:185], v[16:19]
	v_mfma_f32_16x16x32_bf16 v[12:15], v[206:209], v[190:193], v[12:15]
	v_mfma_f32_16x16x32_bf16 v[8:11], v[214:217], v[190:193], v[8:11]
	v_mfma_f32_16x16x32_bf16 v[4:7], v[206:209], v[198:201], v[4:7]
	v_mfma_f32_16x16x32_bf16 v[0:3], v[214:217], v[198:201], v[0:3]
	v_mfma_f32_16x16x32_bf16 v[28:31], v[210:213], v[178:181], v[28:31]
	v_mfma_f32_16x16x32_bf16 v[24:27], v[218:221], v[178:181], v[24:27]
	v_mfma_f32_16x16x32_bf16 v[20:23], v[210:213], v[186:189], v[20:23]
	v_mfma_f32_16x16x32_bf16 v[16:19], v[218:221], v[186:189], v[16:19]
	v_mfma_f32_16x16x32_bf16 v[12:15], v[210:213], v[194:197], v[12:15]
	v_mfma_f32_16x16x32_bf16 v[8:11], v[218:221], v[194:197], v[8:11]
	v_mfma_f32_16x16x32_bf16 v[4:7], v[210:213], v[202:205], v[4:7]
	v_mfma_f32_16x16x32_bf16 v[0:3], v[218:221], v[202:205], v[0:3]
	s_setprio 0
	s_add_i32 s31, s31, 2
	s_add_u32 s18, s18, 0x100
	s_addc_u32 s19, s19, 0
	s_cmpk_lt_u32 s31, 0xfc
	s_barrier
	s_cbranch_scc1 .LBB0_784
	s_mov_b64 s[18:19], 0x407f80
	s_mov_b32 m0, s34
	ds_read_b128 v[134:137], v141
	ds_read_b128 v[162:165], v142
	ds_read_b128 v[166:169], v143
	ds_read_b128 v[170:173], v144
	ds_read_b128 v[174:177], v160
	ds_read_b128 v[178:181], v160 offset:1024
	ds_read_b128 v[182:185], v160 offset:2048
	ds_read_b128 v[186:189], v160 offset:3072
	ds_read_b128 v[190:193], v160 offset:4096
	ds_read_b128 v[194:197], v160 offset:5120
	ds_read_b128 v[198:201], v160 offset:6144
	ds_read_b128 v[202:205], v160 offset:7168
	s_nop 0
	v_lshl_add_u64 v[132:133], v[132:133], 0, s[18:19]
	global_load_lds_dwordx4 v[132:133], off
	v_lshl_add_u64 v[132:133], v[132:133], 0, s[4:5]
	s_mov_b32 m0, s24
	s_nop 0
	global_load_lds_dwordx4 v[132:133], off
	s_barrier
	s_waitcnt lgkmcnt(0)
	s_setprio 1
	s_waitcnt lgkmcnt(0)
	v_mfma_f32_16x16x32_bf16 v[124:127], v[134:137], v[174:177], v[124:127]
	v_mfma_f32_16x16x32_bf16 v[120:123], v[166:169], v[174:177], v[120:123]
	v_mfma_f32_16x16x32_bf16 v[116:119], v[134:137], v[182:185], v[116:119]
	v_mfma_f32_16x16x32_bf16 v[112:115], v[166:169], v[182:185], v[112:115]
	v_mfma_f32_16x16x32_bf16 v[100:103], v[134:137], v[198:201], v[100:103]
	v_mfma_f32_16x16x32_bf16 v[96:99], v[166:169], v[198:201], v[96:99]
	v_mfma_f32_16x16x32_bf16 v[124:127], v[162:165], v[178:181], v[124:127]
	v_mfma_f32_16x16x32_bf16 v[120:123], v[170:173], v[178:181], v[120:123]
	v_mfma_f32_16x16x32_bf16 v[116:119], v[162:165], v[186:189], v[116:119]
	v_mfma_f32_16x16x32_bf16 v[112:115], v[170:173], v[186:189], v[112:115]
	v_mfma_f32_16x16x32_bf16 v[108:111], v[134:137], v[190:193], v[108:111]
	v_mfma_f32_16x16x32_bf16 v[104:107], v[166:169], v[190:193], v[104:107]
	v_mfma_f32_16x16x32_bf16 v[100:103], v[162:165], v[202:205], v[100:103]
	v_mfma_f32_16x16x32_bf16 v[96:99], v[170:173], v[202:205], v[96:99]
	v_mfma_f32_16x16x32_bf16 v[206:209], v[162:165], v[194:197], v[108:111]
	v_mfma_f32_16x16x32_bf16 v[210:213], v[170:173], v[194:197], v[104:107]
	s_setprio 0
	s_barrier
	s_nop 1
	ds_read_b128 v[104:107], v145
	ds_read_b128 v[108:111], v146
	ds_read_b128 v[214:217], v147
	ds_read_b128 v[218:221], v148
	s_barrier
	s_waitcnt lgkmcnt(0)
	s_setprio 1
	s_waitcnt lgkmcnt(0)
	v_mfma_f32_16x16x32_bf16 v[84:87], v[104:107], v[182:185], v[84:87]
	v_mfma_f32_16x16x32_bf16 v[80:83], v[214:217], v[182:185], v[80:83]
	v_mfma_f32_16x16x32_bf16 v[68:71], v[104:107], v[198:201], v[68:71]
	v_mfma_f32_16x16x32_bf16 v[64:67], v[214:217], v[198:201], v[64:67]
	v_mfma_f32_16x16x32_bf16 v[92:95], v[104:107], v[174:177], v[92:95]
	v_mfma_f32_16x16x32_bf16 v[88:91], v[214:217], v[174:177], v[88:91]
	v_mfma_f32_16x16x32_bf16 v[84:87], v[108:111], v[186:189], v[84:87]
	v_mfma_f32_16x16x32_bf16 v[80:83], v[218:221], v[186:189], v[80:83]
	v_mfma_f32_16x16x32_bf16 v[76:79], v[104:107], v[190:193], v[76:79]
	v_mfma_f32_16x16x32_bf16 v[72:75], v[214:217], v[190:193], v[72:75]
	v_mfma_f32_16x16x32_bf16 v[68:71], v[108:111], v[202:205], v[68:71]
	v_mfma_f32_16x16x32_bf16 v[64:67], v[218:221], v[202:205], v[64:67]
	v_mfma_f32_16x16x32_bf16 v[222:225], v[108:111], v[178:181], v[92:95]
	v_mfma_f32_16x16x32_bf16 v[174:177], v[218:221], v[178:181], v[88:91]
	v_mfma_f32_16x16x32_bf16 v[178:181], v[108:111], v[194:197], v[76:79]
	v_mfma_f32_16x16x32_bf16 v[182:185], v[218:221], v[194:197], v[72:75]
	s_setprio 0
	s_barrier
; #define LDA(dst, b, h) for (int m = 0; m < 4; ++m) for (int k = 0; k < 2; ++k) \
;     dst[m][k] = *reinterpret_cast<const bf16x8*>(aRd + (((b) * 2 + (h)) * G_HT * 2 + m * 2048 + k * 1024))
; #define LDB(dst, b, h) for (int n = 0; n < 2; ++n) for (int k = 0; k < 2; ++k) \
;     dst[n][k] = *reinterpret_cast<const bf16x8*>(bRd + (((b) * 2 + (h)) * G_HT * 2 + n * 2048 + k * 1024))
; #define MMA(ai, bj, At, Bx) do { __builtin_amdgcn_s_setprio(1); \
;     for (int m = 0; m < 4; ++m) for (int n = 0; n < 2; ++n) for (int k = 0; k < 2; ++k) \
;       acc[ai][bj][m][n] = __builtin_amdgcn_mfma_f32_16x16x32_bf16(Bx[n][k], At[m][k], acc[ai][bj][m][n], 0, 0, 0);     \
;     __builtin_amdgcn_s_setprio(0); } while (0)
; #define WAIT_V(n) asm volatile("s_waitcnt vmcnt(" #n ")" ::: "memory")
; #define WAIT_L(n) asm volatile("s_waitcnt lgkmcnt(" #n ")" ::: "memory")
; #define BAR __builtin_amdgcn_s_barrier()
; template <int EPI>
; __device__ __forceinline__ void gemm_tile(const bf16* __restrict__ A, int lda, const bf16* __restrict__ Bt, int K,
;                                           int brow, int bcol, const EpiArgs& ea, char* shmc, bool has_next, int nbrow, int nbcol, bool first_tile) {
;     ...
;     LDA(At, 0, 1); WAIT_V(4); BAR; WAIT_L(0); MMA(1, 0, At, B0); MMA(1, 1, At, B1); BAR; }
;   { LDB(B0, 1, 0); LDA(At, 1, 0); WAIT_V(2); BAR; WAIT_L(0); MMA(0, 0, At, B0); BAR;
	s_nop 0
	ds_read_b128 v[72:75], v160 offset:16384
	ds_read_b128 v[76:79], v160 offset:17408
	ds_read_b128 v[88:91], v160 offset:18432
	ds_read_b128 v[92:95], v160 offset:19456
	ds_read_b128 v[186:189], v160 offset:20480
	ds_read_b128 v[190:193], v160 offset:21504
	ds_read_b128 v[194:197], v160 offset:22528
	ds_read_b128 v[198:201], v160 offset:23552
	s_waitcnt vmcnt(4)
	s_barrier
	s_waitcnt lgkmcnt(0)
	s_setprio 1
	s_waitcnt lgkmcnt(0)
	v_mfma_f32_16x16x32_bf16 v[60:63], v[134:137], v[72:75], v[60:63]
	v_mfma_f32_16x16x32_bf16 v[56:59], v[166:169], v[72:75], v[56:59]
	v_mfma_f32_16x16x32_bf16 v[52:55], v[134:137], v[88:91], v[52:55]
	v_mfma_f32_16x16x32_bf16 v[48:51], v[166:169], v[88:91], v[48:51]
	v_mfma_f32_16x16x32_bf16 v[36:39], v[134:137], v[194:197], v[36:39]
	v_mfma_f32_16x16x32_bf16 v[32:35], v[166:169], v[194:197], v[32:35]
	v_mfma_f32_16x16x32_bf16 v[60:63], v[162:165], v[76:79], v[60:63]
	v_mfma_f32_16x16x32_bf16 v[56:59], v[170:173], v[76:79], v[56:59]
	v_mfma_f32_16x16x32_bf16 v[52:55], v[162:165], v[92:95], v[52:55]
	v_mfma_f32_16x16x32_bf16 v[48:51], v[170:173], v[92:95], v[48:51]
	v_mfma_f32_16x16x32_bf16 v[44:47], v[134:137], v[186:189], v[44:47]
	v_mfma_f32_16x16x32_bf16 v[40:43], v[166:169], v[186:189], v[40:43]
	v_mfma_f32_16x16x32_bf16 v[36:39], v[162:165], v[198:201], v[36:39]
	v_mfma_f32_16x16x32_bf16 v[32:35], v[170:173], v[198:201], v[32:35]
	v_mfma_f32_16x16x32_bf16 v[202:205], v[162:165], v[190:193], v[44:47]
	v_mfma_f32_16x16x32_bf16 v[226:229], v[170:173], v[190:193], v[40:43]
	s_setprio 0
	s_setprio 1
	v_mfma_f32_16x16x32_bf16 v[20:23], v[104:107], v[88:91], v[20:23]
	v_mfma_f32_16x16x32_bf16 v[16:19], v[214:217], v[88:91], v[16:19]
	v_mfma_f32_16x16x32_bf16 v[4:7], v[104:107], v[194:197], v[4:7]
	v_mfma_f32_16x16x32_bf16 v[0:3], v[214:217], v[194:197], v[0:3]
	v_mfma_f32_16x16x32_bf16 v[28:31], v[104:107], v[72:75], v[28:31]
	v_mfma_f32_16x16x32_bf16 v[24:27], v[214:217], v[72:75], v[24:27]
	v_mfma_f32_16x16x32_bf16 v[20:23], v[108:111], v[92:95], v[20:23]
	v_mfma_f32_16x16x32_bf16 v[16:19], v[218:221], v[92:95], v[16:19]
	v_mfma_f32_16x16x32_bf16 v[12:15], v[104:107], v[186:189], v[12:15]
	v_mfma_f32_16x16x32_bf16 v[8:11], v[214:217], v[186:189], v[8:11]
	v_mfma_f32_16x16x32_bf16 v[4:7], v[108:111], v[198:201], v[4:7]
	v_mfma_f32_16x16x32_bf16 v[0:3], v[218:221], v[198:201], v[0:3]
	v_mfma_f32_16x16x32_bf16 v[132:135], v[108:111], v[76:79], v[28:31]
	v_mfma_f32_16x16x32_bf16 v[136:139], v[218:221], v[76:79], v[24:27]
	v_mfma_f32_16x16x32_bf16 v[162:165], v[108:111], v[190:193], v[12:15]
	v_mfma_f32_16x16x32_bf16 v[166:169], v[218:221], v[190:193], v[8:11]
	s_setprio 0
	s_barrier
	s_nop 0
	ds_read_b128 v[8:11], v149
	ds_read_b128 v[12:15], v150
	ds_read_b128 v[170:173], v151
	ds_read_b128 v[186:189], v152
	ds_read_b128 v[24:27], v160 offset:32768
	ds_read_b128 v[28:31], v160 offset:33792
	ds_read_b128 v[40:43], v160 offset:34816
	ds_read_b128 v[44:47], v160 offset:35840
	ds_read_b128 v[190:193], v160 offset:36864
	ds_read_b128 v[194:197], v160 offset:37888
	ds_read_b128 v[198:201], v160 offset:38912
	ds_read_b128 v[214:217], v160 offset:39936
	s_waitcnt vmcnt(2)
	s_barrier
	s_waitcnt lgkmcnt(0)
	s_setprio 1
	s_waitcnt lgkmcnt(0)
	v_mfma_f32_16x16x32_bf16 v[72:75], v[8:11], v[24:27], v[124:127]
	v_mfma_f32_16x16x32_bf16 v[124:127], v[12:15], v[28:31], v[72:75]
	v_mfma_f32_16x16x32_bf16 v[72:75], v[170:173], v[24:27], v[120:123]
	v_mfma_f32_16x16x32_bf16 v[120:123], v[186:189], v[28:31], v[72:75]
	v_mfma_f32_16x16x32_bf16 v[72:75], v[8:11], v[40:43], v[116:119]
	v_mfma_f32_16x16x32_bf16 v[108:111], v[12:15], v[44:47], v[72:75]
	v_mfma_f32_16x16x32_bf16 v[72:75], v[170:173], v[40:43], v[112:115]
	v_mfma_f32_16x16x32_bf16 v[104:107], v[186:189], v[44:47], v[72:75]
	v_mfma_f32_16x16x32_bf16 v[72:75], v[8:11], v[190:193], v[206:209]
	v_mfma_f32_16x16x32_bf16 v[92:95], v[12:15], v[194:197], v[72:75]
	v_mfma_f32_16x16x32_bf16 v[72:75], v[170:173], v[190:193], v[210:213]
	v_mfma_f32_16x16x32_bf16 v[88:91], v[186:189], v[194:197], v[72:75]
	v_mfma_f32_16x16x32_bf16 v[72:75], v[8:11], v[198:201], v[100:103]
	v_mfma_f32_16x16x32_bf16 v[76:79], v[12:15], v[214:217], v[72:75]
	v_mfma_f32_16x16x32_bf16 v[72:75], v[170:173], v[198:201], v[96:99]
	v_mfma_f32_16x16x32_bf16 v[72:75], v[186:189], v[214:217], v[72:75]
	s_setprio 0
	s_barrier
; #define LDA(dst, b, h) for (int m = 0; m < 4; ++m) for (int k = 0; k < 2; ++k) \
;     dst[m][k] = *reinterpret_cast<const bf16x8*>(aRd + (((b) * 2 + (h)) * G_HT * 2 + m * 2048 + k * 1024))
; #define LDB(dst, b, h) for (int n = 0; n < 2; ++n) for (int k = 0; k < 2; ++k) \
;     dst[n][k] = *reinterpret_cast<const bf16x8*>(bRd + (((b) * 2 + (h)) * G_HT * 2 + n * 2048 + k * 1024))
; #define MMA(ai, bj, At, Bx) do { __builtin_amdgcn_s_setprio(1); \
;     for (int m = 0; m < 4; ++m) for (int n = 0; n < 2; ++n) for (int k = 0; k < 2; ++k) \
;       acc[ai][bj][m][n] = __builtin_amdgcn_mfma_f32_16x16x32_bf16(Bx[n][k], At[m][k], acc[ai][bj][m][n], 0, 0, 0);     \
;     __builtin_amdgcn_s_setprio(0); } while (0)
; #define WAIT_V(n) asm volatile("s_waitcnt vmcnt(" #n ")" ::: "memory")
; #define WAIT_L(n) asm volatile("s_waitcnt lgkmcnt(" #n ")" ::: "memory")
; #define BAR __builtin_amdgcn_s_barrier()
; template <int EPI>
; __device__ __forceinline__ void gemm_tile(const bf16* __restrict__ A, int lda, const bf16* __restrict__ Bt, int K,
;                                           int brow, int bcol, const EpiArgs& ea, char* shmc, bool has_next, int nbrow, int nbcol, bool first_tile) {
;     ...
;     LDB(B1, 1, 1); WAIT_V(0); BAR; WAIT_L(0); MMA(0, 1, At, B1); BAR;
;     LDA(At, 1, 1); BAR; WAIT_L(0); MMA(1, 0, At, B0); MMA(1, 1, At, B1); BAR; }
;   if (wr == 0) BAR;
	ds_read_b128 v[206:209], v153
	ds_read_b128 v[210:213], v154
	ds_read_b128 v[218:221], v155
	ds_read_b128 v[230:233], v156
	s_waitcnt vmcnt(0)
	s_barrier
	s_waitcnt lgkmcnt(0)
	s_setprio 1
	s_waitcnt lgkmcnt(0)
	v_mfma_f32_16x16x32_bf16 v[96:99], v[206:209], v[24:27], v[222:225]
	v_mfma_f32_16x16x32_bf16 v[24:27], v[218:221], v[24:27], v[174:177]
	v_mfma_f32_16x16x32_bf16 v[112:115], v[230:233], v[28:31], v[24:27]
	v_mfma_f32_16x16x32_bf16 v[24:27], v[206:209], v[40:43], v[84:87]
	v_mfma_f32_16x16x32_bf16 v[100:103], v[210:213], v[44:47], v[24:27]
	v_mfma_f32_16x16x32_bf16 v[24:27], v[218:221], v[40:43], v[80:83]
	v_mfma_f32_16x16x32_bf16 v[116:119], v[210:213], v[28:31], v[96:99]
	v_mfma_f32_16x16x32_bf16 v[96:99], v[230:233], v[44:47], v[24:27]
	v_mfma_f32_16x16x32_bf16 v[24:27], v[206:209], v[190:193], v[178:181]
	v_mfma_f32_16x16x32_bf16 v[84:87], v[210:213], v[194:197], v[24:27]
	v_mfma_f32_16x16x32_bf16 v[24:27], v[218:221], v[190:193], v[182:185]
	v_mfma_f32_16x16x32_bf16 v[80:83], v[230:233], v[194:197], v[24:27]
	v_mfma_f32_16x16x32_bf16 v[24:27], v[206:209], v[198:201], v[68:71]
	v_mfma_f32_16x16x32_bf16 v[68:71], v[210:213], v[214:217], v[24:27]
	v_mfma_f32_16x16x32_bf16 v[24:27], v[218:221], v[198:201], v[64:67]
	v_mfma_f32_16x16x32_bf16 v[64:67], v[230:233], v[214:217], v[24:27]
	s_setprio 0
	s_barrier
	ds_read_b128 v[174:177], v160 offset:49152
	ds_read_b128 v[178:181], v160 offset:50176
	ds_read_b128 v[182:185], v160 offset:51200
	ds_read_b128 v[190:193], v160 offset:52224
	ds_read_b128 v[194:197], v160 offset:53248
	ds_read_b128 v[198:201], v160 offset:54272
	ds_read_b128 v[214:217], v160 offset:55296
	ds_read_b128 v[222:225], v160 offset:56320
	s_barrier
	s_waitcnt lgkmcnt(0)
	s_setprio 1
	s_waitcnt lgkmcnt(0)
	v_mfma_f32_16x16x32_bf16 v[24:27], v[8:11], v[174:177], v[60:63]
	v_mfma_f32_16x16x32_bf16 v[60:63], v[12:15], v[178:181], v[24:27]
	v_mfma_f32_16x16x32_bf16 v[24:27], v[170:173], v[174:177], v[56:59]
	v_mfma_f32_16x16x32_bf16 v[56:59], v[186:189], v[178:181], v[24:27]
	v_mfma_f32_16x16x32_bf16 v[24:27], v[8:11], v[182:185], v[52:55]
	v_mfma_f32_16x16x32_bf16 v[44:47], v[12:15], v[190:193], v[24:27]
	v_mfma_f32_16x16x32_bf16 v[24:27], v[170:173], v[182:185], v[48:51]
	v_mfma_f32_16x16x32_bf16 v[40:43], v[186:189], v[190:193], v[24:27]
	v_mfma_f32_16x16x32_bf16 v[24:27], v[8:11], v[194:197], v[202:205]
	v_mfma_f32_16x16x32_bf16 v[8:11], v[8:11], v[214:217], v[36:39]
	v_mfma_f32_16x16x32_bf16 v[28:31], v[12:15], v[198:201], v[24:27]
	v_mfma_f32_16x16x32_bf16 v[24:27], v[170:173], v[194:197], v[226:229]
	v_mfma_f32_16x16x32_bf16 v[12:15], v[12:15], v[222:225], v[8:11]
	v_mfma_f32_16x16x32_bf16 v[8:11], v[170:173], v[214:217], v[32:35]
	v_mfma_f32_16x16x32_bf16 v[24:27], v[186:189], v[198:201], v[24:27]
	v_mfma_f32_16x16x32_bf16 v[8:11], v[186:189], v[222:225], v[8:11]
	s_setprio 0
	s_setprio 1
	v_mfma_f32_16x16x32_bf16 v[32:35], v[206:209], v[174:177], v[132:135]
	v_mfma_f32_16x16x32_bf16 v[52:55], v[210:213], v[178:181], v[32:35]
	v_mfma_f32_16x16x32_bf16 v[32:35], v[218:221], v[174:177], v[136:139]
	v_mfma_f32_16x16x32_bf16 v[16:19], v[218:221], v[182:185], v[16:19]
	v_mfma_f32_16x16x32_bf16 v[48:51], v[230:233], v[178:181], v[32:35]
	v_mfma_f32_16x16x32_bf16 v[20:23], v[206:209], v[182:185], v[20:23]
	v_mfma_f32_16x16x32_bf16 v[32:35], v[230:233], v[190:193], v[16:19]
	v_mfma_f32_16x16x32_bf16 v[16:19], v[206:209], v[194:197], v[162:165]
	v_mfma_f32_16x16x32_bf16 v[36:39], v[210:213], v[190:193], v[20:23]
	v_mfma_f32_16x16x32_bf16 v[20:23], v[210:213], v[198:201], v[16:19]
	v_mfma_f32_16x16x32_bf16 v[16:19], v[218:221], v[194:197], v[166:169]
	v_mfma_f32_16x16x32_bf16 v[4:7], v[206:209], v[214:217], v[4:7]
	v_mfma_f32_16x16x32_bf16 v[0:3], v[218:221], v[214:217], v[0:3]
	v_mfma_f32_16x16x32_bf16 v[16:19], v[230:233], v[198:201], v[16:19]
	v_mfma_f32_16x16x32_bf16 v[4:7], v[210:213], v[222:225], v[4:7]
	v_mfma_f32_16x16x32_bf16 v[0:3], v[230:233], v[222:225], v[0:3]
	s_setprio 0
	s_barrier
	s_and_saveexec_b64 s[18:19], s[2:3]
	s_cbranch_execz .LBB0_787
	s_barrier
